# speedup vs baseline: 1.0071x; 1.0018x over previous
.Lh2_loop:
	ds_read_b128 v[140:143], v138
	ds_read_b128 v[144:147], v138 offset:1024
	ds_read_b128 v[148:151], v138 offset:2048
	ds_read_b128 v[152:155], v138 offset:3072
	s_add_u32 s8, s6, s65
	s_addc_u32 s9, s7, s66
	ds_read_b128 v[156:159], v134
	ds_read_b128 v[160:163], v134 offset:1024
	ds_read_b128 v[164:167], v133
	ds_read_b128 v[168:171], v133 offset:1024
	ds_read_b128 v[172:175], v132
	ds_read_b128 v[176:179], v132 offset:1024
	ds_read_b128 v[180:183], v131
	ds_read_b128 v[184:187], v131 offset:1024
	s_mov_b32 m0, s76
	s_mov_b32 m0, s75
	s_nop 0
	s_waitcnt lgkmcnt(8)
	s_barrier
	s_waitcnt lgkmcnt(7)
	v_mfma_f32_16x16x32_bf16 v[124:127], v[140:143], v[156:159], v[124:127]
	v_mfma_f32_16x16x32_bf16 v[120:123], v[148:151], v[156:159], v[120:123]
	s_waitcnt lgkmcnt(5)
	v_mfma_f32_16x16x32_bf16 v[116:119], v[140:143], v[164:167], v[116:119]
	v_mfma_f32_16x16x32_bf16 v[112:115], v[148:151], v[164:167], v[112:115]
	s_waitcnt lgkmcnt(3)
	v_mfma_f32_16x16x32_bf16 v[108:111], v[140:143], v[172:175], v[108:111]
	v_mfma_f32_16x16x32_bf16 v[104:107], v[148:151], v[172:175], v[104:107]
	s_waitcnt lgkmcnt(1)
	v_mfma_f32_16x16x32_bf16 v[100:103], v[140:143], v[180:183], v[100:103]
	v_mfma_f32_16x16x32_bf16 v[96:99], v[148:151], v[180:183], v[96:99]
	v_mfma_f32_16x16x32_bf16 v[124:127], v[144:147], v[160:163], v[124:127]
	v_mfma_f32_16x16x32_bf16 v[120:123], v[152:155], v[160:163], v[120:123]
	v_mfma_f32_16x16x32_bf16 v[116:119], v[144:147], v[168:171], v[116:119]
	v_mfma_f32_16x16x32_bf16 v[112:115], v[152:155], v[168:171], v[112:115]
	v_mfma_f32_16x16x32_bf16 v[108:111], v[144:147], v[176:179], v[108:111]
	v_mfma_f32_16x16x32_bf16 v[104:107], v[152:155], v[176:179], v[104:107]
	s_waitcnt lgkmcnt(0)
	v_mfma_f32_16x16x32_bf16 v[100:103], v[144:147], v[184:187], v[100:103]
	v_mfma_f32_16x16x32_bf16 v[96:99], v[152:155], v[184:187], v[96:99]
	s_barrier
	s_add_u32 s10, s6, s36
	s_addc_u32 s11, s7, s37
	ds_read_b128 v[188:191], v137
	ds_read_b128 v[192:195], v137 offset:1024
	ds_read_b128 v[202:205], v137 offset:2048
	ds_read_b128 v[206:209], v137 offset:3072
	s_mov_b32 m0, s63
	s_add_u32 s98, s10, s46
	s_addc_u32 s99, s11, s47
	global_load_lds_dwordx4 v129, s[98:99]
	s_mov_b32 m0, s64
	s_nop 0
	global_load_lds_dwordx4 v130, s[98:99]
	s_barrier
	s_waitcnt lgkmcnt(3)
	v_mfma_f32_16x16x32_bf16 v[92:95], v[188:191], v[156:159], v[92:95]
	s_waitcnt lgkmcnt(1)
	v_mfma_f32_16x16x32_bf16 v[88:91], v[202:205], v[156:159], v[88:91]
	v_mfma_f32_16x16x32_bf16 v[84:87], v[188:191], v[164:167], v[84:87]
	v_mfma_f32_16x16x32_bf16 v[80:83], v[202:205], v[164:167], v[80:83]
	v_mfma_f32_16x16x32_bf16 v[76:79], v[188:191], v[172:175], v[76:79]
	v_mfma_f32_16x16x32_bf16 v[72:75], v[202:205], v[172:175], v[72:75]
	v_mfma_f32_16x16x32_bf16 v[68:71], v[188:191], v[180:183], v[68:71]
	v_mfma_f32_16x16x32_bf16 v[64:67], v[202:205], v[180:183], v[64:67]
	v_mfma_f32_16x16x32_bf16 v[92:95], v[192:195], v[160:163], v[92:95]
	s_waitcnt lgkmcnt(0)
	v_mfma_f32_16x16x32_bf16 v[88:91], v[206:209], v[160:163], v[88:91]
	v_mfma_f32_16x16x32_bf16 v[84:87], v[192:195], v[168:171], v[84:87]
	v_mfma_f32_16x16x32_bf16 v[80:83], v[206:209], v[168:171], v[80:83]
	v_mfma_f32_16x16x32_bf16 v[76:79], v[192:195], v[176:179], v[76:79]
	v_mfma_f32_16x16x32_bf16 v[72:75], v[206:209], v[176:179], v[72:75]
	v_mfma_f32_16x16x32_bf16 v[68:71], v[192:195], v[184:187], v[68:71]
	v_mfma_f32_16x16x32_bf16 v[64:67], v[206:209], v[184:187], v[64:67]
	s_barrier
	s_mov_b32 m0, s62
	s_add_u32 s98, s8, s48
	s_addc_u32 s99, s9, s49
	global_load_lds_dwordx4 v129, s[98:99]
	s_mov_b32 m0, s67
	s_nop 0
	global_load_lds_dwordx4 v130, s[98:99]
	s_waitcnt vmcnt(4)
	s_barrier
	s_mov_b32 m0, s68
	s_add_u32 s98, s10, s50
	s_addc_u32 s99, s11, s51
	global_load_lds_dwordx4 v129, s[98:99]
	s_mov_b32 m0, s69
	s_nop 0
	global_load_lds_dwordx4 v130, s[98:99]
	s_barrier
	ds_read_b128 v[140:143], v136
	ds_read_b128 v[144:147], v136 offset:1024
	ds_read_b128 v[148:151], v136 offset:2048
	ds_read_b128 v[152:155], v136 offset:3072
	ds_read_b128 v[156:159], v134 offset:32768
	ds_read_b128 v[160:163], v134 offset:33792
	ds_read_b128 v[164:167], v133 offset:32768
	ds_read_b128 v[168:171], v133 offset:33792
	ds_read_b128 v[172:175], v132 offset:32768
	ds_read_b128 v[176:179], v132 offset:33792
	ds_read_b128 v[180:183], v131 offset:32768
	ds_read_b128 v[184:187], v131 offset:33792
	s_mov_b32 m0, s70
	s_mov_b32 m0, s71
	s_nop 0
	s_waitcnt lgkmcnt(8)
	s_barrier
	s_waitcnt lgkmcnt(7)
	v_mfma_f32_16x16x32_bf16 v[124:127], v[140:143], v[156:159], v[124:127]
	v_mfma_f32_16x16x32_bf16 v[120:123], v[148:151], v[156:159], v[120:123]
	s_waitcnt lgkmcnt(5)
	v_mfma_f32_16x16x32_bf16 v[116:119], v[140:143], v[164:167], v[116:119]
	v_mfma_f32_16x16x32_bf16 v[112:115], v[148:151], v[164:167], v[112:115]
	s_waitcnt lgkmcnt(3)
	v_mfma_f32_16x16x32_bf16 v[108:111], v[140:143], v[172:175], v[108:111]
	v_mfma_f32_16x16x32_bf16 v[104:107], v[148:151], v[172:175], v[104:107]
	s_waitcnt lgkmcnt(1)
	v_mfma_f32_16x16x32_bf16 v[100:103], v[140:143], v[180:183], v[100:103]
	v_mfma_f32_16x16x32_bf16 v[96:99], v[148:151], v[180:183], v[96:99]
	v_mfma_f32_16x16x32_bf16 v[124:127], v[144:147], v[160:163], v[124:127]
	v_mfma_f32_16x16x32_bf16 v[120:123], v[152:155], v[160:163], v[120:123]
	v_mfma_f32_16x16x32_bf16 v[116:119], v[144:147], v[168:171], v[116:119]
	v_mfma_f32_16x16x32_bf16 v[112:115], v[152:155], v[168:171], v[112:115]
	v_mfma_f32_16x16x32_bf16 v[108:111], v[144:147], v[176:179], v[108:111]
	v_mfma_f32_16x16x32_bf16 v[104:107], v[152:155], v[176:179], v[104:107]
	s_waitcnt lgkmcnt(0)
	v_mfma_f32_16x16x32_bf16 v[100:103], v[144:147], v[184:187], v[100:103]
	v_mfma_f32_16x16x32_bf16 v[96:99], v[152:155], v[184:187], v[96:99]
	s_barrier
	ds_read_b128 v[188:191], v135
	ds_read_b128 v[192:195], v135 offset:1024
	ds_read_b128 v[202:205], v135 offset:2048
	ds_read_b128 v[206:209], v135 offset:3072
	s_mov_b32 m0, s28
	s_add_u32 s98, s10, s92
	s_addc_u32 s99, s11, s93
	global_load_lds_dwordx4 v129, s[98:99]
	s_mov_b32 m0, s29
	s_nop 0
	global_load_lds_dwordx4 v130, s[98:99]
	s_barrier
	s_waitcnt lgkmcnt(3)
	v_mfma_f32_16x16x32_bf16 v[92:95], v[188:191], v[156:159], v[92:95]
	s_waitcnt lgkmcnt(1)
	v_mfma_f32_16x16x32_bf16 v[88:91], v[202:205], v[156:159], v[88:91]
	v_mfma_f32_16x16x32_bf16 v[84:87], v[188:191], v[164:167], v[84:87]
	v_mfma_f32_16x16x32_bf16 v[80:83], v[202:205], v[164:167], v[80:83]
	v_mfma_f32_16x16x32_bf16 v[76:79], v[188:191], v[172:175], v[76:79]
	v_mfma_f32_16x16x32_bf16 v[72:75], v[202:205], v[172:175], v[72:75]
	v_mfma_f32_16x16x32_bf16 v[68:71], v[188:191], v[180:183], v[68:71]
	v_mfma_f32_16x16x32_bf16 v[64:67], v[202:205], v[180:183], v[64:67]
	v_mfma_f32_16x16x32_bf16 v[92:95], v[192:195], v[160:163], v[92:95]
	s_waitcnt lgkmcnt(0)
	v_mfma_f32_16x16x32_bf16 v[88:91], v[206:209], v[160:163], v[88:91]
	v_mfma_f32_16x16x32_bf16 v[84:87], v[192:195], v[168:171], v[84:87]
	v_mfma_f32_16x16x32_bf16 v[80:83], v[206:209], v[168:171], v[80:83]
	v_mfma_f32_16x16x32_bf16 v[76:79], v[192:195], v[176:179], v[76:79]
	v_mfma_f32_16x16x32_bf16 v[72:75], v[206:209], v[176:179], v[72:75]
	v_mfma_f32_16x16x32_bf16 v[68:71], v[192:195], v[184:187], v[68:71]
	v_mfma_f32_16x16x32_bf16 v[64:67], v[206:209], v[184:187], v[64:67]
	v_mov_b32_e32 v210, v130
	s_barrier
	v_mov_b32_e32 v211, v197
	s_mov_b32 m0, s72
	s_add_u32 s98, s8, s96
	s_addc_u32 s99, s9, s97
	global_load_lds_dwordx4 v129, s[98:99]
	s_mov_b32 m0, s73
	s_nop 0
	global_load_lds_dwordx4 v130, s[98:99]
	s_waitcnt vmcnt(4)
	s_barrier
	v_mov_b32_e32 v196, v129
	s_mov_b32 m0, s33
	s_add_u32 s98, s10, vcc_lo
	s_addc_u32 s99, s11, vcc_hi
	global_load_lds_dwordx4 v129, s[98:99]
	s_mov_b32 m0, s74
	s_nop 0
	global_load_lds_dwordx4 v130, s[98:99]
	s_barrier
	s_add_i32 s38, s38, 2
	s_add_u32 s6, s6, 0x100
	s_addc_u32 s7, s7, 0
	s_cmpk_lt_u32 s38, 0x54
	s_cbranch_scc1 .Lh2_loop
	s_add_u32 s4, s4, 0x2b80
	s_addc_u32 s5, s5, 0
	s_mov_b32 m0, s76
	ds_read_b128 v[140:143], v138
	ds_read_b128 v[144:147], v138 offset:1024
	ds_read_b128 v[148:151], v138 offset:2048
	ds_read_b128 v[152:155], v138 offset:3072
	ds_read_b128 v[156:159], v134
	ds_read_b128 v[160:163], v134 offset:1024
	ds_read_b128 v[164:167], v133
	ds_read_b128 v[168:171], v133 offset:1024
	ds_read_b128 v[172:175], v132
	ds_read_b128 v[176:179], v132 offset:1024
	ds_read_b128 v[180:183], v131
	ds_read_b128 v[184:187], v131 offset:1024
	s_nop 0
	s_mov_b32 m0, s75
	s_nop 0
	s_barrier
	s_waitcnt lgkmcnt(0)
	s_setprio 1
	s_waitcnt lgkmcnt(0)
	v_mfma_f32_16x16x32_bf16 v[124:127], v[140:143], v[156:159], v[124:127]
	v_mfma_f32_16x16x32_bf16 v[120:123], v[148:151], v[156:159], v[120:123]
	v_mfma_f32_16x16x32_bf16 v[116:119], v[140:143], v[164:167], v[116:119]
	v_mfma_f32_16x16x32_bf16 v[112:115], v[148:151], v[164:167], v[112:115]
	v_mfma_f32_16x16x32_bf16 v[108:111], v[140:143], v[172:175], v[108:111]
	v_mfma_f32_16x16x32_bf16 v[100:103], v[140:143], v[180:183], v[100:103]
	v_mfma_f32_16x16x32_bf16 v[96:99], v[148:151], v[180:183], v[96:99]
	v_mfma_f32_16x16x32_bf16 v[124:127], v[144:147], v[160:163], v[124:127]
	v_mfma_f32_16x16x32_bf16 v[120:123], v[152:155], v[160:163], v[120:123]
	v_mfma_f32_16x16x32_bf16 v[116:119], v[144:147], v[168:171], v[116:119]
	v_mfma_f32_16x16x32_bf16 v[112:115], v[152:155], v[168:171], v[112:115]
	v_mfma_f32_16x16x32_bf16 v[108:111], v[144:147], v[176:179], v[108:111]
	v_mfma_f32_16x16x32_bf16 v[104:107], v[148:151], v[172:175], v[104:107]
	v_mfma_f32_16x16x32_bf16 v[100:103], v[144:147], v[184:187], v[100:103]
	v_mfma_f32_16x16x32_bf16 v[96:99], v[152:155], v[184:187], v[96:99]
	v_mfma_f32_16x16x32_bf16 v[188:191], v[152:155], v[176:179], v[104:107]
	s_setprio 0
	s_barrier
	s_nop 2
	ds_read_b128 v[104:107], v137
	ds_read_b128 v[192:195], v137 offset:1024
	ds_read_b128 v[202:205], v137 offset:2048
	ds_read_b128 v[206:209], v137 offset:3072
	s_barrier
	s_waitcnt lgkmcnt(0)
	s_setprio 1
	s_waitcnt lgkmcnt(0)
	v_mfma_f32_16x16x32_bf16 v[92:95], v[104:107], v[156:159], v[92:95]
	v_mfma_f32_16x16x32_bf16 v[88:91], v[202:205], v[156:159], v[88:91]
	v_mfma_f32_16x16x32_bf16 v[80:83], v[202:205], v[164:167], v[80:83]
	v_mfma_f32_16x16x32_bf16 v[72:75], v[202:205], v[172:175], v[72:75]
	v_mfma_f32_16x16x32_bf16 v[64:67], v[202:205], v[180:183], v[64:67]
	v_mfma_f32_16x16x32_bf16 v[92:95], v[192:195], v[160:163], v[92:95]
	v_mfma_f32_16x16x32_bf16 v[88:91], v[206:209], v[160:163], v[88:91]
	v_mfma_f32_16x16x32_bf16 v[84:87], v[104:107], v[164:167], v[84:87]
	v_mfma_f32_16x16x32_bf16 v[80:83], v[206:209], v[168:171], v[80:83]
	v_mfma_f32_16x16x32_bf16 v[76:79], v[104:107], v[172:175], v[76:79]
	v_mfma_f32_16x16x32_bf16 v[72:75], v[206:209], v[176:179], v[72:75]
	v_mfma_f32_16x16x32_bf16 v[68:71], v[104:107], v[180:183], v[68:71]
	v_mfma_f32_16x16x32_bf16 v[64:67], v[206:209], v[184:187], v[64:67]
	v_mfma_f32_16x16x32_bf16 v[156:159], v[192:195], v[168:171], v[84:87]
	v_mfma_f32_16x16x32_bf16 v[160:163], v[192:195], v[176:179], v[76:79]
	v_mfma_f32_16x16x32_bf16 v[164:167], v[192:195], v[184:187], v[68:71]
	s_setprio 0
	s_barrier
	s_nop 1
	s_waitcnt vmcnt(2)
	s_barrier
	s_waitcnt lgkmcnt(0)
	s_setprio 1
	s_waitcnt lgkmcnt(0)
	s_setprio 0
	s_setprio 1
	s_setprio 0
	s_barrier
	ds_read_b128 v[16:19], v136
	ds_read_b128 v[180:183], v136 offset:1024
	ds_read_b128 v[184:187], v136 offset:2048
	ds_read_b128 v[192:195], v136 offset:3072
	ds_read_b128 v[0:3], v134 offset:32768
	ds_read_b128 v[4:7], v134 offset:33792
	ds_read_b128 v[8:11], v133 offset:32768
	ds_read_b128 v[12:15], v133 offset:33792
	ds_read_b128 v[44:47], v132 offset:32768
	ds_read_b128 v[202:205], v132 offset:33792
	ds_read_b128 v[206:209], v131 offset:32768
	ds_read_b128 v[222:225], v131 offset:33792
	s_waitcnt vmcnt(0)
	s_barrier
	s_waitcnt lgkmcnt(0)
	s_setprio 1
	s_waitcnt lgkmcnt(0)
	v_mfma_f32_16x16x32_bf16 v[28:31], v[16:19], v[0:3], v[124:127]
	v_mfma_f32_16x16x32_bf16 v[52:55], v[180:183], v[4:7], v[28:31]
	v_mfma_f32_16x16x32_bf16 v[28:31], v[184:187], v[0:3], v[120:123]
	v_mfma_f32_16x16x32_bf16 v[104:107], v[192:195], v[4:7], v[28:31]
	v_mfma_f32_16x16x32_bf16 v[28:31], v[16:19], v[8:11], v[116:119]
	v_mfma_f32_16x16x32_bf16 v[68:71], v[180:183], v[12:15], v[28:31]
	v_mfma_f32_16x16x32_bf16 v[28:31], v[184:187], v[8:11], v[112:115]
	v_mfma_f32_16x16x32_bf16 v[116:119], v[192:195], v[12:15], v[28:31]
	v_mfma_f32_16x16x32_bf16 v[28:31], v[16:19], v[44:47], v[108:111]
	v_mfma_f32_16x16x32_bf16 v[76:79], v[180:183], v[202:205], v[28:31]
	v_mfma_f32_16x16x32_bf16 v[28:31], v[184:187], v[44:47], v[188:191]
	v_mfma_f32_16x16x32_bf16 v[108:111], v[192:195], v[202:205], v[28:31]
	v_mfma_f32_16x16x32_bf16 v[28:31], v[16:19], v[206:209], v[100:103]
	v_mfma_f32_16x16x32_bf16 v[84:87], v[180:183], v[222:225], v[28:31]
	v_mfma_f32_16x16x32_bf16 v[28:31], v[184:187], v[206:209], v[96:99]
	v_mfma_f32_16x16x32_bf16 v[96:99], v[192:195], v[222:225], v[28:31]
	s_setprio 0
	s_barrier
	ds_read_b128 v[188:191], v135
	ds_read_b128 v[228:231], v135 offset:1024
	ds_read_b128 v[232:235], v135 offset:2048
	ds_read_b128 v[236:239], v135 offset:3072
	s_waitcnt vmcnt(0)
	s_barrier
	s_waitcnt lgkmcnt(0)
	s_setprio 1
	s_waitcnt lgkmcnt(0)
	v_mfma_f32_16x16x32_bf16 v[28:31], v[188:191], v[0:3], v[92:95]
	v_mfma_f32_16x16x32_bf16 v[0:3], v[232:235], v[0:3], v[88:91]
	v_mfma_f32_16x16x32_bf16 v[28:31], v[228:231], v[4:7], v[28:31]
	v_mfma_f32_16x16x32_bf16 v[0:3], v[236:239], v[4:7], v[0:3]
	v_mfma_f32_16x16x32_bf16 v[4:7], v[188:191], v[8:11], v[156:159]
	v_mfma_f32_16x16x32_bf16 v[36:39], v[228:231], v[12:15], v[4:7]
	v_mfma_f32_16x16x32_bf16 v[4:7], v[232:235], v[8:11], v[80:83]
	v_mfma_f32_16x16x32_bf16 v[4:7], v[236:239], v[12:15], v[4:7]
	v_mfma_f32_16x16x32_bf16 v[8:11], v[188:191], v[44:47], v[160:163]
	v_mfma_f32_16x16x32_bf16 v[12:15], v[188:191], v[206:209], v[164:167]
	v_mfma_f32_16x16x32_bf16 v[40:43], v[228:231], v[202:205], v[8:11]
	v_mfma_f32_16x16x32_bf16 v[8:11], v[232:235], v[44:47], v[72:75]
	v_mfma_f32_16x16x32_bf16 v[44:47], v[228:231], v[222:225], v[12:15]
	v_mfma_f32_16x16x32_bf16 v[12:15], v[232:235], v[206:209], v[64:67]
	v_mfma_f32_16x16x32_bf16 v[8:11], v[236:239], v[202:205], v[8:11]
	v_mfma_f32_16x16x32_bf16 v[12:15], v[236:239], v[222:225], v[12:15]
	s_setprio 0
	s_barrier
	s_barrier
	s_waitcnt lgkmcnt(0)
	s_setprio 1
	s_waitcnt lgkmcnt(0)
	s_setprio 0
	s_setprio 1
	s_setprio 0
	s_movk_i32 s4, 0x100
	v_cmp_gt_u32_e32 vcc, s4, v128
	s_barrier
	s_and_saveexec_b64 s[4:5], vcc
	s_cbranch_execz .Lh2_epi
	s_barrier

.LBB0_138:
	ds_read_b128 v[140:143], v138
	ds_read_b128 v[144:147], v138 offset:1024
	ds_read_b128 v[148:151], v138 offset:2048
	ds_read_b128 v[152:155], v138 offset:3072
	s_add_u32 s8, s6, s65
	s_addc_u32 s9, s7, s66
	ds_read_b128 v[156:159], v134
	ds_read_b128 v[160:163], v134 offset:1024
	ds_read_b128 v[164:167], v133
	ds_read_b128 v[168:171], v133 offset:1024
	ds_read_b128 v[172:175], v132
	ds_read_b128 v[176:179], v132 offset:1024
	ds_read_b128 v[180:183], v131
	ds_read_b128 v[184:187], v131 offset:1024
	s_mov_b32 m0, s76
	s_add_u32 s98, s8, s44
	s_addc_u32 s99, s9, s45
	global_load_lds_dwordx4 v129, s[98:99]
	s_mov_b32 m0, s75
	s_nop 0
	global_load_lds_dwordx4 v130, s[98:99]
	s_waitcnt lgkmcnt(8)
	s_barrier
	s_waitcnt lgkmcnt(7)
	v_mfma_f32_16x16x32_bf16 v[124:127], v[140:143], v[156:159], v[124:127]
	v_mfma_f32_16x16x32_bf16 v[120:123], v[148:151], v[156:159], v[120:123]
	s_waitcnt lgkmcnt(5)
	v_mfma_f32_16x16x32_bf16 v[116:119], v[140:143], v[164:167], v[116:119]
	v_mfma_f32_16x16x32_bf16 v[112:115], v[148:151], v[164:167], v[112:115]
	s_waitcnt lgkmcnt(3)
	v_mfma_f32_16x16x32_bf16 v[108:111], v[140:143], v[172:175], v[108:111]
	v_mfma_f32_16x16x32_bf16 v[104:107], v[148:151], v[172:175], v[104:107]
	s_waitcnt lgkmcnt(1)
	v_mfma_f32_16x16x32_bf16 v[100:103], v[140:143], v[180:183], v[100:103]
	v_mfma_f32_16x16x32_bf16 v[96:99], v[148:151], v[180:183], v[96:99]
	v_mfma_f32_16x16x32_bf16 v[124:127], v[144:147], v[160:163], v[124:127]
	v_mfma_f32_16x16x32_bf16 v[120:123], v[152:155], v[160:163], v[120:123]
	v_mfma_f32_16x16x32_bf16 v[116:119], v[144:147], v[168:171], v[116:119]
	v_mfma_f32_16x16x32_bf16 v[112:115], v[152:155], v[168:171], v[112:115]
	v_mfma_f32_16x16x32_bf16 v[108:111], v[144:147], v[176:179], v[108:111]
	v_mfma_f32_16x16x32_bf16 v[104:107], v[152:155], v[176:179], v[104:107]
	s_waitcnt lgkmcnt(0)
	v_mfma_f32_16x16x32_bf16 v[100:103], v[144:147], v[184:187], v[100:103]
	v_mfma_f32_16x16x32_bf16 v[96:99], v[152:155], v[184:187], v[96:99]
	s_barrier
	s_add_u32 s10, s6, s36
	s_addc_u32 s11, s7, s37
	ds_read_b128 v[188:191], v137
	ds_read_b128 v[192:195], v137 offset:1024
	ds_read_b128 v[202:205], v137 offset:2048
	ds_read_b128 v[206:209], v137 offset:3072
	s_mov_b32 m0, s63
	s_add_u32 s98, s10, s46
	s_addc_u32 s99, s11, s47
	global_load_lds_dwordx4 v129, s[98:99]
	s_mov_b32 m0, s64
	s_nop 0
	global_load_lds_dwordx4 v130, s[98:99]
	s_barrier
	s_waitcnt lgkmcnt(3)
	v_mfma_f32_16x16x32_bf16 v[92:95], v[188:191], v[156:159], v[92:95]
	s_waitcnt lgkmcnt(1)
	v_mfma_f32_16x16x32_bf16 v[88:91], v[202:205], v[156:159], v[88:91]
	v_mfma_f32_16x16x32_bf16 v[84:87], v[188:191], v[164:167], v[84:87]
	v_mfma_f32_16x16x32_bf16 v[80:83], v[202:205], v[164:167], v[80:83]
	v_mfma_f32_16x16x32_bf16 v[76:79], v[188:191], v[172:175], v[76:79]
	v_mfma_f32_16x16x32_bf16 v[72:75], v[202:205], v[172:175], v[72:75]
	v_mfma_f32_16x16x32_bf16 v[68:71], v[188:191], v[180:183], v[68:71]
	v_mfma_f32_16x16x32_bf16 v[64:67], v[202:205], v[180:183], v[64:67]
	v_mfma_f32_16x16x32_bf16 v[92:95], v[192:195], v[160:163], v[92:95]
	s_waitcnt lgkmcnt(0)
	v_mfma_f32_16x16x32_bf16 v[88:91], v[206:209], v[160:163], v[88:91]
	v_mfma_f32_16x16x32_bf16 v[84:87], v[192:195], v[168:171], v[84:87]
	v_mfma_f32_16x16x32_bf16 v[80:83], v[206:209], v[168:171], v[80:83]
	v_mfma_f32_16x16x32_bf16 v[76:79], v[192:195], v[176:179], v[76:79]
	v_mfma_f32_16x16x32_bf16 v[72:75], v[206:209], v[176:179], v[72:75]
	v_mfma_f32_16x16x32_bf16 v[68:71], v[192:195], v[184:187], v[68:71]
	v_mfma_f32_16x16x32_bf16 v[64:67], v[206:209], v[184:187], v[64:67]
	s_barrier
	ds_read_b128 v[156:159], v134 offset:16384
	ds_read_b128 v[160:163], v134 offset:17408
	ds_read_b128 v[164:167], v133 offset:16384
	ds_read_b128 v[168:171], v133 offset:17408
	ds_read_b128 v[172:175], v132 offset:16384
	ds_read_b128 v[176:179], v132 offset:17408
	ds_read_b128 v[180:183], v131 offset:16384
	ds_read_b128 v[184:187], v131 offset:17408
	s_mov_b32 m0, s62
	s_add_u32 s98, s8, s48
	s_addc_u32 s99, s9, s49
	global_load_lds_dwordx4 v129, s[98:99]
	s_mov_b32 m0, s67
	s_nop 0
	global_load_lds_dwordx4 v130, s[98:99]
	s_barrier
	s_waitcnt lgkmcnt(7)
	v_mfma_f32_16x16x32_bf16 v[60:63], v[140:143], v[156:159], v[60:63]
	v_mfma_f32_16x16x32_bf16 v[56:59], v[148:151], v[156:159], v[56:59]
	s_waitcnt lgkmcnt(5)
	v_mfma_f32_16x16x32_bf16 v[52:55], v[140:143], v[164:167], v[52:55]
	v_mfma_f32_16x16x32_bf16 v[48:51], v[148:151], v[164:167], v[48:51]
	s_waitcnt lgkmcnt(3)
	v_mfma_f32_16x16x32_bf16 v[44:47], v[140:143], v[172:175], v[44:47]
	v_mfma_f32_16x16x32_bf16 v[40:43], v[148:151], v[172:175], v[40:43]
	s_waitcnt lgkmcnt(1)
	v_mfma_f32_16x16x32_bf16 v[36:39], v[140:143], v[180:183], v[36:39]
	v_mfma_f32_16x16x32_bf16 v[32:35], v[148:151], v[180:183], v[32:35]
	v_mfma_f32_16x16x32_bf16 v[60:63], v[144:147], v[160:163], v[60:63]
	v_mfma_f32_16x16x32_bf16 v[56:59], v[152:155], v[160:163], v[56:59]
	v_mfma_f32_16x16x32_bf16 v[52:55], v[144:147], v[168:171], v[52:55]
	v_mfma_f32_16x16x32_bf16 v[48:51], v[152:155], v[168:171], v[48:51]
	v_mfma_f32_16x16x32_bf16 v[44:47], v[144:147], v[176:179], v[44:47]
	v_mfma_f32_16x16x32_bf16 v[40:43], v[152:155], v[176:179], v[40:43]
	s_waitcnt lgkmcnt(0)
	v_mfma_f32_16x16x32_bf16 v[36:39], v[144:147], v[184:187], v[36:39]
	v_mfma_f32_16x16x32_bf16 v[32:35], v[152:155], v[184:187], v[32:35]
	s_barrier
	s_mov_b32 m0, s68
	s_add_u32 s98, s10, s50
	s_addc_u32 s99, s11, s51
	global_load_lds_dwordx4 v129, s[98:99]
	s_mov_b32 m0, s69
	s_nop 0
	global_load_lds_dwordx4 v130, s[98:99]
	s_waitcnt vmcnt(6)
	s_barrier
	v_mfma_f32_16x16x32_bf16 v[28:31], v[188:191], v[156:159], v[28:31]
	v_mfma_f32_16x16x32_bf16 v[24:27], v[202:205], v[156:159], v[24:27]
	v_mfma_f32_16x16x32_bf16 v[20:23], v[188:191], v[164:167], v[20:23]
	v_mfma_f32_16x16x32_bf16 v[16:19], v[202:205], v[164:167], v[16:19]
	v_mfma_f32_16x16x32_bf16 v[12:15], v[188:191], v[172:175], v[12:15]
	v_mfma_f32_16x16x32_bf16 v[8:11], v[202:205], v[172:175], v[8:11]
	v_mfma_f32_16x16x32_bf16 v[4:7], v[188:191], v[180:183], v[4:7]
	v_mfma_f32_16x16x32_bf16 v[0:3], v[202:205], v[180:183], v[0:3]
	v_mfma_f32_16x16x32_bf16 v[28:31], v[192:195], v[160:163], v[28:31]
	v_mfma_f32_16x16x32_bf16 v[24:27], v[206:209], v[160:163], v[24:27]
	v_mfma_f32_16x16x32_bf16 v[20:23], v[192:195], v[168:171], v[20:23]
	v_mfma_f32_16x16x32_bf16 v[16:19], v[206:209], v[168:171], v[16:19]
	v_mfma_f32_16x16x32_bf16 v[12:15], v[192:195], v[176:179], v[12:15]
	v_mfma_f32_16x16x32_bf16 v[8:11], v[206:209], v[176:179], v[8:11]
	v_mfma_f32_16x16x32_bf16 v[4:7], v[192:195], v[184:187], v[4:7]
	v_mfma_f32_16x16x32_bf16 v[0:3], v[206:209], v[184:187], v[0:3]
	s_barrier
	ds_read_b128 v[140:143], v136
	ds_read_b128 v[144:147], v136 offset:1024
	ds_read_b128 v[148:151], v136 offset:2048
	ds_read_b128 v[152:155], v136 offset:3072
	ds_read_b128 v[156:159], v134 offset:32768
	ds_read_b128 v[160:163], v134 offset:33792
	ds_read_b128 v[164:167], v133 offset:32768
	ds_read_b128 v[168:171], v133 offset:33792
	ds_read_b128 v[172:175], v132 offset:32768
	ds_read_b128 v[176:179], v132 offset:33792
	ds_read_b128 v[180:183], v131 offset:32768
	ds_read_b128 v[184:187], v131 offset:33792
	s_mov_b32 m0, s70
	s_add_u32 s98, s8, s90
	s_addc_u32 s99, s9, s91
	global_load_lds_dwordx4 v129, s[98:99]
	s_mov_b32 m0, s71
	s_nop 0
	global_load_lds_dwordx4 v130, s[98:99]
	s_waitcnt lgkmcnt(8)
	s_barrier
	s_waitcnt lgkmcnt(7)
	v_mfma_f32_16x16x32_bf16 v[124:127], v[140:143], v[156:159], v[124:127]
	v_mfma_f32_16x16x32_bf16 v[120:123], v[148:151], v[156:159], v[120:123]
	s_waitcnt lgkmcnt(5)
	v_mfma_f32_16x16x32_bf16 v[116:119], v[140:143], v[164:167], v[116:119]
	v_mfma_f32_16x16x32_bf16 v[112:115], v[148:151], v[164:167], v[112:115]
	s_waitcnt lgkmcnt(3)
	v_mfma_f32_16x16x32_bf16 v[108:111], v[140:143], v[172:175], v[108:111]
	v_mfma_f32_16x16x32_bf16 v[104:107], v[148:151], v[172:175], v[104:107]
	s_waitcnt lgkmcnt(1)
	v_mfma_f32_16x16x32_bf16 v[100:103], v[140:143], v[180:183], v[100:103]
	v_mfma_f32_16x16x32_bf16 v[96:99], v[148:151], v[180:183], v[96:99]
	v_mfma_f32_16x16x32_bf16 v[124:127], v[144:147], v[160:163], v[124:127]
	v_mfma_f32_16x16x32_bf16 v[120:123], v[152:155], v[160:163], v[120:123]
	v_mfma_f32_16x16x32_bf16 v[116:119], v[144:147], v[168:171], v[116:119]
	v_mfma_f32_16x16x32_bf16 v[112:115], v[152:155], v[168:171], v[112:115]
	v_mfma_f32_16x16x32_bf16 v[108:111], v[144:147], v[176:179], v[108:111]
	v_mfma_f32_16x16x32_bf16 v[104:107], v[152:155], v[176:179], v[104:107]
	s_waitcnt lgkmcnt(0)
	v_mfma_f32_16x16x32_bf16 v[100:103], v[144:147], v[184:187], v[100:103]
	v_mfma_f32_16x16x32_bf16 v[96:99], v[152:155], v[184:187], v[96:99]
	s_barrier
	ds_read_b128 v[188:191], v135
	ds_read_b128 v[192:195], v135 offset:1024
	ds_read_b128 v[202:205], v135 offset:2048
	ds_read_b128 v[206:209], v135 offset:3072
	s_mov_b32 m0, s28
	s_add_u32 s98, s10, s92
	s_addc_u32 s99, s11, s93
	global_load_lds_dwordx4 v129, s[98:99]
	s_mov_b32 m0, s29
	s_nop 0
	global_load_lds_dwordx4 v130, s[98:99]
	s_barrier
	s_waitcnt lgkmcnt(3)
	v_mfma_f32_16x16x32_bf16 v[92:95], v[188:191], v[156:159], v[92:95]
	s_waitcnt lgkmcnt(1)
	v_mfma_f32_16x16x32_bf16 v[88:91], v[202:205], v[156:159], v[88:91]
	v_mfma_f32_16x16x32_bf16 v[84:87], v[188:191], v[164:167], v[84:87]
	v_mfma_f32_16x16x32_bf16 v[80:83], v[202:205], v[164:167], v[80:83]
	v_mfma_f32_16x16x32_bf16 v[76:79], v[188:191], v[172:175], v[76:79]
	v_mfma_f32_16x16x32_bf16 v[72:75], v[202:205], v[172:175], v[72:75]
	v_mfma_f32_16x16x32_bf16 v[68:71], v[188:191], v[180:183], v[68:71]
	v_mfma_f32_16x16x32_bf16 v[64:67], v[202:205], v[180:183], v[64:67]
	v_mfma_f32_16x16x32_bf16 v[92:95], v[192:195], v[160:163], v[92:95]
	s_waitcnt lgkmcnt(0)
	v_mfma_f32_16x16x32_bf16 v[88:91], v[206:209], v[160:163], v[88:91]
	v_mfma_f32_16x16x32_bf16 v[84:87], v[192:195], v[168:171], v[84:87]
	v_mfma_f32_16x16x32_bf16 v[80:83], v[206:209], v[168:171], v[80:83]
	v_mfma_f32_16x16x32_bf16 v[76:79], v[192:195], v[176:179], v[76:79]
	v_mfma_f32_16x16x32_bf16 v[72:75], v[206:209], v[176:179], v[72:75]
	v_mfma_f32_16x16x32_bf16 v[68:71], v[192:195], v[184:187], v[68:71]
	v_mfma_f32_16x16x32_bf16 v[64:67], v[206:209], v[184:187], v[64:67]
	v_mov_b32_e32 v210, v130
	s_barrier
	ds_read_b128 v[156:159], v134 offset:49152
	ds_read_b128 v[160:163], v134 offset:50176
	ds_read_b128 v[164:167], v133 offset:49152
	ds_read_b128 v[168:171], v133 offset:50176
	ds_read_b128 v[172:175], v132 offset:49152
	ds_read_b128 v[176:179], v132 offset:50176
	ds_read_b128 v[180:183], v131 offset:49152
	ds_read_b128 v[184:187], v131 offset:50176
	v_mov_b32_e32 v211, v197
	s_mov_b32 m0, s72
	s_add_u32 s98, s8, s96
	s_addc_u32 s99, s9, s97
	global_load_lds_dwordx4 v129, s[98:99]
	s_mov_b32 m0, s73
	s_nop 0
	global_load_lds_dwordx4 v130, s[98:99]
	s_barrier
	s_waitcnt lgkmcnt(7)
	v_mfma_f32_16x16x32_bf16 v[60:63], v[140:143], v[156:159], v[60:63]
	v_mfma_f32_16x16x32_bf16 v[56:59], v[148:151], v[156:159], v[56:59]
	s_waitcnt lgkmcnt(5)
	v_mfma_f32_16x16x32_bf16 v[52:55], v[140:143], v[164:167], v[52:55]
	v_mfma_f32_16x16x32_bf16 v[48:51], v[148:151], v[164:167], v[48:51]
	s_waitcnt lgkmcnt(3)
	v_mfma_f32_16x16x32_bf16 v[44:47], v[140:143], v[172:175], v[44:47]
	v_mfma_f32_16x16x32_bf16 v[40:43], v[148:151], v[172:175], v[40:43]
	s_waitcnt lgkmcnt(1)
	v_mfma_f32_16x16x32_bf16 v[36:39], v[140:143], v[180:183], v[36:39]
	v_mfma_f32_16x16x32_bf16 v[32:35], v[148:151], v[180:183], v[32:35]
	v_mfma_f32_16x16x32_bf16 v[60:63], v[144:147], v[160:163], v[60:63]
	v_mfma_f32_16x16x32_bf16 v[56:59], v[152:155], v[160:163], v[56:59]
	v_mfma_f32_16x16x32_bf16 v[52:55], v[144:147], v[168:171], v[52:55]
	v_mfma_f32_16x16x32_bf16 v[48:51], v[152:155], v[168:171], v[48:51]
	v_mfma_f32_16x16x32_bf16 v[44:47], v[144:147], v[176:179], v[44:47]
	v_mfma_f32_16x16x32_bf16 v[40:43], v[152:155], v[176:179], v[40:43]
	s_waitcnt lgkmcnt(0)
	v_mfma_f32_16x16x32_bf16 v[36:39], v[144:147], v[184:187], v[36:39]
	v_mfma_f32_16x16x32_bf16 v[32:35], v[152:155], v[184:187], v[32:35]
	s_barrier
	v_mov_b32_e32 v196, v129
	s_mov_b32 m0, s33
	s_add_u32 s98, s10, vcc_lo
	s_addc_u32 s99, s11, vcc_hi
	global_load_lds_dwordx4 v129, s[98:99]
	s_mov_b32 m0, s74
	s_nop 0
	global_load_lds_dwordx4 v130, s[98:99]
	s_waitcnt vmcnt(6)
	s_barrier
	v_mfma_f32_16x16x32_bf16 v[28:31], v[188:191], v[156:159], v[28:31]
	v_mfma_f32_16x16x32_bf16 v[24:27], v[202:205], v[156:159], v[24:27]
	v_mfma_f32_16x16x32_bf16 v[20:23], v[188:191], v[164:167], v[20:23]
	v_mfma_f32_16x16x32_bf16 v[16:19], v[202:205], v[164:167], v[16:19]
	v_mfma_f32_16x16x32_bf16 v[12:15], v[188:191], v[172:175], v[12:15]
	v_mfma_f32_16x16x32_bf16 v[8:11], v[202:205], v[172:175], v[8:11]
	v_mfma_f32_16x16x32_bf16 v[4:7], v[188:191], v[180:183], v[4:7]
	v_mfma_f32_16x16x32_bf16 v[0:3], v[202:205], v[180:183], v[0:3]
	v_mfma_f32_16x16x32_bf16 v[28:31], v[192:195], v[160:163], v[28:31]
	v_mfma_f32_16x16x32_bf16 v[24:27], v[206:209], v[160:163], v[24:27]
	v_mfma_f32_16x16x32_bf16 v[20:23], v[192:195], v[168:171], v[20:23]
	v_mfma_f32_16x16x32_bf16 v[16:19], v[206:209], v[168:171], v[16:19]
	v_mfma_f32_16x16x32_bf16 v[12:15], v[192:195], v[176:179], v[12:15]
	v_mfma_f32_16x16x32_bf16 v[8:11], v[206:209], v[176:179], v[8:11]
	v_mfma_f32_16x16x32_bf16 v[4:7], v[192:195], v[184:187], v[4:7]
	v_mfma_f32_16x16x32_bf16 v[0:3], v[206:209], v[184:187], v[0:3]
	s_add_i32 s38, s38, 2
	s_add_u32 s6, s6, 0x100
	s_addc_u32 s7, s7, 0
	s_cmpk_lt_u32 s38, 0x54
	s_barrier
	s_cbranch_scc1 .LBB0_138
	s_add_u32 s4, s4, 0x2b80
	s_addc_u32 s5, s5, 0
	s_mov_b32 m0, s76
	ds_read_b128 v[140:143], v138
	ds_read_b128 v[144:147], v138 offset:1024
	ds_read_b128 v[148:151], v138 offset:2048
	ds_read_b128 v[152:155], v138 offset:3072
	ds_read_b128 v[156:159], v134
	ds_read_b128 v[160:163], v134 offset:1024
	ds_read_b128 v[164:167], v133
	ds_read_b128 v[168:171], v133 offset:1024
	ds_read_b128 v[172:175], v132
	ds_read_b128 v[176:179], v132 offset:1024
	ds_read_b128 v[180:183], v131
	ds_read_b128 v[184:187], v131 offset:1024
	s_nop 0
	global_load_lds_dwordx4 v129, s[4:5]
	s_mov_b32 m0, s75
	s_nop 0
	global_load_lds_dwordx4 v130, s[4:5]
	s_barrier
	s_waitcnt lgkmcnt(0)
	s_setprio 1
	s_waitcnt lgkmcnt(0)
	v_mfma_f32_16x16x32_bf16 v[124:127], v[140:143], v[156:159], v[124:127]
	v_mfma_f32_16x16x32_bf16 v[120:123], v[148:151], v[156:159], v[120:123]
	v_mfma_f32_16x16x32_bf16 v[116:119], v[140:143], v[164:167], v[116:119]
	v_mfma_f32_16x16x32_bf16 v[112:115], v[148:151], v[164:167], v[112:115]
	v_mfma_f32_16x16x32_bf16 v[108:111], v[140:143], v[172:175], v[108:111]
	v_mfma_f32_16x16x32_bf16 v[100:103], v[140:143], v[180:183], v[100:103]
	v_mfma_f32_16x16x32_bf16 v[96:99], v[148:151], v[180:183], v[96:99]
	v_mfma_f32_16x16x32_bf16 v[124:127], v[144:147], v[160:163], v[124:127]
	v_mfma_f32_16x16x32_bf16 v[120:123], v[152:155], v[160:163], v[120:123]
	v_mfma_f32_16x16x32_bf16 v[116:119], v[144:147], v[168:171], v[116:119]
	v_mfma_f32_16x16x32_bf16 v[112:115], v[152:155], v[168:171], v[112:115]
	v_mfma_f32_16x16x32_bf16 v[108:111], v[144:147], v[176:179], v[108:111]
	v_mfma_f32_16x16x32_bf16 v[104:107], v[148:151], v[172:175], v[104:107]
	v_mfma_f32_16x16x32_bf16 v[100:103], v[144:147], v[184:187], v[100:103]
	v_mfma_f32_16x16x32_bf16 v[96:99], v[152:155], v[184:187], v[96:99]
	v_mfma_f32_16x16x32_bf16 v[188:191], v[152:155], v[176:179], v[104:107]
	s_setprio 0
	s_barrier
	s_nop 2
	ds_read_b128 v[104:107], v137
	ds_read_b128 v[192:195], v137 offset:1024
	ds_read_b128 v[202:205], v137 offset:2048
	ds_read_b128 v[206:209], v137 offset:3072
	s_barrier
	s_waitcnt lgkmcnt(0)
	s_setprio 1
	s_waitcnt lgkmcnt(0)
	v_mfma_f32_16x16x32_bf16 v[92:95], v[104:107], v[156:159], v[92:95]
	v_mfma_f32_16x16x32_bf16 v[88:91], v[202:205], v[156:159], v[88:91]
	v_mfma_f32_16x16x32_bf16 v[80:83], v[202:205], v[164:167], v[80:83]
	v_mfma_f32_16x16x32_bf16 v[72:75], v[202:205], v[172:175], v[72:75]
	v_mfma_f32_16x16x32_bf16 v[64:67], v[202:205], v[180:183], v[64:67]
	v_mfma_f32_16x16x32_bf16 v[92:95], v[192:195], v[160:163], v[92:95]
	v_mfma_f32_16x16x32_bf16 v[88:91], v[206:209], v[160:163], v[88:91]
	v_mfma_f32_16x16x32_bf16 v[84:87], v[104:107], v[164:167], v[84:87]
	v_mfma_f32_16x16x32_bf16 v[80:83], v[206:209], v[168:171], v[80:83]
	v_mfma_f32_16x16x32_bf16 v[76:79], v[104:107], v[172:175], v[76:79]
	v_mfma_f32_16x16x32_bf16 v[72:75], v[206:209], v[176:179], v[72:75]
	v_mfma_f32_16x16x32_bf16 v[68:71], v[104:107], v[180:183], v[68:71]
	v_mfma_f32_16x16x32_bf16 v[64:67], v[206:209], v[184:187], v[64:67]
	v_mfma_f32_16x16x32_bf16 v[156:159], v[192:195], v[168:171], v[84:87]
	v_mfma_f32_16x16x32_bf16 v[160:163], v[192:195], v[176:179], v[76:79]
	v_mfma_f32_16x16x32_bf16 v[164:167], v[192:195], v[184:187], v[68:71]
	s_setprio 0
	s_barrier
	s_nop 1
	ds_read_b128 v[68:71], v134 offset:16384
	ds_read_b128 v[76:79], v134 offset:17408
	ds_read_b128 v[84:87], v133 offset:16384
	ds_read_b128 v[168:171], v133 offset:17408
	ds_read_b128 v[172:175], v132 offset:16384
	ds_read_b128 v[176:179], v132 offset:17408
	ds_read_b128 v[180:183], v131 offset:16384
	ds_read_b128 v[184:187], v131 offset:17408
	s_waitcnt vmcnt(4)
	s_barrier
	s_waitcnt lgkmcnt(0)
	s_setprio 1
	s_waitcnt lgkmcnt(0)
	v_mfma_f32_16x16x32_bf16 v[60:63], v[140:143], v[68:71], v[60:63]
	v_mfma_f32_16x16x32_bf16 v[56:59], v[148:151], v[68:71], v[56:59]
	v_mfma_f32_16x16x32_bf16 v[48:51], v[148:151], v[84:87], v[48:51]
	v_mfma_f32_16x16x32_bf16 v[32:35], v[148:151], v[180:183], v[32:35]
	v_mfma_f32_16x16x32_bf16 v[60:63], v[144:147], v[76:79], v[60:63]
	v_mfma_f32_16x16x32_bf16 v[56:59], v[152:155], v[76:79], v[56:59]
	v_mfma_f32_16x16x32_bf16 v[52:55], v[140:143], v[84:87], v[52:55]
	v_mfma_f32_16x16x32_bf16 v[48:51], v[152:155], v[168:171], v[48:51]
	v_mfma_f32_16x16x32_bf16 v[44:47], v[140:143], v[172:175], v[44:47]
	v_mfma_f32_16x16x32_bf16 v[40:43], v[148:151], v[172:175], v[40:43]
	v_mfma_f32_16x16x32_bf16 v[36:39], v[140:143], v[180:183], v[36:39]
	v_mfma_f32_16x16x32_bf16 v[32:35], v[152:155], v[184:187], v[32:35]
	v_mfma_f32_16x16x32_bf16 v[210:213], v[144:147], v[168:171], v[52:55]
	v_mfma_f32_16x16x32_bf16 v[214:217], v[144:147], v[176:179], v[44:47]
	v_mfma_f32_16x16x32_bf16 v[218:221], v[152:155], v[176:179], v[40:43]
	v_mfma_f32_16x16x32_bf16 v[138:141], v[144:147], v[184:187], v[36:39]
	s_setprio 0
	s_setprio 1
	v_mfma_f32_16x16x32_bf16 v[24:27], v[202:205], v[68:71], v[24:27]
	v_mfma_f32_16x16x32_bf16 v[20:23], v[104:107], v[84:87], v[20:23]
	v_mfma_f32_16x16x32_bf16 v[28:31], v[104:107], v[68:71], v[28:31]
	v_mfma_f32_16x16x32_bf16 v[24:27], v[206:209], v[76:79], v[24:27]
	v_mfma_f32_16x16x32_bf16 v[20:23], v[192:195], v[168:171], v[20:23]
	v_mfma_f32_16x16x32_bf16 v[16:19], v[202:205], v[84:87], v[16:19]
	v_mfma_f32_16x16x32_bf16 v[12:15], v[104:107], v[172:175], v[12:15]
	v_mfma_f32_16x16x32_bf16 v[8:11], v[202:205], v[172:175], v[8:11]
	v_mfma_f32_16x16x32_bf16 v[4:7], v[104:107], v[180:183], v[4:7]
	v_mfma_f32_16x16x32_bf16 v[0:3], v[202:205], v[180:183], v[0:3]
	v_mfma_f32_16x16x32_bf16 v[142:145], v[192:195], v[76:79], v[28:31]
	v_mfma_f32_16x16x32_bf16 v[146:149], v[206:209], v[168:171], v[16:19]
	v_mfma_f32_16x16x32_bf16 v[150:153], v[192:195], v[176:179], v[12:15]
	v_mfma_f32_16x16x32_bf16 v[168:171], v[206:209], v[176:179], v[8:11]
	v_mfma_f32_16x16x32_bf16 v[172:175], v[192:195], v[184:187], v[4:7]
	v_mfma_f32_16x16x32_bf16 v[176:179], v[206:209], v[184:187], v[0:3]
	s_setprio 0
	s_barrier
	ds_read_b128 v[16:19], v136
	ds_read_b128 v[180:183], v136 offset:1024
	ds_read_b128 v[184:187], v136 offset:2048
	ds_read_b128 v[192:195], v136 offset:3072
	ds_read_b128 v[0:3], v134 offset:32768
	ds_read_b128 v[4:7], v134 offset:33792
	ds_read_b128 v[8:11], v133 offset:32768
	ds_read_b128 v[12:15], v133 offset:33792
	ds_read_b128 v[44:47], v132 offset:32768
	ds_read_b128 v[202:205], v132 offset:33792
	ds_read_b128 v[206:209], v131 offset:32768
	ds_read_b128 v[222:225], v131 offset:33792
	s_waitcnt vmcnt(2)
	s_barrier
	s_waitcnt lgkmcnt(0)
	s_setprio 1
	s_waitcnt lgkmcnt(0)
	v_mfma_f32_16x16x32_bf16 v[28:31], v[16:19], v[0:3], v[124:127]
	v_mfma_f32_16x16x32_bf16 v[52:55], v[180:183], v[4:7], v[28:31]
	v_mfma_f32_16x16x32_bf16 v[28:31], v[184:187], v[0:3], v[120:123]
	v_mfma_f32_16x16x32_bf16 v[104:107], v[192:195], v[4:7], v[28:31]
	v_mfma_f32_16x16x32_bf16 v[28:31], v[16:19], v[8:11], v[116:119]
	v_mfma_f32_16x16x32_bf16 v[68:71], v[180:183], v[12:15], v[28:31]
	v_mfma_f32_16x16x32_bf16 v[28:31], v[184:187], v[8:11], v[112:115]
	v_mfma_f32_16x16x32_bf16 v[116:119], v[192:195], v[12:15], v[28:31]
	v_mfma_f32_16x16x32_bf16 v[28:31], v[16:19], v[44:47], v[108:111]
	v_mfma_f32_16x16x32_bf16 v[76:79], v[180:183], v[202:205], v[28:31]
	v_mfma_f32_16x16x32_bf16 v[28:31], v[184:187], v[44:47], v[188:191]
	v_mfma_f32_16x16x32_bf16 v[108:111], v[192:195], v[202:205], v[28:31]
	v_mfma_f32_16x16x32_bf16 v[28:31], v[16:19], v[206:209], v[100:103]
	v_mfma_f32_16x16x32_bf16 v[84:87], v[180:183], v[222:225], v[28:31]
	v_mfma_f32_16x16x32_bf16 v[28:31], v[184:187], v[206:209], v[96:99]
	v_mfma_f32_16x16x32_bf16 v[96:99], v[192:195], v[222:225], v[28:31]
	s_setprio 0
	s_barrier
	ds_read_b128 v[188:191], v135
	ds_read_b128 v[228:231], v135 offset:1024
	ds_read_b128 v[232:235], v135 offset:2048
	ds_read_b128 v[236:239], v135 offset:3072
	s_waitcnt vmcnt(0)
	s_barrier
	s_waitcnt lgkmcnt(0)
	s_setprio 1
	s_waitcnt lgkmcnt(0)
	v_mfma_f32_16x16x32_bf16 v[28:31], v[188:191], v[0:3], v[92:95]
	v_mfma_f32_16x16x32_bf16 v[0:3], v[232:235], v[0:3], v[88:91]
	v_mfma_f32_16x16x32_bf16 v[28:31], v[228:231], v[4:7], v[28:31]
	v_mfma_f32_16x16x32_bf16 v[0:3], v[236:239], v[4:7], v[0:3]
	v_mfma_f32_16x16x32_bf16 v[4:7], v[188:191], v[8:11], v[156:159]
	v_mfma_f32_16x16x32_bf16 v[36:39], v[228:231], v[12:15], v[4:7]
	v_mfma_f32_16x16x32_bf16 v[4:7], v[232:235], v[8:11], v[80:83]
	v_mfma_f32_16x16x32_bf16 v[4:7], v[236:239], v[12:15], v[4:7]
	v_mfma_f32_16x16x32_bf16 v[8:11], v[188:191], v[44:47], v[160:163]
	v_mfma_f32_16x16x32_bf16 v[12:15], v[188:191], v[206:209], v[164:167]
	v_mfma_f32_16x16x32_bf16 v[40:43], v[228:231], v[202:205], v[8:11]
	v_mfma_f32_16x16x32_bf16 v[8:11], v[232:235], v[44:47], v[72:75]
	v_mfma_f32_16x16x32_bf16 v[44:47], v[228:231], v[222:225], v[12:15]
	v_mfma_f32_16x16x32_bf16 v[12:15], v[232:235], v[206:209], v[64:67]
	v_mfma_f32_16x16x32_bf16 v[8:11], v[236:239], v[202:205], v[8:11]
	v_mfma_f32_16x16x32_bf16 v[12:15], v[236:239], v[222:225], v[12:15]
	s_setprio 0
	s_barrier
	ds_read_b128 v[64:67], v134 offset:49152
	ds_read_b128 v[134:137], v134 offset:50176
	ds_read_b128 v[154:157], v133 offset:49152
	ds_read_b128 v[158:161], v133 offset:50176
	ds_read_b128 v[162:165], v132 offset:49152
	ds_read_b128 v[202:205], v132 offset:50176
	ds_read_b128 v[206:209], v131 offset:49152
	ds_read_b128 v[130:133], v131 offset:50176
	s_barrier
	s_waitcnt lgkmcnt(0)
	s_setprio 1
	s_waitcnt lgkmcnt(0)
	v_mfma_f32_16x16x32_bf16 v[56:59], v[184:187], v[64:67], v[56:59]
	v_mfma_f32_16x16x32_bf16 v[48:51], v[184:187], v[154:157], v[48:51]
	v_mfma_f32_16x16x32_bf16 v[60:63], v[16:19], v[64:67], v[60:63]
	v_mfma_f32_16x16x32_bf16 v[92:95], v[192:195], v[134:137], v[56:59]
	v_mfma_f32_16x16x32_bf16 v[56:59], v[16:19], v[154:157], v[210:213]
	v_mfma_f32_16x16x32_bf16 v[88:91], v[192:195], v[158:161], v[48:51]
	v_mfma_f32_16x16x32_bf16 v[48:51], v[16:19], v[162:165], v[214:217]
	v_mfma_f32_16x16x32_bf16 v[16:19], v[16:19], v[206:209], v[138:141]
	v_mfma_f32_16x16x32_bf16 v[120:123], v[180:183], v[202:205], v[48:51]
	v_mfma_f32_16x16x32_bf16 v[48:51], v[184:187], v[162:165], v[218:221]
	v_mfma_f32_16x16x32_bf16 v[124:127], v[180:183], v[130:133], v[16:19]
	v_mfma_f32_16x16x32_bf16 v[16:19], v[184:187], v[206:209], v[32:35]
	v_mfma_f32_16x16x32_bf16 v[100:103], v[180:183], v[134:137], v[60:63]
	v_mfma_f32_16x16x32_bf16 v[112:115], v[180:183], v[158:161], v[56:59]
	v_mfma_f32_16x16x32_bf16 v[80:83], v[192:195], v[202:205], v[48:51]
	v_mfma_f32_16x16x32_bf16 v[72:75], v[192:195], v[130:133], v[16:19]
	s_setprio 0
	s_setprio 1
	v_mfma_f32_16x16x32_bf16 v[16:19], v[188:191], v[64:67], v[142:145]
	v_mfma_f32_16x16x32_bf16 v[48:51], v[228:231], v[134:137], v[16:19]
	v_mfma_f32_16x16x32_bf16 v[16:19], v[232:235], v[64:67], v[24:27]
	v_mfma_f32_16x16x32_bf16 v[20:23], v[188:191], v[154:157], v[20:23]
	v_mfma_f32_16x16x32_bf16 v[24:27], v[188:191], v[162:165], v[150:153]
	v_mfma_f32_16x16x32_bf16 v[32:35], v[188:191], v[206:209], v[172:175]
	v_mfma_f32_16x16x32_bf16 v[56:59], v[228:231], v[158:161], v[20:23]
	v_mfma_f32_16x16x32_bf16 v[20:23], v[232:235], v[154:157], v[146:149]
	v_mfma_f32_16x16x32_bf16 v[60:63], v[228:231], v[202:205], v[24:27]
	v_mfma_f32_16x16x32_bf16 v[24:27], v[232:235], v[162:165], v[168:171]
	v_mfma_f32_16x16x32_bf16 v[64:67], v[228:231], v[130:133], v[32:35]
	v_mfma_f32_16x16x32_bf16 v[32:35], v[232:235], v[206:209], v[176:179]
	v_mfma_f32_16x16x32_bf16 v[16:19], v[236:239], v[134:137], v[16:19]
	v_mfma_f32_16x16x32_bf16 v[20:23], v[236:239], v[158:161], v[20:23]
	v_mfma_f32_16x16x32_bf16 v[24:27], v[236:239], v[202:205], v[24:27]
	v_mfma_f32_16x16x32_bf16 v[32:35], v[236:239], v[130:133], v[32:35]
	s_setprio 0
	s_movk_i32 s4, 0x100
	v_cmp_gt_u32_e32 vcc, s4, v128
	s_barrier
	s_and_saveexec_b64 s[4:5], vcc
	s_cbranch_execz .LBB0_95
	s_barrier
	s_branch .LBB0_95

.Lhf_192:
	ds_read_b128 v[140:143], v129
	ds_read_b128 v[144:147], v129 offset:1024
	ds_read_b128 v[148:151], v129 offset:2048
	ds_read_b128 v[152:155], v129 offset:3072
	s_add_u32 s28, s56, s4
	s_addc_u32 s29, s57, s5
	ds_read_b128 v[156:159], v136
	ds_read_b128 v[160:163], v136 offset:1024
	ds_read_b128 v[164:167], v135
	ds_read_b128 v[168:171], v135 offset:1024
	ds_read_b128 v[172:175], v134
	ds_read_b128 v[176:179], v134 offset:1024
	ds_read_b128 v[180:183], v133
	ds_read_b128 v[184:187], v133 offset:1024
	s_add_i32 s40, s52, 0xc000
	s_mov_b32 m0, s40
	s_add_i32 s39, s52, 0xe000
	s_mov_b32 m0, s39
	s_nop 0
	s_waitcnt lgkmcnt(8)
	s_barrier
	s_waitcnt lgkmcnt(7)
	v_mfma_f32_16x16x32_bf16 v[124:127], v[140:143], v[156:159], v[124:127]
	v_mfma_f32_16x16x32_bf16 v[120:123], v[148:151], v[156:159], v[120:123]
	s_waitcnt lgkmcnt(5)
	v_mfma_f32_16x16x32_bf16 v[116:119], v[140:143], v[164:167], v[116:119]
	v_mfma_f32_16x16x32_bf16 v[112:115], v[148:151], v[164:167], v[112:115]
	s_waitcnt lgkmcnt(3)
	v_mfma_f32_16x16x32_bf16 v[108:111], v[140:143], v[172:175], v[108:111]
	v_mfma_f32_16x16x32_bf16 v[104:107], v[148:151], v[172:175], v[104:107]
	s_waitcnt lgkmcnt(1)
	v_mfma_f32_16x16x32_bf16 v[100:103], v[140:143], v[180:183], v[100:103]
	v_mfma_f32_16x16x32_bf16 v[96:99], v[148:151], v[180:183], v[96:99]
	v_mfma_f32_16x16x32_bf16 v[124:127], v[144:147], v[160:163], v[124:127]
	v_mfma_f32_16x16x32_bf16 v[120:123], v[152:155], v[160:163], v[120:123]
	v_mfma_f32_16x16x32_bf16 v[116:119], v[144:147], v[168:171], v[116:119]
	v_mfma_f32_16x16x32_bf16 v[112:115], v[152:155], v[168:171], v[112:115]
	v_mfma_f32_16x16x32_bf16 v[108:111], v[144:147], v[176:179], v[108:111]
	v_mfma_f32_16x16x32_bf16 v[104:107], v[152:155], v[176:179], v[104:107]
	s_waitcnt lgkmcnt(0)
	v_mfma_f32_16x16x32_bf16 v[100:103], v[144:147], v[184:187], v[100:103]
	v_mfma_f32_16x16x32_bf16 v[96:99], v[152:155], v[184:187], v[96:99]
	s_barrier
	s_add_u32 s58, s56, s36
	s_addc_u32 s59, s57, s37
	ds_read_b128 v[188:191], v139
	ds_read_b128 v[192:195], v139 offset:1024
	ds_read_b128 v[202:205], v139 offset:2048
	ds_read_b128 v[206:209], v139 offset:3072
	s_add_i32 m0, s52, 0x10000
	s_add_u32 s98, s58, s46
	s_addc_u32 s99, s59, s47
	global_load_lds_dwordx4 v128, s[98:99]
	s_add_i32 m0, s52, 0x12000
	s_nop 0
	global_load_lds_dwordx4 v130, s[98:99]
	s_barrier
	s_waitcnt lgkmcnt(3)
	v_mfma_f32_16x16x32_bf16 v[92:95], v[188:191], v[156:159], v[92:95]
	s_waitcnt lgkmcnt(1)
	v_mfma_f32_16x16x32_bf16 v[88:91], v[202:205], v[156:159], v[88:91]
	v_mfma_f32_16x16x32_bf16 v[84:87], v[188:191], v[164:167], v[84:87]
	v_mfma_f32_16x16x32_bf16 v[80:83], v[202:205], v[164:167], v[80:83]
	v_mfma_f32_16x16x32_bf16 v[76:79], v[188:191], v[172:175], v[76:79]
	v_mfma_f32_16x16x32_bf16 v[72:75], v[202:205], v[172:175], v[72:75]
	v_mfma_f32_16x16x32_bf16 v[68:71], v[188:191], v[180:183], v[68:71]
	v_mfma_f32_16x16x32_bf16 v[64:67], v[202:205], v[180:183], v[64:67]
	v_mfma_f32_16x16x32_bf16 v[92:95], v[192:195], v[160:163], v[92:95]
	s_waitcnt lgkmcnt(0)
	v_mfma_f32_16x16x32_bf16 v[88:91], v[206:209], v[160:163], v[88:91]
	v_mfma_f32_16x16x32_bf16 v[84:87], v[192:195], v[168:171], v[84:87]
	v_mfma_f32_16x16x32_bf16 v[80:83], v[206:209], v[168:171], v[80:83]
	v_mfma_f32_16x16x32_bf16 v[76:79], v[192:195], v[176:179], v[76:79]
	v_mfma_f32_16x16x32_bf16 v[72:75], v[206:209], v[176:179], v[72:75]
	v_mfma_f32_16x16x32_bf16 v[68:71], v[192:195], v[184:187], v[68:71]
	v_mfma_f32_16x16x32_bf16 v[64:67], v[206:209], v[184:187], v[64:67]
	s_barrier
	s_mov_b32 m0, s52
	s_add_u32 s98, s28, s48
	s_addc_u32 s99, s29, s49
	global_load_lds_dwordx4 v128, s[98:99]
	s_add_i32 m0, s52, 0x2000
	s_nop 0
	global_load_lds_dwordx4 v130, s[98:99]
	s_waitcnt vmcnt(4)
	s_barrier
	s_add_i32 m0, s52, 0x14000
	s_add_u32 s98, s58, s50
	s_addc_u32 s99, s59, s51
	global_load_lds_dwordx4 v128, s[98:99]
	s_add_i32 m0, s52, 0x16000
	s_nop 0
	global_load_lds_dwordx4 v130, s[98:99]
	s_barrier
	ds_read_b128 v[140:143], v138
	ds_read_b128 v[144:147], v138 offset:1024
	ds_read_b128 v[148:151], v138 offset:2048
	ds_read_b128 v[152:155], v138 offset:3072
	ds_read_b128 v[156:159], v136 offset:32768
	ds_read_b128 v[160:163], v136 offset:33792
	ds_read_b128 v[164:167], v135 offset:32768
	ds_read_b128 v[168:171], v135 offset:33792
	ds_read_b128 v[172:175], v134 offset:32768
	ds_read_b128 v[176:179], v134 offset:33792
	ds_read_b128 v[180:183], v133 offset:32768
	ds_read_b128 v[184:187], v133 offset:33792
	s_add_i32 m0, s52, 0x4000
	s_add_i32 m0, s52, 0x6000
	s_nop 0
	s_waitcnt lgkmcnt(8)
	s_barrier
	s_waitcnt lgkmcnt(7)
	v_mfma_f32_16x16x32_bf16 v[124:127], v[140:143], v[156:159], v[124:127]
	v_mfma_f32_16x16x32_bf16 v[120:123], v[148:151], v[156:159], v[120:123]
	s_waitcnt lgkmcnt(5)
	v_mfma_f32_16x16x32_bf16 v[116:119], v[140:143], v[164:167], v[116:119]
	v_mfma_f32_16x16x32_bf16 v[112:115], v[148:151], v[164:167], v[112:115]
	s_waitcnt lgkmcnt(3)
	v_mfma_f32_16x16x32_bf16 v[108:111], v[140:143], v[172:175], v[108:111]
	v_mfma_f32_16x16x32_bf16 v[104:107], v[148:151], v[172:175], v[104:107]
	s_waitcnt lgkmcnt(1)
	v_mfma_f32_16x16x32_bf16 v[100:103], v[140:143], v[180:183], v[100:103]
	v_mfma_f32_16x16x32_bf16 v[96:99], v[148:151], v[180:183], v[96:99]
	v_mfma_f32_16x16x32_bf16 v[124:127], v[144:147], v[160:163], v[124:127]
	v_mfma_f32_16x16x32_bf16 v[120:123], v[152:155], v[160:163], v[120:123]
	v_mfma_f32_16x16x32_bf16 v[116:119], v[144:147], v[168:171], v[116:119]
	v_mfma_f32_16x16x32_bf16 v[112:115], v[152:155], v[168:171], v[112:115]
	v_mfma_f32_16x16x32_bf16 v[108:111], v[144:147], v[176:179], v[108:111]
	v_mfma_f32_16x16x32_bf16 v[104:107], v[152:155], v[176:179], v[104:107]
	s_waitcnt lgkmcnt(0)
	v_mfma_f32_16x16x32_bf16 v[100:103], v[144:147], v[184:187], v[100:103]
	v_mfma_f32_16x16x32_bf16 v[96:99], v[152:155], v[184:187], v[96:99]
	s_barrier
	ds_read_b128 v[188:191], v137
	ds_read_b128 v[192:195], v137 offset:1024
	ds_read_b128 v[202:205], v137 offset:2048
	ds_read_b128 v[206:209], v137 offset:3072
	s_mov_b32 m0, s7
	s_add_u32 s98, s58, s68
	s_addc_u32 s99, s59, s69
	global_load_lds_dwordx4 v128, s[98:99]
	s_mov_b32 m0, s53
	s_nop 0
	global_load_lds_dwordx4 v130, s[98:99]
	s_barrier
	s_waitcnt lgkmcnt(3)
	v_mfma_f32_16x16x32_bf16 v[92:95], v[188:191], v[156:159], v[92:95]
	s_waitcnt lgkmcnt(1)
	v_mfma_f32_16x16x32_bf16 v[88:91], v[202:205], v[156:159], v[88:91]
	v_mfma_f32_16x16x32_bf16 v[84:87], v[188:191], v[164:167], v[84:87]
	v_mfma_f32_16x16x32_bf16 v[80:83], v[202:205], v[164:167], v[80:83]
	v_mfma_f32_16x16x32_bf16 v[76:79], v[188:191], v[172:175], v[76:79]
	v_mfma_f32_16x16x32_bf16 v[72:75], v[202:205], v[172:175], v[72:75]
	v_mfma_f32_16x16x32_bf16 v[68:71], v[188:191], v[180:183], v[68:71]
	v_mfma_f32_16x16x32_bf16 v[64:67], v[202:205], v[180:183], v[64:67]
	v_mfma_f32_16x16x32_bf16 v[92:95], v[192:195], v[160:163], v[92:95]
	s_waitcnt lgkmcnt(0)
	v_mfma_f32_16x16x32_bf16 v[88:91], v[206:209], v[160:163], v[88:91]
	v_mfma_f32_16x16x32_bf16 v[84:87], v[192:195], v[168:171], v[84:87]
	v_mfma_f32_16x16x32_bf16 v[80:83], v[206:209], v[168:171], v[80:83]
	v_mfma_f32_16x16x32_bf16 v[76:79], v[192:195], v[176:179], v[76:79]
	v_mfma_f32_16x16x32_bf16 v[72:75], v[206:209], v[176:179], v[72:75]
	v_mfma_f32_16x16x32_bf16 v[68:71], v[192:195], v[184:187], v[68:71]
	v_mfma_f32_16x16x32_bf16 v[64:67], v[206:209], v[184:187], v[64:67]
	v_mov_b32_e32 v210, v130
	s_barrier
	v_mov_b32_e32 v211, v197
	s_mov_b32 m0, s9
	s_add_u32 s98, s28, s70
	s_addc_u32 s99, s29, s71
	global_load_lds_dwordx4 v128, s[98:99]
	s_mov_b32 m0, s33
	s_nop 0
	global_load_lds_dwordx4 v130, s[98:99]
	s_waitcnt vmcnt(4)
	s_barrier
	v_mov_b32_e32 v196, v128
	s_mov_b32 m0, s65
	s_add_u32 s98, s58, s72
	s_addc_u32 s99, s59, s73
	global_load_lds_dwordx4 v128, s[98:99]
	s_mov_b32 m0, s66
	s_nop 0
	global_load_lds_dwordx4 v130, s[98:99]
	s_barrier
	s_add_i32 s38, s38, 2
	s_add_u32 s56, s56, 0x100
	s_addc_u32 s57, s57, 0
	s_cmp_lt_u32 s38, 28
	s_cbranch_scc1 .Lhf_192
	s_lshl_b64 s[4:5], s[10:11], 12
	v_readlane_b32 s10, v254, 12
	v_readlane_b32 s11, v254, 13
	s_add_u32 s4, s10, s4
	s_addc_u32 s5, s11, s5
	ds_read_b128 v[140:143], v129
	ds_read_b128 v[144:147], v129 offset:1024
	ds_read_b128 v[148:151], v129 offset:2048
	ds_read_b128 v[152:155], v129 offset:3072
	ds_read_b128 v[156:159], v136
	ds_read_b128 v[160:163], v136 offset:1024
	ds_read_b128 v[164:167], v135
	ds_read_b128 v[168:171], v135 offset:1024
	ds_read_b128 v[172:175], v134
	ds_read_b128 v[176:179], v134 offset:1024
	ds_read_b128 v[180:183], v133
	ds_read_b128 v[184:187], v133 offset:1024
	v_mov_b32_e32 v129, v197
	v_lshl_add_u64 v[128:129], s[4:5], 0, v[128:129]
	s_mov_b64 s[10:11], 0xf80
	s_mov_b32 m0, s40
	v_lshl_add_u64 v[128:129], v[128:129], 0, s[10:11]
	v_mov_b32_e32 v131, v197
	v_lshl_add_u64 v[128:129], s[4:5], 0, v[130:131]
	v_lshl_add_u64 v[128:129], v[128:129], 0, s[10:11]
	s_mov_b32 m0, s39
	s_nop 0
	s_barrier
	s_waitcnt lgkmcnt(0)
	s_setprio 1
	s_waitcnt lgkmcnt(0)
	v_mfma_f32_16x16x32_bf16 v[124:127], v[140:143], v[156:159], v[124:127]
	v_mfma_f32_16x16x32_bf16 v[116:119], v[140:143], v[164:167], v[116:119]
	v_mfma_f32_16x16x32_bf16 v[112:115], v[148:151], v[164:167], v[112:115]
	v_mfma_f32_16x16x32_bf16 v[108:111], v[140:143], v[172:175], v[108:111]
	v_mfma_f32_16x16x32_bf16 v[104:107], v[148:151], v[172:175], v[104:107]
	v_mfma_f32_16x16x32_bf16 v[100:103], v[140:143], v[180:183], v[100:103]
	v_mfma_f32_16x16x32_bf16 v[96:99], v[148:151], v[180:183], v[96:99]
	v_mfma_f32_16x16x32_bf16 v[124:127], v[144:147], v[160:163], v[124:127]
	v_mfma_f32_16x16x32_bf16 v[120:123], v[148:151], v[156:159], v[120:123]
	v_mfma_f32_16x16x32_bf16 v[116:119], v[144:147], v[168:171], v[116:119]
	v_mfma_f32_16x16x32_bf16 v[112:115], v[152:155], v[168:171], v[112:115]
	v_mfma_f32_16x16x32_bf16 v[108:111], v[144:147], v[176:179], v[108:111]
	v_mfma_f32_16x16x32_bf16 v[104:107], v[152:155], v[176:179], v[104:107]
	v_mfma_f32_16x16x32_bf16 v[100:103], v[144:147], v[184:187], v[100:103]
	v_mfma_f32_16x16x32_bf16 v[96:99], v[152:155], v[184:187], v[96:99]
	v_mfma_f32_16x16x32_bf16 v[128:131], v[152:155], v[160:163], v[120:123]
	s_setprio 0
	s_barrier
	s_nop 0
	ds_read_b128 v[120:123], v139
	ds_read_b128 v[188:191], v139 offset:1024
	ds_read_b128 v[192:195], v139 offset:2048
	ds_read_b128 v[202:205], v139 offset:3072
	s_barrier
	s_waitcnt lgkmcnt(0)
	s_setprio 1
	s_waitcnt lgkmcnt(0)
	v_mfma_f32_16x16x32_bf16 v[76:79], v[120:123], v[172:175], v[76:79]
	v_mfma_f32_16x16x32_bf16 v[68:71], v[120:123], v[180:183], v[68:71]
	v_mfma_f32_16x16x32_bf16 v[64:67], v[192:195], v[180:183], v[64:67]
	v_mfma_f32_16x16x32_bf16 v[92:95], v[120:123], v[156:159], v[92:95]
	v_mfma_f32_16x16x32_bf16 v[88:91], v[192:195], v[156:159], v[88:91]
	v_mfma_f32_16x16x32_bf16 v[84:87], v[120:123], v[164:167], v[84:87]
	v_mfma_f32_16x16x32_bf16 v[80:83], v[192:195], v[164:167], v[80:83]
	v_mfma_f32_16x16x32_bf16 v[76:79], v[188:191], v[176:179], v[76:79]
	v_mfma_f32_16x16x32_bf16 v[72:75], v[192:195], v[172:175], v[72:75]
	v_mfma_f32_16x16x32_bf16 v[68:71], v[188:191], v[184:187], v[68:71]
	v_mfma_f32_16x16x32_bf16 v[64:67], v[202:205], v[184:187], v[64:67]
	v_mfma_f32_16x16x32_bf16 v[206:209], v[188:191], v[160:163], v[92:95]
	v_mfma_f32_16x16x32_bf16 v[156:159], v[202:205], v[160:163], v[88:91]
	v_mfma_f32_16x16x32_bf16 v[160:163], v[188:191], v[168:171], v[84:87]
	v_mfma_f32_16x16x32_bf16 v[164:167], v[202:205], v[168:171], v[80:83]
	v_mfma_f32_16x16x32_bf16 v[168:171], v[202:205], v[176:179], v[72:75]
	s_setprio 0
	s_barrier
	s_nop 0
	s_waitcnt vmcnt(2)
	s_barrier
	s_waitcnt lgkmcnt(0)
	s_setprio 1
	s_waitcnt lgkmcnt(0)
	s_setprio 0
	s_setprio 1
	s_setprio 0
	s_barrier
	s_nop 0
	ds_read_b128 v[8:11], v138
	ds_read_b128 v[16:19], v138 offset:1024
	ds_read_b128 v[176:179], v138 offset:2048
	ds_read_b128 v[180:183], v138 offset:3072
	ds_read_b128 v[20:23], v136 offset:32768
	ds_read_b128 v[24:27], v136 offset:33792
	ds_read_b128 v[28:31], v135 offset:32768
	ds_read_b128 v[56:59], v135 offset:33792
	ds_read_b128 v[188:191], v134 offset:32768
	ds_read_b128 v[192:195], v134 offset:33792
	ds_read_b128 v[202:205], v133 offset:32768
	ds_read_b128 v[210:213], v133 offset:33792
	s_waitcnt vmcnt(0)
	s_barrier
	s_waitcnt lgkmcnt(0)
	s_setprio 1
	s_waitcnt lgkmcnt(0)
	v_mfma_f32_16x16x32_bf16 v[72:75], v[8:11], v[20:23], v[124:127]
	v_mfma_f32_16x16x32_bf16 v[120:123], v[16:19], v[24:27], v[72:75]
	v_mfma_f32_16x16x32_bf16 v[72:75], v[176:179], v[20:23], v[128:131]
	v_mfma_f32_16x16x32_bf16 v[124:127], v[180:183], v[24:27], v[72:75]
	v_mfma_f32_16x16x32_bf16 v[72:75], v[8:11], v[28:31], v[116:119]
	v_mfma_f32_16x16x32_bf16 v[116:119], v[16:19], v[56:59], v[72:75]
	v_mfma_f32_16x16x32_bf16 v[72:75], v[176:179], v[28:31], v[112:115]
	v_mfma_f32_16x16x32_bf16 v[112:115], v[180:183], v[56:59], v[72:75]
	v_mfma_f32_16x16x32_bf16 v[72:75], v[8:11], v[188:191], v[108:111]
	v_mfma_f32_16x16x32_bf16 v[88:91], v[16:19], v[192:195], v[72:75]
	v_mfma_f32_16x16x32_bf16 v[72:75], v[176:179], v[188:191], v[104:107]
	v_mfma_f32_16x16x32_bf16 v[92:95], v[180:183], v[192:195], v[72:75]
	v_mfma_f32_16x16x32_bf16 v[72:75], v[8:11], v[202:205], v[100:103]
	v_mfma_f32_16x16x32_bf16 v[84:87], v[16:19], v[210:213], v[72:75]
	v_mfma_f32_16x16x32_bf16 v[72:75], v[176:179], v[202:205], v[96:99]
	v_mfma_f32_16x16x32_bf16 v[80:83], v[180:183], v[210:213], v[72:75]
	s_setprio 0
	s_barrier
	ds_read_b128 v[128:131], v137
	ds_read_b128 v[214:217], v137 offset:1024
	ds_read_b128 v[218:221], v137 offset:2048
	ds_read_b128 v[222:225], v137 offset:3072
	s_waitcnt vmcnt(0)
	s_barrier
	s_waitcnt lgkmcnt(0)
	s_setprio 1
	s_waitcnt lgkmcnt(0)
	v_mfma_f32_16x16x32_bf16 v[72:75], v[128:131], v[20:23], v[206:209]
	v_mfma_f32_16x16x32_bf16 v[20:23], v[218:221], v[20:23], v[156:159]
	v_mfma_f32_16x16x32_bf16 v[108:111], v[222:225], v[24:27], v[20:23]
	v_mfma_f32_16x16x32_bf16 v[20:23], v[128:131], v[28:31], v[160:163]
	v_mfma_f32_16x16x32_bf16 v[100:103], v[214:217], v[56:59], v[20:23]
	v_mfma_f32_16x16x32_bf16 v[20:23], v[218:221], v[28:31], v[164:167]
	v_mfma_f32_16x16x32_bf16 v[96:99], v[222:225], v[56:59], v[20:23]
	v_mfma_f32_16x16x32_bf16 v[20:23], v[128:131], v[188:191], v[76:79]
	v_mfma_f32_16x16x32_bf16 v[104:107], v[214:217], v[24:27], v[72:75]
	v_mfma_f32_16x16x32_bf16 v[72:75], v[214:217], v[192:195], v[20:23]
	v_mfma_f32_16x16x32_bf16 v[20:23], v[218:221], v[188:191], v[168:171]
	v_mfma_f32_16x16x32_bf16 v[76:79], v[222:225], v[192:195], v[20:23]
	v_mfma_f32_16x16x32_bf16 v[20:23], v[128:131], v[202:205], v[68:71]
	v_mfma_f32_16x16x32_bf16 v[68:71], v[214:217], v[210:213], v[20:23]
	v_mfma_f32_16x16x32_bf16 v[20:23], v[218:221], v[202:205], v[64:67]
	v_mfma_f32_16x16x32_bf16 v[64:67], v[222:225], v[210:213], v[20:23]
	s_setprio 0
	s_barrier
	s_barrier
	s_waitcnt lgkmcnt(0)
	s_setprio 1
	s_waitcnt lgkmcnt(0)
	s_setprio 0
	s_setprio 1
	s_setprio 0
	s_movk_i32 s4, 0x100
	v_cmp_gt_u32_e32 vcc, s4, v132
	s_barrier
	s_and_saveexec_b64 s[4:5], vcc
	s_cbranch_execz .Lhf_195
	s_barrier

.LBB0_192:
	ds_read_b128 v[140:143], v129
	ds_read_b128 v[144:147], v129 offset:1024
	ds_read_b128 v[148:151], v129 offset:2048
	ds_read_b128 v[152:155], v129 offset:3072
	s_add_u32 s28, s56, s4
	s_addc_u32 s29, s57, s5
	ds_read_b128 v[156:159], v136
	ds_read_b128 v[160:163], v136 offset:1024
	ds_read_b128 v[164:167], v135
	ds_read_b128 v[168:171], v135 offset:1024
	ds_read_b128 v[172:175], v134
	ds_read_b128 v[176:179], v134 offset:1024
	ds_read_b128 v[180:183], v133
	ds_read_b128 v[184:187], v133 offset:1024
	s_add_i32 s40, s52, 0xc000
	s_mov_b32 m0, s40
	s_add_i32 s39, s52, 0xe000
	s_add_u32 s98, s28, s44
	s_addc_u32 s99, s29, s45
	global_load_lds_dwordx4 v128, s[98:99]
	s_mov_b32 m0, s39
	s_nop 0
	global_load_lds_dwordx4 v130, s[98:99]
	s_waitcnt lgkmcnt(8)
	s_barrier
	s_waitcnt lgkmcnt(7)
	v_mfma_f32_16x16x32_bf16 v[124:127], v[140:143], v[156:159], v[124:127]
	v_mfma_f32_16x16x32_bf16 v[120:123], v[148:151], v[156:159], v[120:123]
	s_waitcnt lgkmcnt(5)
	v_mfma_f32_16x16x32_bf16 v[116:119], v[140:143], v[164:167], v[116:119]
	v_mfma_f32_16x16x32_bf16 v[112:115], v[148:151], v[164:167], v[112:115]
	s_waitcnt lgkmcnt(3)
	v_mfma_f32_16x16x32_bf16 v[108:111], v[140:143], v[172:175], v[108:111]
	v_mfma_f32_16x16x32_bf16 v[104:107], v[148:151], v[172:175], v[104:107]
	s_waitcnt lgkmcnt(1)
	v_mfma_f32_16x16x32_bf16 v[100:103], v[140:143], v[180:183], v[100:103]
	v_mfma_f32_16x16x32_bf16 v[96:99], v[148:151], v[180:183], v[96:99]
	v_mfma_f32_16x16x32_bf16 v[124:127], v[144:147], v[160:163], v[124:127]
	v_mfma_f32_16x16x32_bf16 v[120:123], v[152:155], v[160:163], v[120:123]
	v_mfma_f32_16x16x32_bf16 v[116:119], v[144:147], v[168:171], v[116:119]
	v_mfma_f32_16x16x32_bf16 v[112:115], v[152:155], v[168:171], v[112:115]
	v_mfma_f32_16x16x32_bf16 v[108:111], v[144:147], v[176:179], v[108:111]
	v_mfma_f32_16x16x32_bf16 v[104:107], v[152:155], v[176:179], v[104:107]
	s_waitcnt lgkmcnt(0)
	v_mfma_f32_16x16x32_bf16 v[100:103], v[144:147], v[184:187], v[100:103]
	v_mfma_f32_16x16x32_bf16 v[96:99], v[152:155], v[184:187], v[96:99]
	s_barrier
	s_add_u32 s58, s56, s36
	s_addc_u32 s59, s57, s37
	ds_read_b128 v[188:191], v139
	ds_read_b128 v[192:195], v139 offset:1024
	ds_read_b128 v[202:205], v139 offset:2048
	ds_read_b128 v[206:209], v139 offset:3072
	s_add_i32 m0, s52, 0x10000
	s_add_u32 s98, s58, s46
	s_addc_u32 s99, s59, s47
	global_load_lds_dwordx4 v128, s[98:99]
	s_add_i32 m0, s52, 0x12000
	s_nop 0
	global_load_lds_dwordx4 v130, s[98:99]
	s_barrier
	s_waitcnt lgkmcnt(3)
	v_mfma_f32_16x16x32_bf16 v[92:95], v[188:191], v[156:159], v[92:95]
	s_waitcnt lgkmcnt(1)
	v_mfma_f32_16x16x32_bf16 v[88:91], v[202:205], v[156:159], v[88:91]
	v_mfma_f32_16x16x32_bf16 v[84:87], v[188:191], v[164:167], v[84:87]
	v_mfma_f32_16x16x32_bf16 v[80:83], v[202:205], v[164:167], v[80:83]
	v_mfma_f32_16x16x32_bf16 v[76:79], v[188:191], v[172:175], v[76:79]
	v_mfma_f32_16x16x32_bf16 v[72:75], v[202:205], v[172:175], v[72:75]
	v_mfma_f32_16x16x32_bf16 v[68:71], v[188:191], v[180:183], v[68:71]
	v_mfma_f32_16x16x32_bf16 v[64:67], v[202:205], v[180:183], v[64:67]
	v_mfma_f32_16x16x32_bf16 v[92:95], v[192:195], v[160:163], v[92:95]
	s_waitcnt lgkmcnt(0)
	v_mfma_f32_16x16x32_bf16 v[88:91], v[206:209], v[160:163], v[88:91]
	v_mfma_f32_16x16x32_bf16 v[84:87], v[192:195], v[168:171], v[84:87]
	v_mfma_f32_16x16x32_bf16 v[80:83], v[206:209], v[168:171], v[80:83]
	v_mfma_f32_16x16x32_bf16 v[76:79], v[192:195], v[176:179], v[76:79]
	v_mfma_f32_16x16x32_bf16 v[72:75], v[206:209], v[176:179], v[72:75]
	v_mfma_f32_16x16x32_bf16 v[68:71], v[192:195], v[184:187], v[68:71]
	v_mfma_f32_16x16x32_bf16 v[64:67], v[206:209], v[184:187], v[64:67]
	s_barrier
	ds_read_b128 v[156:159], v136 offset:16384
	ds_read_b128 v[160:163], v136 offset:17408
	ds_read_b128 v[164:167], v135 offset:16384
	ds_read_b128 v[168:171], v135 offset:17408
	ds_read_b128 v[172:175], v134 offset:16384
	ds_read_b128 v[176:179], v134 offset:17408
	ds_read_b128 v[180:183], v133 offset:16384
	ds_read_b128 v[184:187], v133 offset:17408
	s_mov_b32 m0, s52
	s_add_u32 s98, s28, s48
	s_addc_u32 s99, s29, s49
	global_load_lds_dwordx4 v128, s[98:99]
	s_add_i32 m0, s52, 0x2000
	s_nop 0
	global_load_lds_dwordx4 v130, s[98:99]
	s_barrier
	s_waitcnt lgkmcnt(7)
	v_mfma_f32_16x16x32_bf16 v[60:63], v[140:143], v[156:159], v[60:63]
	v_mfma_f32_16x16x32_bf16 v[56:59], v[148:151], v[156:159], v[56:59]
	s_waitcnt lgkmcnt(5)
	v_mfma_f32_16x16x32_bf16 v[52:55], v[140:143], v[164:167], v[52:55]
	v_mfma_f32_16x16x32_bf16 v[48:51], v[148:151], v[164:167], v[48:51]
	s_waitcnt lgkmcnt(3)
	v_mfma_f32_16x16x32_bf16 v[44:47], v[140:143], v[172:175], v[44:47]
	v_mfma_f32_16x16x32_bf16 v[40:43], v[148:151], v[172:175], v[40:43]
	s_waitcnt lgkmcnt(1)
	v_mfma_f32_16x16x32_bf16 v[36:39], v[140:143], v[180:183], v[36:39]
	v_mfma_f32_16x16x32_bf16 v[32:35], v[148:151], v[180:183], v[32:35]
	v_mfma_f32_16x16x32_bf16 v[60:63], v[144:147], v[160:163], v[60:63]
	v_mfma_f32_16x16x32_bf16 v[56:59], v[152:155], v[160:163], v[56:59]
	v_mfma_f32_16x16x32_bf16 v[52:55], v[144:147], v[168:171], v[52:55]
	v_mfma_f32_16x16x32_bf16 v[48:51], v[152:155], v[168:171], v[48:51]
	v_mfma_f32_16x16x32_bf16 v[44:47], v[144:147], v[176:179], v[44:47]
	v_mfma_f32_16x16x32_bf16 v[40:43], v[152:155], v[176:179], v[40:43]
	s_waitcnt lgkmcnt(0)
	v_mfma_f32_16x16x32_bf16 v[36:39], v[144:147], v[184:187], v[36:39]
	v_mfma_f32_16x16x32_bf16 v[32:35], v[152:155], v[184:187], v[32:35]
	s_barrier
	s_add_i32 m0, s52, 0x14000
	s_add_u32 s98, s58, s50
	s_addc_u32 s99, s59, s51
	global_load_lds_dwordx4 v128, s[98:99]
	s_add_i32 m0, s52, 0x16000
	s_nop 0
	global_load_lds_dwordx4 v130, s[98:99]
	s_waitcnt vmcnt(6)
	s_barrier
	v_mfma_f32_16x16x32_bf16 v[28:31], v[188:191], v[156:159], v[28:31]
	v_mfma_f32_16x16x32_bf16 v[24:27], v[202:205], v[156:159], v[24:27]
	v_mfma_f32_16x16x32_bf16 v[20:23], v[188:191], v[164:167], v[20:23]
	v_mfma_f32_16x16x32_bf16 v[16:19], v[202:205], v[164:167], v[16:19]
	v_mfma_f32_16x16x32_bf16 v[12:15], v[188:191], v[172:175], v[12:15]
	v_mfma_f32_16x16x32_bf16 v[8:11], v[202:205], v[172:175], v[8:11]
	v_mfma_f32_16x16x32_bf16 v[4:7], v[188:191], v[180:183], v[4:7]
	v_mfma_f32_16x16x32_bf16 v[0:3], v[202:205], v[180:183], v[0:3]
	v_mfma_f32_16x16x32_bf16 v[28:31], v[192:195], v[160:163], v[28:31]
	v_mfma_f32_16x16x32_bf16 v[24:27], v[206:209], v[160:163], v[24:27]
	v_mfma_f32_16x16x32_bf16 v[20:23], v[192:195], v[168:171], v[20:23]
	v_mfma_f32_16x16x32_bf16 v[16:19], v[206:209], v[168:171], v[16:19]
	v_mfma_f32_16x16x32_bf16 v[12:15], v[192:195], v[176:179], v[12:15]
	v_mfma_f32_16x16x32_bf16 v[8:11], v[206:209], v[176:179], v[8:11]
	v_mfma_f32_16x16x32_bf16 v[4:7], v[192:195], v[184:187], v[4:7]
	v_mfma_f32_16x16x32_bf16 v[0:3], v[206:209], v[184:187], v[0:3]
	s_barrier
	ds_read_b128 v[140:143], v138
	ds_read_b128 v[144:147], v138 offset:1024
	ds_read_b128 v[148:151], v138 offset:2048
	ds_read_b128 v[152:155], v138 offset:3072
	ds_read_b128 v[156:159], v136 offset:32768
	ds_read_b128 v[160:163], v136 offset:33792
	ds_read_b128 v[164:167], v135 offset:32768
	ds_read_b128 v[168:171], v135 offset:33792
	ds_read_b128 v[172:175], v134 offset:32768
	ds_read_b128 v[176:179], v134 offset:33792
	ds_read_b128 v[180:183], v133 offset:32768
	ds_read_b128 v[184:187], v133 offset:33792
	s_add_i32 m0, s52, 0x4000
	s_add_u32 s98, s28, s54
	s_addc_u32 s99, s29, s55
	global_load_lds_dwordx4 v128, s[98:99]
	s_add_i32 m0, s52, 0x6000
	s_nop 0
	global_load_lds_dwordx4 v130, s[98:99]
	s_waitcnt lgkmcnt(8)
	s_barrier
	s_waitcnt lgkmcnt(7)
	v_mfma_f32_16x16x32_bf16 v[124:127], v[140:143], v[156:159], v[124:127]
	v_mfma_f32_16x16x32_bf16 v[120:123], v[148:151], v[156:159], v[120:123]
	s_waitcnt lgkmcnt(5)
	v_mfma_f32_16x16x32_bf16 v[116:119], v[140:143], v[164:167], v[116:119]
	v_mfma_f32_16x16x32_bf16 v[112:115], v[148:151], v[164:167], v[112:115]
	s_waitcnt lgkmcnt(3)
	v_mfma_f32_16x16x32_bf16 v[108:111], v[140:143], v[172:175], v[108:111]
	v_mfma_f32_16x16x32_bf16 v[104:107], v[148:151], v[172:175], v[104:107]
	s_waitcnt lgkmcnt(1)
	v_mfma_f32_16x16x32_bf16 v[100:103], v[140:143], v[180:183], v[100:103]
	v_mfma_f32_16x16x32_bf16 v[96:99], v[148:151], v[180:183], v[96:99]
	v_mfma_f32_16x16x32_bf16 v[124:127], v[144:147], v[160:163], v[124:127]
	v_mfma_f32_16x16x32_bf16 v[120:123], v[152:155], v[160:163], v[120:123]
	v_mfma_f32_16x16x32_bf16 v[116:119], v[144:147], v[168:171], v[116:119]
	v_mfma_f32_16x16x32_bf16 v[112:115], v[152:155], v[168:171], v[112:115]
	v_mfma_f32_16x16x32_bf16 v[108:111], v[144:147], v[176:179], v[108:111]
	v_mfma_f32_16x16x32_bf16 v[104:107], v[152:155], v[176:179], v[104:107]
	s_waitcnt lgkmcnt(0)
	v_mfma_f32_16x16x32_bf16 v[100:103], v[144:147], v[184:187], v[100:103]
	v_mfma_f32_16x16x32_bf16 v[96:99], v[152:155], v[184:187], v[96:99]
	s_barrier
	ds_read_b128 v[188:191], v137
	ds_read_b128 v[192:195], v137 offset:1024
	ds_read_b128 v[202:205], v137 offset:2048
	ds_read_b128 v[206:209], v137 offset:3072
	s_mov_b32 m0, s7
	s_add_u32 s98, s58, s68
	s_addc_u32 s99, s59, s69
	global_load_lds_dwordx4 v128, s[98:99]
	s_mov_b32 m0, s53
	s_nop 0
	global_load_lds_dwordx4 v130, s[98:99]
	s_barrier
	s_waitcnt lgkmcnt(3)
	v_mfma_f32_16x16x32_bf16 v[92:95], v[188:191], v[156:159], v[92:95]
	s_waitcnt lgkmcnt(1)
	v_mfma_f32_16x16x32_bf16 v[88:91], v[202:205], v[156:159], v[88:91]
	v_mfma_f32_16x16x32_bf16 v[84:87], v[188:191], v[164:167], v[84:87]
	v_mfma_f32_16x16x32_bf16 v[80:83], v[202:205], v[164:167], v[80:83]
	v_mfma_f32_16x16x32_bf16 v[76:79], v[188:191], v[172:175], v[76:79]
	v_mfma_f32_16x16x32_bf16 v[72:75], v[202:205], v[172:175], v[72:75]
	v_mfma_f32_16x16x32_bf16 v[68:71], v[188:191], v[180:183], v[68:71]
	v_mfma_f32_16x16x32_bf16 v[64:67], v[202:205], v[180:183], v[64:67]
	v_mfma_f32_16x16x32_bf16 v[92:95], v[192:195], v[160:163], v[92:95]
	s_waitcnt lgkmcnt(0)
	v_mfma_f32_16x16x32_bf16 v[88:91], v[206:209], v[160:163], v[88:91]
	v_mfma_f32_16x16x32_bf16 v[84:87], v[192:195], v[168:171], v[84:87]
	v_mfma_f32_16x16x32_bf16 v[80:83], v[206:209], v[168:171], v[80:83]
	v_mfma_f32_16x16x32_bf16 v[76:79], v[192:195], v[176:179], v[76:79]
	v_mfma_f32_16x16x32_bf16 v[72:75], v[206:209], v[176:179], v[72:75]
	v_mfma_f32_16x16x32_bf16 v[68:71], v[192:195], v[184:187], v[68:71]
	v_mfma_f32_16x16x32_bf16 v[64:67], v[206:209], v[184:187], v[64:67]
	v_mov_b32_e32 v210, v130
	s_barrier
	ds_read_b128 v[156:159], v136 offset:49152
	ds_read_b128 v[160:163], v136 offset:50176
	ds_read_b128 v[164:167], v135 offset:49152
	ds_read_b128 v[168:171], v135 offset:50176
	ds_read_b128 v[172:175], v134 offset:49152
	ds_read_b128 v[176:179], v134 offset:50176
	ds_read_b128 v[180:183], v133 offset:49152
	ds_read_b128 v[184:187], v133 offset:50176
	v_mov_b32_e32 v211, v197
	s_mov_b32 m0, s9
	s_add_u32 s98, s28, s70
	s_addc_u32 s99, s29, s71
	global_load_lds_dwordx4 v128, s[98:99]
	s_mov_b32 m0, s33
	s_nop 0
	global_load_lds_dwordx4 v130, s[98:99]
	s_barrier
	s_waitcnt lgkmcnt(7)
	v_mfma_f32_16x16x32_bf16 v[60:63], v[140:143], v[156:159], v[60:63]
	v_mfma_f32_16x16x32_bf16 v[56:59], v[148:151], v[156:159], v[56:59]
	s_waitcnt lgkmcnt(5)
	v_mfma_f32_16x16x32_bf16 v[52:55], v[140:143], v[164:167], v[52:55]
	v_mfma_f32_16x16x32_bf16 v[48:51], v[148:151], v[164:167], v[48:51]
	s_waitcnt lgkmcnt(3)
	v_mfma_f32_16x16x32_bf16 v[44:47], v[140:143], v[172:175], v[44:47]
	v_mfma_f32_16x16x32_bf16 v[40:43], v[148:151], v[172:175], v[40:43]
	s_waitcnt lgkmcnt(1)
	v_mfma_f32_16x16x32_bf16 v[36:39], v[140:143], v[180:183], v[36:39]
	v_mfma_f32_16x16x32_bf16 v[32:35], v[148:151], v[180:183], v[32:35]
	v_mfma_f32_16x16x32_bf16 v[60:63], v[144:147], v[160:163], v[60:63]
	v_mfma_f32_16x16x32_bf16 v[56:59], v[152:155], v[160:163], v[56:59]
	v_mfma_f32_16x16x32_bf16 v[52:55], v[144:147], v[168:171], v[52:55]
	v_mfma_f32_16x16x32_bf16 v[48:51], v[152:155], v[168:171], v[48:51]
	v_mfma_f32_16x16x32_bf16 v[44:47], v[144:147], v[176:179], v[44:47]
	v_mfma_f32_16x16x32_bf16 v[40:43], v[152:155], v[176:179], v[40:43]
	s_waitcnt lgkmcnt(0)
	v_mfma_f32_16x16x32_bf16 v[36:39], v[144:147], v[184:187], v[36:39]
	v_mfma_f32_16x16x32_bf16 v[32:35], v[152:155], v[184:187], v[32:35]
	s_barrier
	v_mov_b32_e32 v196, v128
	s_mov_b32 m0, s65
	s_add_u32 s98, s58, s72
	s_addc_u32 s99, s59, s73
	global_load_lds_dwordx4 v128, s[98:99]
	s_mov_b32 m0, s66
	s_nop 0
	global_load_lds_dwordx4 v130, s[98:99]
	s_waitcnt vmcnt(6)
	s_barrier
	v_mfma_f32_16x16x32_bf16 v[28:31], v[188:191], v[156:159], v[28:31]
	v_mfma_f32_16x16x32_bf16 v[24:27], v[202:205], v[156:159], v[24:27]
	v_mfma_f32_16x16x32_bf16 v[20:23], v[188:191], v[164:167], v[20:23]
	v_mfma_f32_16x16x32_bf16 v[16:19], v[202:205], v[164:167], v[16:19]
	v_mfma_f32_16x16x32_bf16 v[12:15], v[188:191], v[172:175], v[12:15]
	v_mfma_f32_16x16x32_bf16 v[8:11], v[202:205], v[172:175], v[8:11]
	v_mfma_f32_16x16x32_bf16 v[4:7], v[188:191], v[180:183], v[4:7]
	v_mfma_f32_16x16x32_bf16 v[0:3], v[202:205], v[180:183], v[0:3]
	v_mfma_f32_16x16x32_bf16 v[28:31], v[192:195], v[160:163], v[28:31]
	v_mfma_f32_16x16x32_bf16 v[24:27], v[206:209], v[160:163], v[24:27]
	v_mfma_f32_16x16x32_bf16 v[20:23], v[192:195], v[168:171], v[20:23]
	v_mfma_f32_16x16x32_bf16 v[16:19], v[206:209], v[168:171], v[16:19]
	v_mfma_f32_16x16x32_bf16 v[12:15], v[192:195], v[176:179], v[12:15]
	v_mfma_f32_16x16x32_bf16 v[8:11], v[206:209], v[176:179], v[8:11]
	v_mfma_f32_16x16x32_bf16 v[4:7], v[192:195], v[184:187], v[4:7]
	v_mfma_f32_16x16x32_bf16 v[0:3], v[206:209], v[184:187], v[0:3]
	s_add_i32 s38, s38, 2
	s_add_u32 s56, s56, 0x100
	s_addc_u32 s57, s57, 0
	s_cmp_lt_u32 s38, 28
	s_barrier
	s_cbranch_scc1 .LBB0_192
	s_lshl_b64 s[4:5], s[10:11], 12
	v_readlane_b32 s10, v254, 12
	v_readlane_b32 s11, v254, 13
	s_add_u32 s4, s10, s4
	s_addc_u32 s5, s11, s5
	ds_read_b128 v[140:143], v129
	ds_read_b128 v[144:147], v129 offset:1024
	ds_read_b128 v[148:151], v129 offset:2048
	ds_read_b128 v[152:155], v129 offset:3072
	ds_read_b128 v[156:159], v136
	ds_read_b128 v[160:163], v136 offset:1024
	ds_read_b128 v[164:167], v135
	ds_read_b128 v[168:171], v135 offset:1024
	ds_read_b128 v[172:175], v134
	ds_read_b128 v[176:179], v134 offset:1024
	ds_read_b128 v[180:183], v133
	ds_read_b128 v[184:187], v133 offset:1024
	v_mov_b32_e32 v129, v197
	v_lshl_add_u64 v[128:129], s[4:5], 0, v[128:129]
	s_mov_b64 s[10:11], 0xf80
	s_mov_b32 m0, s40
	v_lshl_add_u64 v[128:129], v[128:129], 0, s[10:11]
	v_mov_b32_e32 v131, v197
	global_load_lds_dwordx4 v[128:129], off
	v_lshl_add_u64 v[128:129], s[4:5], 0, v[130:131]
	v_lshl_add_u64 v[128:129], v[128:129], 0, s[10:11]
	s_mov_b32 m0, s39
	s_nop 0
	global_load_lds_dwordx4 v[128:129], off
	s_barrier
	s_waitcnt lgkmcnt(0)
	s_setprio 1
	s_waitcnt lgkmcnt(0)
	v_mfma_f32_16x16x32_bf16 v[124:127], v[140:143], v[156:159], v[124:127]
	v_mfma_f32_16x16x32_bf16 v[116:119], v[140:143], v[164:167], v[116:119]
	v_mfma_f32_16x16x32_bf16 v[112:115], v[148:151], v[164:167], v[112:115]
	v_mfma_f32_16x16x32_bf16 v[108:111], v[140:143], v[172:175], v[108:111]
	v_mfma_f32_16x16x32_bf16 v[104:107], v[148:151], v[172:175], v[104:107]
	v_mfma_f32_16x16x32_bf16 v[100:103], v[140:143], v[180:183], v[100:103]
	v_mfma_f32_16x16x32_bf16 v[96:99], v[148:151], v[180:183], v[96:99]
	v_mfma_f32_16x16x32_bf16 v[124:127], v[144:147], v[160:163], v[124:127]
	v_mfma_f32_16x16x32_bf16 v[120:123], v[148:151], v[156:159], v[120:123]
	v_mfma_f32_16x16x32_bf16 v[116:119], v[144:147], v[168:171], v[116:119]
	v_mfma_f32_16x16x32_bf16 v[112:115], v[152:155], v[168:171], v[112:115]
	v_mfma_f32_16x16x32_bf16 v[108:111], v[144:147], v[176:179], v[108:111]
	v_mfma_f32_16x16x32_bf16 v[104:107], v[152:155], v[176:179], v[104:107]
	v_mfma_f32_16x16x32_bf16 v[100:103], v[144:147], v[184:187], v[100:103]
	v_mfma_f32_16x16x32_bf16 v[96:99], v[152:155], v[184:187], v[96:99]
	v_mfma_f32_16x16x32_bf16 v[128:131], v[152:155], v[160:163], v[120:123]
	s_setprio 0
	s_barrier
	s_nop 0
	ds_read_b128 v[120:123], v139
	ds_read_b128 v[188:191], v139 offset:1024
	ds_read_b128 v[192:195], v139 offset:2048
	ds_read_b128 v[202:205], v139 offset:3072
	s_barrier
	s_waitcnt lgkmcnt(0)
	s_setprio 1
	s_waitcnt lgkmcnt(0)
	v_mfma_f32_16x16x32_bf16 v[76:79], v[120:123], v[172:175], v[76:79]
	v_mfma_f32_16x16x32_bf16 v[68:71], v[120:123], v[180:183], v[68:71]
	v_mfma_f32_16x16x32_bf16 v[64:67], v[192:195], v[180:183], v[64:67]
	v_mfma_f32_16x16x32_bf16 v[92:95], v[120:123], v[156:159], v[92:95]
	v_mfma_f32_16x16x32_bf16 v[88:91], v[192:195], v[156:159], v[88:91]
	v_mfma_f32_16x16x32_bf16 v[84:87], v[120:123], v[164:167], v[84:87]
	v_mfma_f32_16x16x32_bf16 v[80:83], v[192:195], v[164:167], v[80:83]
	v_mfma_f32_16x16x32_bf16 v[76:79], v[188:191], v[176:179], v[76:79]
	v_mfma_f32_16x16x32_bf16 v[72:75], v[192:195], v[172:175], v[72:75]
	v_mfma_f32_16x16x32_bf16 v[68:71], v[188:191], v[184:187], v[68:71]
	v_mfma_f32_16x16x32_bf16 v[64:67], v[202:205], v[184:187], v[64:67]
	v_mfma_f32_16x16x32_bf16 v[206:209], v[188:191], v[160:163], v[92:95]
	v_mfma_f32_16x16x32_bf16 v[156:159], v[202:205], v[160:163], v[88:91]
	v_mfma_f32_16x16x32_bf16 v[160:163], v[188:191], v[168:171], v[84:87]
	v_mfma_f32_16x16x32_bf16 v[164:167], v[202:205], v[168:171], v[80:83]
	v_mfma_f32_16x16x32_bf16 v[168:171], v[202:205], v[176:179], v[72:75]
	s_setprio 0
	s_barrier
	s_nop 0
	ds_read_b128 v[72:75], v136 offset:16384
	ds_read_b128 v[80:83], v136 offset:17408
	ds_read_b128 v[84:87], v135 offset:16384
	ds_read_b128 v[88:91], v135 offset:17408
	ds_read_b128 v[92:95], v134 offset:16384
	ds_read_b128 v[172:175], v134 offset:17408
	ds_read_b128 v[176:179], v133 offset:16384
	ds_read_b128 v[180:183], v133 offset:17408
	s_waitcnt vmcnt(4)
	s_barrier
	s_waitcnt lgkmcnt(0)
	s_setprio 1
	s_waitcnt lgkmcnt(0)
	v_mfma_f32_16x16x32_bf16 v[60:63], v[140:143], v[72:75], v[60:63]
	v_mfma_f32_16x16x32_bf16 v[52:55], v[140:143], v[84:87], v[52:55]
	v_mfma_f32_16x16x32_bf16 v[48:51], v[148:151], v[84:87], v[48:51]
	v_mfma_f32_16x16x32_bf16 v[44:47], v[140:143], v[92:95], v[44:47]
	v_mfma_f32_16x16x32_bf16 v[40:43], v[148:151], v[92:95], v[40:43]
	v_mfma_f32_16x16x32_bf16 v[36:39], v[140:143], v[176:179], v[36:39]
	v_mfma_f32_16x16x32_bf16 v[32:35], v[148:151], v[176:179], v[32:35]
	v_mfma_f32_16x16x32_bf16 v[60:63], v[144:147], v[80:83], v[60:63]
	v_mfma_f32_16x16x32_bf16 v[56:59], v[148:151], v[72:75], v[56:59]
	v_mfma_f32_16x16x32_bf16 v[52:55], v[144:147], v[88:91], v[52:55]
	v_mfma_f32_16x16x32_bf16 v[48:51], v[152:155], v[88:91], v[48:51]
	v_mfma_f32_16x16x32_bf16 v[44:47], v[144:147], v[172:175], v[44:47]
	v_mfma_f32_16x16x32_bf16 v[40:43], v[152:155], v[172:175], v[40:43]
	v_mfma_f32_16x16x32_bf16 v[36:39], v[144:147], v[180:183], v[36:39]
	v_mfma_f32_16x16x32_bf16 v[32:35], v[152:155], v[180:183], v[32:35]
	v_mfma_f32_16x16x32_bf16 v[184:187], v[152:155], v[80:83], v[56:59]
	s_setprio 0
	s_setprio 1
	v_mfma_f32_16x16x32_bf16 v[12:15], v[120:123], v[92:95], v[12:15]
	v_mfma_f32_16x16x32_bf16 v[4:7], v[120:123], v[176:179], v[4:7]
	v_mfma_f32_16x16x32_bf16 v[0:3], v[192:195], v[176:179], v[0:3]
	v_mfma_f32_16x16x32_bf16 v[28:31], v[120:123], v[72:75], v[28:31]
	v_mfma_f32_16x16x32_bf16 v[24:27], v[192:195], v[72:75], v[24:27]
	v_mfma_f32_16x16x32_bf16 v[20:23], v[120:123], v[84:87], v[20:23]
	v_mfma_f32_16x16x32_bf16 v[16:19], v[192:195], v[84:87], v[16:19]
	v_mfma_f32_16x16x32_bf16 v[12:15], v[188:191], v[172:175], v[12:15]
	v_mfma_f32_16x16x32_bf16 v[8:11], v[192:195], v[92:95], v[8:11]
	v_mfma_f32_16x16x32_bf16 v[4:7], v[188:191], v[180:183], v[4:7]
	v_mfma_f32_16x16x32_bf16 v[0:3], v[202:205], v[180:183], v[0:3]
	v_mfma_f32_16x16x32_bf16 v[140:143], v[188:191], v[80:83], v[28:31]
	v_mfma_f32_16x16x32_bf16 v[144:147], v[202:205], v[80:83], v[24:27]
	v_mfma_f32_16x16x32_bf16 v[148:151], v[188:191], v[88:91], v[20:23]
	v_mfma_f32_16x16x32_bf16 v[152:155], v[202:205], v[88:91], v[16:19]
	v_mfma_f32_16x16x32_bf16 v[172:175], v[202:205], v[172:175], v[8:11]
	s_setprio 0
	s_barrier
	s_nop 0
	ds_read_b128 v[8:11], v138
	ds_read_b128 v[16:19], v138 offset:1024
	ds_read_b128 v[176:179], v138 offset:2048
	ds_read_b128 v[180:183], v138 offset:3072
	ds_read_b128 v[20:23], v136 offset:32768
	ds_read_b128 v[24:27], v136 offset:33792
	ds_read_b128 v[28:31], v135 offset:32768
	ds_read_b128 v[56:59], v135 offset:33792
	ds_read_b128 v[188:191], v134 offset:32768
	ds_read_b128 v[192:195], v134 offset:33792
	ds_read_b128 v[202:205], v133 offset:32768
	ds_read_b128 v[210:213], v133 offset:33792
	s_waitcnt vmcnt(2)
	s_barrier
	s_waitcnt lgkmcnt(0)
	s_setprio 1
	s_waitcnt lgkmcnt(0)
	v_mfma_f32_16x16x32_bf16 v[72:75], v[8:11], v[20:23], v[124:127]
	v_mfma_f32_16x16x32_bf16 v[120:123], v[16:19], v[24:27], v[72:75]
	v_mfma_f32_16x16x32_bf16 v[72:75], v[176:179], v[20:23], v[128:131]
	v_mfma_f32_16x16x32_bf16 v[124:127], v[180:183], v[24:27], v[72:75]
	v_mfma_f32_16x16x32_bf16 v[72:75], v[8:11], v[28:31], v[116:119]
	v_mfma_f32_16x16x32_bf16 v[116:119], v[16:19], v[56:59], v[72:75]
	v_mfma_f32_16x16x32_bf16 v[72:75], v[176:179], v[28:31], v[112:115]
	v_mfma_f32_16x16x32_bf16 v[112:115], v[180:183], v[56:59], v[72:75]
	v_mfma_f32_16x16x32_bf16 v[72:75], v[8:11], v[188:191], v[108:111]
	v_mfma_f32_16x16x32_bf16 v[88:91], v[16:19], v[192:195], v[72:75]
	v_mfma_f32_16x16x32_bf16 v[72:75], v[176:179], v[188:191], v[104:107]
	v_mfma_f32_16x16x32_bf16 v[92:95], v[180:183], v[192:195], v[72:75]
	v_mfma_f32_16x16x32_bf16 v[72:75], v[8:11], v[202:205], v[100:103]
	v_mfma_f32_16x16x32_bf16 v[84:87], v[16:19], v[210:213], v[72:75]
	v_mfma_f32_16x16x32_bf16 v[72:75], v[176:179], v[202:205], v[96:99]
	v_mfma_f32_16x16x32_bf16 v[80:83], v[180:183], v[210:213], v[72:75]
	s_setprio 0
	s_barrier
	ds_read_b128 v[128:131], v137
	ds_read_b128 v[214:217], v137 offset:1024
	ds_read_b128 v[218:221], v137 offset:2048
	ds_read_b128 v[222:225], v137 offset:3072
	s_waitcnt vmcnt(0)
	s_barrier
	s_waitcnt lgkmcnt(0)
	s_setprio 1
	s_waitcnt lgkmcnt(0)
	v_mfma_f32_16x16x32_bf16 v[72:75], v[128:131], v[20:23], v[206:209]
	v_mfma_f32_16x16x32_bf16 v[20:23], v[218:221], v[20:23], v[156:159]
	v_mfma_f32_16x16x32_bf16 v[108:111], v[222:225], v[24:27], v[20:23]
	v_mfma_f32_16x16x32_bf16 v[20:23], v[128:131], v[28:31], v[160:163]
	v_mfma_f32_16x16x32_bf16 v[100:103], v[214:217], v[56:59], v[20:23]
	v_mfma_f32_16x16x32_bf16 v[20:23], v[218:221], v[28:31], v[164:167]
	v_mfma_f32_16x16x32_bf16 v[96:99], v[222:225], v[56:59], v[20:23]
	v_mfma_f32_16x16x32_bf16 v[20:23], v[128:131], v[188:191], v[76:79]
	v_mfma_f32_16x16x32_bf16 v[104:107], v[214:217], v[24:27], v[72:75]
	v_mfma_f32_16x16x32_bf16 v[72:75], v[214:217], v[192:195], v[20:23]
	v_mfma_f32_16x16x32_bf16 v[20:23], v[218:221], v[188:191], v[168:171]
	v_mfma_f32_16x16x32_bf16 v[76:79], v[222:225], v[192:195], v[20:23]
	v_mfma_f32_16x16x32_bf16 v[20:23], v[128:131], v[202:205], v[68:71]
	v_mfma_f32_16x16x32_bf16 v[68:71], v[214:217], v[210:213], v[20:23]
	v_mfma_f32_16x16x32_bf16 v[20:23], v[218:221], v[202:205], v[64:67]
	v_mfma_f32_16x16x32_bf16 v[64:67], v[222:225], v[210:213], v[20:23]
	s_setprio 0
	s_barrier
	ds_read_b128 v[156:159], v136 offset:49152
	ds_read_b128 v[136:139], v136 offset:50176
	ds_read_b128 v[160:163], v135 offset:49152
	ds_read_b128 v[164:167], v135 offset:50176
	ds_read_b128 v[168:171], v134 offset:49152
	ds_read_b128 v[188:191], v134 offset:50176
	ds_read_b128 v[192:195], v133 offset:49152
	ds_read_b128 v[202:205], v133 offset:50176
	s_barrier
	s_waitcnt lgkmcnt(0)
	s_setprio 1
	s_waitcnt lgkmcnt(0)
	v_mfma_f32_16x16x32_bf16 v[20:23], v[8:11], v[156:159], v[60:63]
	v_mfma_f32_16x16x32_bf16 v[56:59], v[16:19], v[136:139], v[20:23]
	v_mfma_f32_16x16x32_bf16 v[20:23], v[176:179], v[156:159], v[184:187]
	v_mfma_f32_16x16x32_bf16 v[60:63], v[180:183], v[136:139], v[20:23]
	v_mfma_f32_16x16x32_bf16 v[20:23], v[8:11], v[160:163], v[52:55]
	v_mfma_f32_16x16x32_bf16 v[52:55], v[16:19], v[164:167], v[20:23]
	v_mfma_f32_16x16x32_bf16 v[20:23], v[176:179], v[160:163], v[48:51]
	v_mfma_f32_16x16x32_bf16 v[48:51], v[180:183], v[164:167], v[20:23]
	v_mfma_f32_16x16x32_bf16 v[20:23], v[8:11], v[168:171], v[44:47]
	v_mfma_f32_16x16x32_bf16 v[24:27], v[16:19], v[188:191], v[20:23]
	v_mfma_f32_16x16x32_bf16 v[20:23], v[176:179], v[168:171], v[40:43]
	v_mfma_f32_16x16x32_bf16 v[8:11], v[8:11], v[192:195], v[36:39]
	v_mfma_f32_16x16x32_bf16 v[28:31], v[180:183], v[188:191], v[20:23]
	v_mfma_f32_16x16x32_bf16 v[20:23], v[16:19], v[202:205], v[8:11]
	v_mfma_f32_16x16x32_bf16 v[8:11], v[176:179], v[192:195], v[32:35]
	v_mfma_f32_16x16x32_bf16 v[16:19], v[180:183], v[202:205], v[8:11]
	s_setprio 0
	s_setprio 1
	v_mfma_f32_16x16x32_bf16 v[8:11], v[128:131], v[156:159], v[140:143]
	v_mfma_f32_16x16x32_bf16 v[40:43], v[214:217], v[136:139], v[8:11]
	v_mfma_f32_16x16x32_bf16 v[8:11], v[218:221], v[156:159], v[144:147]
	v_mfma_f32_16x16x32_bf16 v[44:47], v[222:225], v[136:139], v[8:11]
	v_mfma_f32_16x16x32_bf16 v[8:11], v[128:131], v[160:163], v[148:151]
	v_mfma_f32_16x16x32_bf16 v[36:39], v[214:217], v[164:167], v[8:11]
	v_mfma_f32_16x16x32_bf16 v[8:11], v[218:221], v[160:163], v[152:155]
	v_mfma_f32_16x16x32_bf16 v[32:35], v[222:225], v[164:167], v[8:11]
	v_mfma_f32_16x16x32_bf16 v[8:11], v[128:131], v[168:171], v[12:15]
	v_mfma_f32_16x16x32_bf16 v[12:15], v[218:221], v[168:171], v[172:175]
	v_mfma_f32_16x16x32_bf16 v[4:7], v[128:131], v[192:195], v[4:7]
	v_mfma_f32_16x16x32_bf16 v[0:3], v[218:221], v[192:195], v[0:3]
	v_mfma_f32_16x16x32_bf16 v[8:11], v[214:217], v[188:191], v[8:11]
	v_mfma_f32_16x16x32_bf16 v[12:15], v[222:225], v[188:191], v[12:15]
	v_mfma_f32_16x16x32_bf16 v[4:7], v[214:217], v[202:205], v[4:7]
	v_mfma_f32_16x16x32_bf16 v[0:3], v[222:225], v[202:205], v[0:3]
	s_setprio 0
	s_movk_i32 s4, 0x100
	v_cmp_gt_u32_e32 vcc, s4, v132
	s_barrier
	s_and_saveexec_b64 s[4:5], vcc
	s_cbranch_execz .LBB0_195
	s_barrier

.Lh1_loop:
	ds_read_b128 v[140:143], v129
	ds_read_b128 v[144:147], v129 offset:1024
	ds_read_b128 v[148:151], v129 offset:2048
	ds_read_b128 v[152:155], v129 offset:3072
	s_add_u32 s28, s60, s56
	s_addc_u32 s29, s61, s57
	ds_read_b128 v[156:159], v136
	ds_read_b128 v[160:163], v136 offset:1024
	ds_read_b128 v[164:167], v135
	ds_read_b128 v[168:171], v135 offset:1024
	ds_read_b128 v[172:175], v134
	ds_read_b128 v[176:179], v134 offset:1024
	ds_read_b128 v[180:183], v133
	ds_read_b128 v[184:187], v133 offset:1024
	s_add_i32 s40, s53, 0xc000
	s_mov_b32 m0, s40
	s_add_i32 s39, s53, 0xe000
	s_mov_b32 m0, s39
	s_nop 0
	s_waitcnt lgkmcnt(8)
	s_barrier
	s_waitcnt lgkmcnt(7)
	v_mfma_f32_16x16x32_bf16 v[124:127], v[140:143], v[156:159], v[124:127]
	v_mfma_f32_16x16x32_bf16 v[120:123], v[148:151], v[156:159], v[120:123]
	s_waitcnt lgkmcnt(5)
	v_mfma_f32_16x16x32_bf16 v[116:119], v[140:143], v[164:167], v[116:119]
	v_mfma_f32_16x16x32_bf16 v[112:115], v[148:151], v[164:167], v[112:115]
	s_waitcnt lgkmcnt(3)
	v_mfma_f32_16x16x32_bf16 v[108:111], v[140:143], v[172:175], v[108:111]
	v_mfma_f32_16x16x32_bf16 v[104:107], v[148:151], v[172:175], v[104:107]
	s_waitcnt lgkmcnt(1)
	v_mfma_f32_16x16x32_bf16 v[100:103], v[140:143], v[180:183], v[100:103]
	v_mfma_f32_16x16x32_bf16 v[96:99], v[148:151], v[180:183], v[96:99]
	v_mfma_f32_16x16x32_bf16 v[124:127], v[144:147], v[160:163], v[124:127]
	v_mfma_f32_16x16x32_bf16 v[120:123], v[152:155], v[160:163], v[120:123]
	v_mfma_f32_16x16x32_bf16 v[116:119], v[144:147], v[168:171], v[116:119]
	v_mfma_f32_16x16x32_bf16 v[112:115], v[152:155], v[168:171], v[112:115]
	v_mfma_f32_16x16x32_bf16 v[108:111], v[144:147], v[176:179], v[108:111]
	v_mfma_f32_16x16x32_bf16 v[104:107], v[152:155], v[176:179], v[104:107]
	s_waitcnt lgkmcnt(0)
	v_mfma_f32_16x16x32_bf16 v[100:103], v[144:147], v[184:187], v[100:103]
	v_mfma_f32_16x16x32_bf16 v[96:99], v[152:155], v[184:187], v[96:99]
	s_barrier
	s_add_u32 s62, s60, s36
	s_addc_u32 s63, s61, s37
	ds_read_b128 v[188:191], v139
	ds_read_b128 v[192:195], v139 offset:1024
	ds_read_b128 v[202:205], v139 offset:2048
	ds_read_b128 v[206:209], v139 offset:3072
	s_mov_b32 m0, s68
	s_add_u32 s98, s62, s46
	s_addc_u32 s99, s63, s47
	global_load_lds_dwordx4 v128, s[98:99]
	s_mov_b32 m0, s69
	s_nop 0
	global_load_lds_dwordx4 v130, s[98:99]
	s_barrier
	s_waitcnt lgkmcnt(3)
	v_mfma_f32_16x16x32_bf16 v[92:95], v[188:191], v[156:159], v[92:95]
	s_waitcnt lgkmcnt(1)
	v_mfma_f32_16x16x32_bf16 v[88:91], v[202:205], v[156:159], v[88:91]
	v_mfma_f32_16x16x32_bf16 v[84:87], v[188:191], v[164:167], v[84:87]
	v_mfma_f32_16x16x32_bf16 v[80:83], v[202:205], v[164:167], v[80:83]
	v_mfma_f32_16x16x32_bf16 v[76:79], v[188:191], v[172:175], v[76:79]
	v_mfma_f32_16x16x32_bf16 v[72:75], v[202:205], v[172:175], v[72:75]
	v_mfma_f32_16x16x32_bf16 v[68:71], v[188:191], v[180:183], v[68:71]
	v_mfma_f32_16x16x32_bf16 v[64:67], v[202:205], v[180:183], v[64:67]
	v_mfma_f32_16x16x32_bf16 v[92:95], v[192:195], v[160:163], v[92:95]
	s_waitcnt lgkmcnt(0)
	v_mfma_f32_16x16x32_bf16 v[88:91], v[206:209], v[160:163], v[88:91]
	v_mfma_f32_16x16x32_bf16 v[84:87], v[192:195], v[168:171], v[84:87]
	v_mfma_f32_16x16x32_bf16 v[80:83], v[206:209], v[168:171], v[80:83]
	v_mfma_f32_16x16x32_bf16 v[76:79], v[192:195], v[176:179], v[76:79]
	v_mfma_f32_16x16x32_bf16 v[72:75], v[206:209], v[176:179], v[72:75]
	v_mfma_f32_16x16x32_bf16 v[68:71], v[192:195], v[184:187], v[68:71]
	v_mfma_f32_16x16x32_bf16 v[64:67], v[206:209], v[184:187], v[64:67]
	s_barrier
	s_mov_b32 m0, s53
	s_add_u32 s98, s28, s48
	s_addc_u32 s99, s29, s49
	global_load_lds_dwordx4 v128, s[98:99]
	s_mov_b32 m0, s11
	s_nop 0
	global_load_lds_dwordx4 v130, s[98:99]
	s_waitcnt vmcnt(4)
	s_barrier
	s_mov_b32 m0, s9
	s_add_u32 s98, s62, s50
	s_addc_u32 s99, s63, s51
	global_load_lds_dwordx4 v128, s[98:99]
	s_mov_b32 m0, s70
	s_nop 0
	global_load_lds_dwordx4 v130, s[98:99]
	s_barrier
	ds_read_b128 v[140:143], v138
	ds_read_b128 v[144:147], v138 offset:1024
	ds_read_b128 v[148:151], v138 offset:2048
	ds_read_b128 v[152:155], v138 offset:3072
	ds_read_b128 v[156:159], v136 offset:32768
	ds_read_b128 v[160:163], v136 offset:33792
	ds_read_b128 v[164:167], v135 offset:32768
	ds_read_b128 v[168:171], v135 offset:33792
	ds_read_b128 v[172:175], v134 offset:32768
	ds_read_b128 v[176:179], v134 offset:33792
	ds_read_b128 v[180:183], v133 offset:32768
	ds_read_b128 v[184:187], v133 offset:33792
	s_mov_b32 m0, s71
	s_mov_b32 m0, s72
	s_nop 0
	s_waitcnt lgkmcnt(8)
	s_barrier
	s_waitcnt lgkmcnt(7)
	v_mfma_f32_16x16x32_bf16 v[124:127], v[140:143], v[156:159], v[124:127]
	v_mfma_f32_16x16x32_bf16 v[120:123], v[148:151], v[156:159], v[120:123]
	s_waitcnt lgkmcnt(5)
	v_mfma_f32_16x16x32_bf16 v[116:119], v[140:143], v[164:167], v[116:119]
	v_mfma_f32_16x16x32_bf16 v[112:115], v[148:151], v[164:167], v[112:115]
	s_waitcnt lgkmcnt(3)
	v_mfma_f32_16x16x32_bf16 v[108:111], v[140:143], v[172:175], v[108:111]
	v_mfma_f32_16x16x32_bf16 v[104:107], v[148:151], v[172:175], v[104:107]
	s_waitcnt lgkmcnt(1)
	v_mfma_f32_16x16x32_bf16 v[100:103], v[140:143], v[180:183], v[100:103]
	v_mfma_f32_16x16x32_bf16 v[96:99], v[148:151], v[180:183], v[96:99]
	v_mfma_f32_16x16x32_bf16 v[124:127], v[144:147], v[160:163], v[124:127]
	v_mfma_f32_16x16x32_bf16 v[120:123], v[152:155], v[160:163], v[120:123]
	v_mfma_f32_16x16x32_bf16 v[116:119], v[144:147], v[168:171], v[116:119]
	v_mfma_f32_16x16x32_bf16 v[112:115], v[152:155], v[168:171], v[112:115]
	v_mfma_f32_16x16x32_bf16 v[108:111], v[144:147], v[176:179], v[108:111]
	v_mfma_f32_16x16x32_bf16 v[104:107], v[152:155], v[176:179], v[104:107]
	s_waitcnt lgkmcnt(0)
	v_mfma_f32_16x16x32_bf16 v[100:103], v[144:147], v[184:187], v[100:103]
	v_mfma_f32_16x16x32_bf16 v[96:99], v[152:155], v[184:187], v[96:99]
	s_barrier
	ds_read_b128 v[188:191], v137
	ds_read_b128 v[192:195], v137 offset:1024
	ds_read_b128 v[202:205], v137 offset:2048
	ds_read_b128 v[206:209], v137 offset:3072
	s_mov_b32 m0, s66
	s_add_u32 s98, s62, s90
	s_addc_u32 s99, s63, s91
	global_load_lds_dwordx4 v128, s[98:99]
	s_mov_b32 m0, s64
	s_nop 0
	global_load_lds_dwordx4 v130, s[98:99]
	s_barrier
	s_waitcnt lgkmcnt(3)
	v_mfma_f32_16x16x32_bf16 v[92:95], v[188:191], v[156:159], v[92:95]
	s_waitcnt lgkmcnt(1)
	v_mfma_f32_16x16x32_bf16 v[88:91], v[202:205], v[156:159], v[88:91]
	v_mfma_f32_16x16x32_bf16 v[84:87], v[188:191], v[164:167], v[84:87]
	v_mfma_f32_16x16x32_bf16 v[80:83], v[202:205], v[164:167], v[80:83]
	v_mfma_f32_16x16x32_bf16 v[76:79], v[188:191], v[172:175], v[76:79]
	v_mfma_f32_16x16x32_bf16 v[72:75], v[202:205], v[172:175], v[72:75]
	v_mfma_f32_16x16x32_bf16 v[68:71], v[188:191], v[180:183], v[68:71]
	v_mfma_f32_16x16x32_bf16 v[64:67], v[202:205], v[180:183], v[64:67]
	v_mfma_f32_16x16x32_bf16 v[92:95], v[192:195], v[160:163], v[92:95]
	s_waitcnt lgkmcnt(0)
	v_mfma_f32_16x16x32_bf16 v[88:91], v[206:209], v[160:163], v[88:91]
	v_mfma_f32_16x16x32_bf16 v[84:87], v[192:195], v[168:171], v[84:87]
	v_mfma_f32_16x16x32_bf16 v[80:83], v[206:209], v[168:171], v[80:83]
	v_mfma_f32_16x16x32_bf16 v[76:79], v[192:195], v[176:179], v[76:79]
	v_mfma_f32_16x16x32_bf16 v[72:75], v[206:209], v[176:179], v[72:75]
	v_mfma_f32_16x16x32_bf16 v[68:71], v[192:195], v[184:187], v[68:71]
	v_mfma_f32_16x16x32_bf16 v[64:67], v[206:209], v[184:187], v[64:67]
	v_mov_b32_e32 v210, v130
	s_barrier
	v_mov_b32_e32 v211, v197
	s_mov_b32 m0, s65
	s_add_u32 s98, s28, s92
	s_addc_u32 s99, s29, s93
	global_load_lds_dwordx4 v128, s[98:99]
	s_mov_b32 m0, s67
	s_nop 0
	global_load_lds_dwordx4 v130, s[98:99]
	s_waitcnt vmcnt(4)
	s_barrier
	v_mov_b32_e32 v196, v128
	s_mov_b32 m0, s33
	s_add_u32 s98, s62, s96
	s_addc_u32 s99, s63, s97
	global_load_lds_dwordx4 v128, s[98:99]
	s_mov_b32 m0, s73
	s_nop 0
	global_load_lds_dwordx4 v130, s[98:99]
	s_barrier
	s_add_i32 s38, s38, 2
	s_add_u32 s60, s60, 0x100
	s_addc_u32 s61, s61, 0
	s_cmp_lt_u32 s38, 28
	s_cbranch_scc1 .Lh1_loop
	ds_read_b128 v[140:143], v129
	ds_read_b128 v[144:147], v129 offset:1024
	ds_read_b128 v[148:151], v129 offset:2048
	ds_read_b128 v[152:155], v129 offset:3072
	ds_read_b128 v[156:159], v136
	ds_read_b128 v[160:163], v136 offset:1024
	ds_read_b128 v[164:167], v135
	ds_read_b128 v[168:171], v135 offset:1024
	ds_read_b128 v[172:175], v134
	ds_read_b128 v[176:179], v134 offset:1024
	ds_read_b128 v[180:183], v133
	ds_read_b128 v[184:187], v133 offset:1024
	v_mov_b32_e32 v129, v197
	v_lshl_add_u64 v[128:129], s[58:59], 0, v[128:129]
	s_mov_b64 s[28:29], 0xf80
	s_mov_b32 m0, s40
	v_lshl_add_u64 v[128:129], v[128:129], 0, s[28:29]
	v_mov_b32_e32 v131, v197
	v_lshl_add_u64 v[128:129], s[58:59], 0, v[130:131]
	v_lshl_add_u64 v[128:129], v[128:129], 0, s[28:29]
	s_mov_b32 m0, s39
	s_nop 0
	s_barrier
	s_waitcnt lgkmcnt(0)
	s_setprio 1
	s_waitcnt lgkmcnt(0)
	v_mfma_f32_16x16x32_bf16 v[124:127], v[140:143], v[156:159], v[124:127]
	v_mfma_f32_16x16x32_bf16 v[120:123], v[148:151], v[156:159], v[120:123]
	v_mfma_f32_16x16x32_bf16 v[116:119], v[140:143], v[164:167], v[116:119]
	v_mfma_f32_16x16x32_bf16 v[112:115], v[148:151], v[164:167], v[112:115]
	v_mfma_f32_16x16x32_bf16 v[108:111], v[140:143], v[172:175], v[108:111]
	v_mfma_f32_16x16x32_bf16 v[100:103], v[140:143], v[180:183], v[100:103]
	v_mfma_f32_16x16x32_bf16 v[96:99], v[148:151], v[180:183], v[96:99]
	v_mfma_f32_16x16x32_bf16 v[124:127], v[144:147], v[160:163], v[124:127]
	v_mfma_f32_16x16x32_bf16 v[120:123], v[152:155], v[160:163], v[120:123]
	v_mfma_f32_16x16x32_bf16 v[116:119], v[144:147], v[168:171], v[116:119]
	v_mfma_f32_16x16x32_bf16 v[112:115], v[152:155], v[168:171], v[112:115]
	v_mfma_f32_16x16x32_bf16 v[108:111], v[144:147], v[176:179], v[108:111]
	v_mfma_f32_16x16x32_bf16 v[104:107], v[148:151], v[172:175], v[104:107]
	v_mfma_f32_16x16x32_bf16 v[100:103], v[144:147], v[184:187], v[100:103]
	v_mfma_f32_16x16x32_bf16 v[96:99], v[152:155], v[184:187], v[96:99]
	v_mfma_f32_16x16x32_bf16 v[128:131], v[152:155], v[176:179], v[104:107]
	s_setprio 0
	s_barrier
	s_nop 2
	ds_read_b128 v[104:107], v139
	ds_read_b128 v[188:191], v139 offset:1024
	ds_read_b128 v[192:195], v139 offset:2048
	ds_read_b128 v[202:205], v139 offset:3072
	s_barrier
	s_waitcnt lgkmcnt(0)
	s_setprio 1
	s_waitcnt lgkmcnt(0)
	v_mfma_f32_16x16x32_bf16 v[92:95], v[104:107], v[156:159], v[92:95]
	v_mfma_f32_16x16x32_bf16 v[84:87], v[104:107], v[164:167], v[84:87]
	v_mfma_f32_16x16x32_bf16 v[76:79], v[104:107], v[172:175], v[76:79]
	v_mfma_f32_16x16x32_bf16 v[68:71], v[104:107], v[180:183], v[68:71]
	v_mfma_f32_16x16x32_bf16 v[64:67], v[192:195], v[180:183], v[64:67]
	v_mfma_f32_16x16x32_bf16 v[92:95], v[188:191], v[160:163], v[92:95]
	v_mfma_f32_16x16x32_bf16 v[88:91], v[192:195], v[156:159], v[88:91]
	v_mfma_f32_16x16x32_bf16 v[84:87], v[188:191], v[168:171], v[84:87]
	v_mfma_f32_16x16x32_bf16 v[80:83], v[192:195], v[164:167], v[80:83]
	v_mfma_f32_16x16x32_bf16 v[76:79], v[188:191], v[176:179], v[76:79]
	v_mfma_f32_16x16x32_bf16 v[72:75], v[192:195], v[172:175], v[72:75]
	v_mfma_f32_16x16x32_bf16 v[68:71], v[188:191], v[184:187], v[68:71]
	v_mfma_f32_16x16x32_bf16 v[64:67], v[202:205], v[184:187], v[64:67]
	v_mfma_f32_16x16x32_bf16 v[156:159], v[202:205], v[160:163], v[88:91]
	v_mfma_f32_16x16x32_bf16 v[160:163], v[202:205], v[168:171], v[80:83]
	v_mfma_f32_16x16x32_bf16 v[164:167], v[202:205], v[176:179], v[72:75]
	s_setprio 0
	s_barrier
	s_nop 0
	s_waitcnt vmcnt(2)
	s_barrier
	s_waitcnt lgkmcnt(0)
	s_setprio 1
	s_waitcnt lgkmcnt(0)
	s_setprio 0
	s_setprio 1
	s_setprio 0
	s_barrier
	ds_read_b128 v[16:19], v138
	ds_read_b128 v[180:183], v138 offset:1024
	ds_read_b128 v[184:187], v138 offset:2048
	ds_read_b128 v[188:191], v138 offset:3072
	ds_read_b128 v[0:3], v136 offset:32768
	ds_read_b128 v[4:7], v136 offset:33792
	ds_read_b128 v[8:11], v135 offset:32768
	ds_read_b128 v[12:15], v135 offset:33792
	ds_read_b128 v[44:47], v134 offset:32768
	ds_read_b128 v[192:195], v134 offset:33792
	ds_read_b128 v[202:205], v133 offset:32768
	ds_read_b128 v[218:221], v133 offset:33792
	s_waitcnt vmcnt(0)
	s_barrier
	s_waitcnt lgkmcnt(0)
	s_setprio 1
	s_waitcnt lgkmcnt(0)
	v_mfma_f32_16x16x32_bf16 v[28:31], v[16:19], v[0:3], v[124:127]
	v_mfma_f32_16x16x32_bf16 v[52:55], v[180:183], v[4:7], v[28:31]
	v_mfma_f32_16x16x32_bf16 v[28:31], v[184:187], v[0:3], v[120:123]
	v_mfma_f32_16x16x32_bf16 v[104:107], v[188:191], v[4:7], v[28:31]
	v_mfma_f32_16x16x32_bf16 v[28:31], v[16:19], v[8:11], v[116:119]
	v_mfma_f32_16x16x32_bf16 v[72:75], v[180:183], v[12:15], v[28:31]
	v_mfma_f32_16x16x32_bf16 v[28:31], v[184:187], v[8:11], v[112:115]
	v_mfma_f32_16x16x32_bf16 v[116:119], v[188:191], v[12:15], v[28:31]
	v_mfma_f32_16x16x32_bf16 v[28:31], v[16:19], v[44:47], v[108:111]
	v_mfma_f32_16x16x32_bf16 v[80:83], v[180:183], v[192:195], v[28:31]
	v_mfma_f32_16x16x32_bf16 v[28:31], v[184:187], v[44:47], v[128:131]
	v_mfma_f32_16x16x32_bf16 v[108:111], v[188:191], v[192:195], v[28:31]
	v_mfma_f32_16x16x32_bf16 v[28:31], v[16:19], v[202:205], v[100:103]
	v_mfma_f32_16x16x32_bf16 v[88:91], v[180:183], v[218:221], v[28:31]
	v_mfma_f32_16x16x32_bf16 v[28:31], v[184:187], v[202:205], v[96:99]
	v_mfma_f32_16x16x32_bf16 v[96:99], v[188:191], v[218:221], v[28:31]
	s_setprio 0
	s_barrier
	ds_read_b128 v[128:131], v137
	ds_read_b128 v[222:225], v137 offset:1024
	ds_read_b128 v[228:231], v137 offset:2048
	ds_read_b128 v[232:235], v137 offset:3072
	s_waitcnt vmcnt(0)
	s_barrier
	s_waitcnt lgkmcnt(0)
	s_setprio 1
	s_waitcnt lgkmcnt(0)
	v_mfma_f32_16x16x32_bf16 v[28:31], v[128:131], v[0:3], v[92:95]
	v_mfma_f32_16x16x32_bf16 v[0:3], v[228:231], v[0:3], v[156:159]
	v_mfma_f32_16x16x32_bf16 v[28:31], v[222:225], v[4:7], v[28:31]
	v_mfma_f32_16x16x32_bf16 v[0:3], v[232:235], v[4:7], v[0:3]
	v_mfma_f32_16x16x32_bf16 v[4:7], v[128:131], v[8:11], v[84:87]
	v_mfma_f32_16x16x32_bf16 v[36:39], v[222:225], v[12:15], v[4:7]
	v_mfma_f32_16x16x32_bf16 v[4:7], v[228:231], v[8:11], v[160:163]
	v_mfma_f32_16x16x32_bf16 v[4:7], v[232:235], v[12:15], v[4:7]
	v_mfma_f32_16x16x32_bf16 v[8:11], v[128:131], v[44:47], v[76:79]
	v_mfma_f32_16x16x32_bf16 v[12:15], v[128:131], v[202:205], v[68:71]
	v_mfma_f32_16x16x32_bf16 v[40:43], v[222:225], v[192:195], v[8:11]
	v_mfma_f32_16x16x32_bf16 v[8:11], v[228:231], v[44:47], v[164:167]
	v_mfma_f32_16x16x32_bf16 v[44:47], v[222:225], v[218:221], v[12:15]
	v_mfma_f32_16x16x32_bf16 v[12:15], v[228:231], v[202:205], v[64:67]
	v_mfma_f32_16x16x32_bf16 v[8:11], v[232:235], v[192:195], v[8:11]
	v_mfma_f32_16x16x32_bf16 v[12:15], v[232:235], v[218:221], v[12:15]
	s_setprio 0
	s_barrier
	s_barrier
	s_waitcnt lgkmcnt(0)
	s_setprio 1
	s_waitcnt lgkmcnt(0)
	s_setprio 0
	s_setprio 1
	s_setprio 0
	s_movk_i32 s9, 0x100
	v_cmp_gt_u32_e32 vcc, s9, v132
	s_barrier
	s_and_saveexec_b64 s[28:29], vcc
	s_cbranch_execz .Lh1_epi
	s_barrier

.LBB0_255:
	ds_read_b128 v[140:143], v129
	ds_read_b128 v[144:147], v129 offset:1024
	ds_read_b128 v[148:151], v129 offset:2048
	ds_read_b128 v[152:155], v129 offset:3072
	s_add_u32 s28, s60, s56
	s_addc_u32 s29, s61, s57
	ds_read_b128 v[156:159], v136
	ds_read_b128 v[160:163], v136 offset:1024
	ds_read_b128 v[164:167], v135
	ds_read_b128 v[168:171], v135 offset:1024
	ds_read_b128 v[172:175], v134
	ds_read_b128 v[176:179], v134 offset:1024
	ds_read_b128 v[180:183], v133
	ds_read_b128 v[184:187], v133 offset:1024
	s_add_i32 s40, s53, 0xc000
	s_mov_b32 m0, s40
	s_add_i32 s39, s53, 0xe000
	s_add_u32 s98, s28, s44
	s_addc_u32 s99, s29, s45
	global_load_lds_dwordx4 v128, s[98:99]
	s_mov_b32 m0, s39
	s_nop 0
	global_load_lds_dwordx4 v130, s[98:99]
	s_waitcnt lgkmcnt(8)
	s_barrier
	s_waitcnt lgkmcnt(7)
	v_mfma_f32_16x16x32_bf16 v[124:127], v[140:143], v[156:159], v[124:127]
	v_mfma_f32_16x16x32_bf16 v[120:123], v[148:151], v[156:159], v[120:123]
	s_waitcnt lgkmcnt(5)
	v_mfma_f32_16x16x32_bf16 v[116:119], v[140:143], v[164:167], v[116:119]
	v_mfma_f32_16x16x32_bf16 v[112:115], v[148:151], v[164:167], v[112:115]
	s_waitcnt lgkmcnt(3)
	v_mfma_f32_16x16x32_bf16 v[108:111], v[140:143], v[172:175], v[108:111]
	v_mfma_f32_16x16x32_bf16 v[104:107], v[148:151], v[172:175], v[104:107]
	s_waitcnt lgkmcnt(1)
	v_mfma_f32_16x16x32_bf16 v[100:103], v[140:143], v[180:183], v[100:103]
	v_mfma_f32_16x16x32_bf16 v[96:99], v[148:151], v[180:183], v[96:99]
	v_mfma_f32_16x16x32_bf16 v[124:127], v[144:147], v[160:163], v[124:127]
	v_mfma_f32_16x16x32_bf16 v[120:123], v[152:155], v[160:163], v[120:123]
	v_mfma_f32_16x16x32_bf16 v[116:119], v[144:147], v[168:171], v[116:119]
	v_mfma_f32_16x16x32_bf16 v[112:115], v[152:155], v[168:171], v[112:115]
	v_mfma_f32_16x16x32_bf16 v[108:111], v[144:147], v[176:179], v[108:111]
	v_mfma_f32_16x16x32_bf16 v[104:107], v[152:155], v[176:179], v[104:107]
	s_waitcnt lgkmcnt(0)
	v_mfma_f32_16x16x32_bf16 v[100:103], v[144:147], v[184:187], v[100:103]
	v_mfma_f32_16x16x32_bf16 v[96:99], v[152:155], v[184:187], v[96:99]
	s_barrier
	s_add_u32 s62, s60, s36
	s_addc_u32 s63, s61, s37
	ds_read_b128 v[188:191], v139
	ds_read_b128 v[192:195], v139 offset:1024
	ds_read_b128 v[202:205], v139 offset:2048
	ds_read_b128 v[206:209], v139 offset:3072
	s_mov_b32 m0, s68
	s_add_u32 s98, s62, s46
	s_addc_u32 s99, s63, s47
	global_load_lds_dwordx4 v128, s[98:99]
	s_mov_b32 m0, s69
	s_nop 0
	global_load_lds_dwordx4 v130, s[98:99]
	s_barrier
	s_waitcnt lgkmcnt(3)
	v_mfma_f32_16x16x32_bf16 v[92:95], v[188:191], v[156:159], v[92:95]
	s_waitcnt lgkmcnt(1)
	v_mfma_f32_16x16x32_bf16 v[88:91], v[202:205], v[156:159], v[88:91]
	v_mfma_f32_16x16x32_bf16 v[84:87], v[188:191], v[164:167], v[84:87]
	v_mfma_f32_16x16x32_bf16 v[80:83], v[202:205], v[164:167], v[80:83]
	v_mfma_f32_16x16x32_bf16 v[76:79], v[188:191], v[172:175], v[76:79]
	v_mfma_f32_16x16x32_bf16 v[72:75], v[202:205], v[172:175], v[72:75]
	v_mfma_f32_16x16x32_bf16 v[68:71], v[188:191], v[180:183], v[68:71]
	v_mfma_f32_16x16x32_bf16 v[64:67], v[202:205], v[180:183], v[64:67]
	v_mfma_f32_16x16x32_bf16 v[92:95], v[192:195], v[160:163], v[92:95]
	s_waitcnt lgkmcnt(0)
	v_mfma_f32_16x16x32_bf16 v[88:91], v[206:209], v[160:163], v[88:91]
	v_mfma_f32_16x16x32_bf16 v[84:87], v[192:195], v[168:171], v[84:87]
	v_mfma_f32_16x16x32_bf16 v[80:83], v[206:209], v[168:171], v[80:83]
	v_mfma_f32_16x16x32_bf16 v[76:79], v[192:195], v[176:179], v[76:79]
	v_mfma_f32_16x16x32_bf16 v[72:75], v[206:209], v[176:179], v[72:75]
	v_mfma_f32_16x16x32_bf16 v[68:71], v[192:195], v[184:187], v[68:71]
	v_mfma_f32_16x16x32_bf16 v[64:67], v[206:209], v[184:187], v[64:67]
	s_barrier
	ds_read_b128 v[156:159], v136 offset:16384
	ds_read_b128 v[160:163], v136 offset:17408
	ds_read_b128 v[164:167], v135 offset:16384
	ds_read_b128 v[168:171], v135 offset:17408
	ds_read_b128 v[172:175], v134 offset:16384
	ds_read_b128 v[176:179], v134 offset:17408
	ds_read_b128 v[180:183], v133 offset:16384
	ds_read_b128 v[184:187], v133 offset:17408
	s_mov_b32 m0, s53
	s_add_u32 s98, s28, s48
	s_addc_u32 s99, s29, s49
	global_load_lds_dwordx4 v128, s[98:99]
	s_mov_b32 m0, s11
	s_nop 0
	global_load_lds_dwordx4 v130, s[98:99]
	s_barrier
	s_waitcnt lgkmcnt(7)
	v_mfma_f32_16x16x32_bf16 v[60:63], v[140:143], v[156:159], v[60:63]
	v_mfma_f32_16x16x32_bf16 v[56:59], v[148:151], v[156:159], v[56:59]
	s_waitcnt lgkmcnt(5)
	v_mfma_f32_16x16x32_bf16 v[52:55], v[140:143], v[164:167], v[52:55]
	v_mfma_f32_16x16x32_bf16 v[48:51], v[148:151], v[164:167], v[48:51]
	s_waitcnt lgkmcnt(3)
	v_mfma_f32_16x16x32_bf16 v[44:47], v[140:143], v[172:175], v[44:47]
	v_mfma_f32_16x16x32_bf16 v[40:43], v[148:151], v[172:175], v[40:43]
	s_waitcnt lgkmcnt(1)
	v_mfma_f32_16x16x32_bf16 v[36:39], v[140:143], v[180:183], v[36:39]
	v_mfma_f32_16x16x32_bf16 v[32:35], v[148:151], v[180:183], v[32:35]
	v_mfma_f32_16x16x32_bf16 v[60:63], v[144:147], v[160:163], v[60:63]
	v_mfma_f32_16x16x32_bf16 v[56:59], v[152:155], v[160:163], v[56:59]
	v_mfma_f32_16x16x32_bf16 v[52:55], v[144:147], v[168:171], v[52:55]
	v_mfma_f32_16x16x32_bf16 v[48:51], v[152:155], v[168:171], v[48:51]
	v_mfma_f32_16x16x32_bf16 v[44:47], v[144:147], v[176:179], v[44:47]
	v_mfma_f32_16x16x32_bf16 v[40:43], v[152:155], v[176:179], v[40:43]
	s_waitcnt lgkmcnt(0)
	v_mfma_f32_16x16x32_bf16 v[36:39], v[144:147], v[184:187], v[36:39]
	v_mfma_f32_16x16x32_bf16 v[32:35], v[152:155], v[184:187], v[32:35]
	s_barrier
	s_mov_b32 m0, s9
	s_add_u32 s98, s62, s50
	s_addc_u32 s99, s63, s51
	global_load_lds_dwordx4 v128, s[98:99]
	s_mov_b32 m0, s70
	s_nop 0
	global_load_lds_dwordx4 v130, s[98:99]
	s_waitcnt vmcnt(6)
	s_barrier
	v_mfma_f32_16x16x32_bf16 v[28:31], v[188:191], v[156:159], v[28:31]
	v_mfma_f32_16x16x32_bf16 v[24:27], v[202:205], v[156:159], v[24:27]
	v_mfma_f32_16x16x32_bf16 v[20:23], v[188:191], v[164:167], v[20:23]
	v_mfma_f32_16x16x32_bf16 v[16:19], v[202:205], v[164:167], v[16:19]
	v_mfma_f32_16x16x32_bf16 v[12:15], v[188:191], v[172:175], v[12:15]
	v_mfma_f32_16x16x32_bf16 v[8:11], v[202:205], v[172:175], v[8:11]
	v_mfma_f32_16x16x32_bf16 v[4:7], v[188:191], v[180:183], v[4:7]
	v_mfma_f32_16x16x32_bf16 v[0:3], v[202:205], v[180:183], v[0:3]
	v_mfma_f32_16x16x32_bf16 v[28:31], v[192:195], v[160:163], v[28:31]
	v_mfma_f32_16x16x32_bf16 v[24:27], v[206:209], v[160:163], v[24:27]
	v_mfma_f32_16x16x32_bf16 v[20:23], v[192:195], v[168:171], v[20:23]
	v_mfma_f32_16x16x32_bf16 v[16:19], v[206:209], v[168:171], v[16:19]
	v_mfma_f32_16x16x32_bf16 v[12:15], v[192:195], v[176:179], v[12:15]
	v_mfma_f32_16x16x32_bf16 v[8:11], v[206:209], v[176:179], v[8:11]
	v_mfma_f32_16x16x32_bf16 v[4:7], v[192:195], v[184:187], v[4:7]
	v_mfma_f32_16x16x32_bf16 v[0:3], v[206:209], v[184:187], v[0:3]
	s_barrier
	ds_read_b128 v[140:143], v138
	ds_read_b128 v[144:147], v138 offset:1024
	ds_read_b128 v[148:151], v138 offset:2048
	ds_read_b128 v[152:155], v138 offset:3072
	ds_read_b128 v[156:159], v136 offset:32768
	ds_read_b128 v[160:163], v136 offset:33792
	ds_read_b128 v[164:167], v135 offset:32768
	ds_read_b128 v[168:171], v135 offset:33792
	ds_read_b128 v[172:175], v134 offset:32768
	ds_read_b128 v[176:179], v134 offset:33792
	ds_read_b128 v[180:183], v133 offset:32768
	ds_read_b128 v[184:187], v133 offset:33792
	s_mov_b32 m0, s71
	s_add_u32 s98, s28, s74
	s_addc_u32 s99, s29, s75
	global_load_lds_dwordx4 v128, s[98:99]
	s_mov_b32 m0, s72
	s_nop 0
	global_load_lds_dwordx4 v130, s[98:99]
	s_waitcnt lgkmcnt(8)
	s_barrier
	s_waitcnt lgkmcnt(7)
	v_mfma_f32_16x16x32_bf16 v[124:127], v[140:143], v[156:159], v[124:127]
	v_mfma_f32_16x16x32_bf16 v[120:123], v[148:151], v[156:159], v[120:123]
	s_waitcnt lgkmcnt(5)
	v_mfma_f32_16x16x32_bf16 v[116:119], v[140:143], v[164:167], v[116:119]
	v_mfma_f32_16x16x32_bf16 v[112:115], v[148:151], v[164:167], v[112:115]
	s_waitcnt lgkmcnt(3)
	v_mfma_f32_16x16x32_bf16 v[108:111], v[140:143], v[172:175], v[108:111]
	v_mfma_f32_16x16x32_bf16 v[104:107], v[148:151], v[172:175], v[104:107]
	s_waitcnt lgkmcnt(1)
	v_mfma_f32_16x16x32_bf16 v[100:103], v[140:143], v[180:183], v[100:103]
	v_mfma_f32_16x16x32_bf16 v[96:99], v[148:151], v[180:183], v[96:99]
	v_mfma_f32_16x16x32_bf16 v[124:127], v[144:147], v[160:163], v[124:127]
	v_mfma_f32_16x16x32_bf16 v[120:123], v[152:155], v[160:163], v[120:123]
	v_mfma_f32_16x16x32_bf16 v[116:119], v[144:147], v[168:171], v[116:119]
	v_mfma_f32_16x16x32_bf16 v[112:115], v[152:155], v[168:171], v[112:115]
	v_mfma_f32_16x16x32_bf16 v[108:111], v[144:147], v[176:179], v[108:111]
	v_mfma_f32_16x16x32_bf16 v[104:107], v[152:155], v[176:179], v[104:107]
	s_waitcnt lgkmcnt(0)
	v_mfma_f32_16x16x32_bf16 v[100:103], v[144:147], v[184:187], v[100:103]
	v_mfma_f32_16x16x32_bf16 v[96:99], v[152:155], v[184:187], v[96:99]
	s_barrier
	ds_read_b128 v[188:191], v137
	ds_read_b128 v[192:195], v137 offset:1024
	ds_read_b128 v[202:205], v137 offset:2048
	ds_read_b128 v[206:209], v137 offset:3072
	s_mov_b32 m0, s66
	s_add_u32 s98, s62, s90
	s_addc_u32 s99, s63, s91
	global_load_lds_dwordx4 v128, s[98:99]
	s_mov_b32 m0, s64
	s_nop 0
	global_load_lds_dwordx4 v130, s[98:99]
	s_barrier
	s_waitcnt lgkmcnt(3)
	v_mfma_f32_16x16x32_bf16 v[92:95], v[188:191], v[156:159], v[92:95]
	s_waitcnt lgkmcnt(1)
	v_mfma_f32_16x16x32_bf16 v[88:91], v[202:205], v[156:159], v[88:91]
	v_mfma_f32_16x16x32_bf16 v[84:87], v[188:191], v[164:167], v[84:87]
	v_mfma_f32_16x16x32_bf16 v[80:83], v[202:205], v[164:167], v[80:83]
	v_mfma_f32_16x16x32_bf16 v[76:79], v[188:191], v[172:175], v[76:79]
	v_mfma_f32_16x16x32_bf16 v[72:75], v[202:205], v[172:175], v[72:75]
	v_mfma_f32_16x16x32_bf16 v[68:71], v[188:191], v[180:183], v[68:71]
	v_mfma_f32_16x16x32_bf16 v[64:67], v[202:205], v[180:183], v[64:67]
	v_mfma_f32_16x16x32_bf16 v[92:95], v[192:195], v[160:163], v[92:95]
	s_waitcnt lgkmcnt(0)
	v_mfma_f32_16x16x32_bf16 v[88:91], v[206:209], v[160:163], v[88:91]
	v_mfma_f32_16x16x32_bf16 v[84:87], v[192:195], v[168:171], v[84:87]
	v_mfma_f32_16x16x32_bf16 v[80:83], v[206:209], v[168:171], v[80:83]
	v_mfma_f32_16x16x32_bf16 v[76:79], v[192:195], v[176:179], v[76:79]
	v_mfma_f32_16x16x32_bf16 v[72:75], v[206:209], v[176:179], v[72:75]
	v_mfma_f32_16x16x32_bf16 v[68:71], v[192:195], v[184:187], v[68:71]
	v_mfma_f32_16x16x32_bf16 v[64:67], v[206:209], v[184:187], v[64:67]
	v_mov_b32_e32 v210, v130
	s_barrier
	ds_read_b128 v[156:159], v136 offset:49152
	ds_read_b128 v[160:163], v136 offset:50176
	ds_read_b128 v[164:167], v135 offset:49152
	ds_read_b128 v[168:171], v135 offset:50176
	ds_read_b128 v[172:175], v134 offset:49152
	ds_read_b128 v[176:179], v134 offset:50176
	ds_read_b128 v[180:183], v133 offset:49152
	ds_read_b128 v[184:187], v133 offset:50176
	v_mov_b32_e32 v211, v197
	s_mov_b32 m0, s65
	s_add_u32 s98, s28, s92
	s_addc_u32 s99, s29, s93
	global_load_lds_dwordx4 v128, s[98:99]
	s_mov_b32 m0, s67
	s_nop 0
	global_load_lds_dwordx4 v130, s[98:99]
	s_barrier
	s_waitcnt lgkmcnt(7)
	v_mfma_f32_16x16x32_bf16 v[60:63], v[140:143], v[156:159], v[60:63]
	v_mfma_f32_16x16x32_bf16 v[56:59], v[148:151], v[156:159], v[56:59]
	s_waitcnt lgkmcnt(5)
	v_mfma_f32_16x16x32_bf16 v[52:55], v[140:143], v[164:167], v[52:55]
	v_mfma_f32_16x16x32_bf16 v[48:51], v[148:151], v[164:167], v[48:51]
	s_waitcnt lgkmcnt(3)
	v_mfma_f32_16x16x32_bf16 v[44:47], v[140:143], v[172:175], v[44:47]
	v_mfma_f32_16x16x32_bf16 v[40:43], v[148:151], v[172:175], v[40:43]
	s_waitcnt lgkmcnt(1)
	v_mfma_f32_16x16x32_bf16 v[36:39], v[140:143], v[180:183], v[36:39]
	v_mfma_f32_16x16x32_bf16 v[32:35], v[148:151], v[180:183], v[32:35]
	v_mfma_f32_16x16x32_bf16 v[60:63], v[144:147], v[160:163], v[60:63]
	v_mfma_f32_16x16x32_bf16 v[56:59], v[152:155], v[160:163], v[56:59]
	v_mfma_f32_16x16x32_bf16 v[52:55], v[144:147], v[168:171], v[52:55]
	v_mfma_f32_16x16x32_bf16 v[48:51], v[152:155], v[168:171], v[48:51]
	v_mfma_f32_16x16x32_bf16 v[44:47], v[144:147], v[176:179], v[44:47]
	v_mfma_f32_16x16x32_bf16 v[40:43], v[152:155], v[176:179], v[40:43]
	s_waitcnt lgkmcnt(0)
	v_mfma_f32_16x16x32_bf16 v[36:39], v[144:147], v[184:187], v[36:39]
	v_mfma_f32_16x16x32_bf16 v[32:35], v[152:155], v[184:187], v[32:35]
	s_barrier
	v_mov_b32_e32 v196, v128
	s_mov_b32 m0, s33
	s_add_u32 s98, s62, s96
	s_addc_u32 s99, s63, s97
	global_load_lds_dwordx4 v128, s[98:99]
	s_mov_b32 m0, s73
	s_nop 0
	global_load_lds_dwordx4 v130, s[98:99]
	s_waitcnt vmcnt(6)
	s_barrier
	v_mfma_f32_16x16x32_bf16 v[28:31], v[188:191], v[156:159], v[28:31]
	v_mfma_f32_16x16x32_bf16 v[24:27], v[202:205], v[156:159], v[24:27]
	v_mfma_f32_16x16x32_bf16 v[20:23], v[188:191], v[164:167], v[20:23]
	v_mfma_f32_16x16x32_bf16 v[16:19], v[202:205], v[164:167], v[16:19]
	v_mfma_f32_16x16x32_bf16 v[12:15], v[188:191], v[172:175], v[12:15]
	v_mfma_f32_16x16x32_bf16 v[8:11], v[202:205], v[172:175], v[8:11]
	v_mfma_f32_16x16x32_bf16 v[4:7], v[188:191], v[180:183], v[4:7]
	v_mfma_f32_16x16x32_bf16 v[0:3], v[202:205], v[180:183], v[0:3]
	v_mfma_f32_16x16x32_bf16 v[28:31], v[192:195], v[160:163], v[28:31]
	v_mfma_f32_16x16x32_bf16 v[24:27], v[206:209], v[160:163], v[24:27]
	v_mfma_f32_16x16x32_bf16 v[20:23], v[192:195], v[168:171], v[20:23]
	v_mfma_f32_16x16x32_bf16 v[16:19], v[206:209], v[168:171], v[16:19]
	v_mfma_f32_16x16x32_bf16 v[12:15], v[192:195], v[176:179], v[12:15]
	v_mfma_f32_16x16x32_bf16 v[8:11], v[206:209], v[176:179], v[8:11]
	v_mfma_f32_16x16x32_bf16 v[4:7], v[192:195], v[184:187], v[4:7]
	v_mfma_f32_16x16x32_bf16 v[0:3], v[206:209], v[184:187], v[0:3]
	s_add_i32 s38, s38, 2
	s_add_u32 s60, s60, 0x100
	s_addc_u32 s61, s61, 0
	s_cmp_lt_u32 s38, 28
	s_barrier
	s_cbranch_scc1 .LBB0_255
	ds_read_b128 v[140:143], v129
	ds_read_b128 v[144:147], v129 offset:1024
	ds_read_b128 v[148:151], v129 offset:2048
	ds_read_b128 v[152:155], v129 offset:3072
	ds_read_b128 v[156:159], v136
	ds_read_b128 v[160:163], v136 offset:1024
	ds_read_b128 v[164:167], v135
	ds_read_b128 v[168:171], v135 offset:1024
	ds_read_b128 v[172:175], v134
	ds_read_b128 v[176:179], v134 offset:1024
	ds_read_b128 v[180:183], v133
	ds_read_b128 v[184:187], v133 offset:1024
	v_mov_b32_e32 v129, v197
	v_lshl_add_u64 v[128:129], s[58:59], 0, v[128:129]
	s_mov_b64 s[28:29], 0xf80
	s_mov_b32 m0, s40
	v_lshl_add_u64 v[128:129], v[128:129], 0, s[28:29]
	v_mov_b32_e32 v131, v197
	global_load_lds_dwordx4 v[128:129], off
	v_lshl_add_u64 v[128:129], s[58:59], 0, v[130:131]
	v_lshl_add_u64 v[128:129], v[128:129], 0, s[28:29]
	s_mov_b32 m0, s39
	s_nop 0
	global_load_lds_dwordx4 v[128:129], off
	s_barrier
	s_waitcnt lgkmcnt(0)
	s_setprio 1
	s_waitcnt lgkmcnt(0)
	v_mfma_f32_16x16x32_bf16 v[124:127], v[140:143], v[156:159], v[124:127]
	v_mfma_f32_16x16x32_bf16 v[120:123], v[148:151], v[156:159], v[120:123]
	v_mfma_f32_16x16x32_bf16 v[116:119], v[140:143], v[164:167], v[116:119]
	v_mfma_f32_16x16x32_bf16 v[112:115], v[148:151], v[164:167], v[112:115]
	v_mfma_f32_16x16x32_bf16 v[108:111], v[140:143], v[172:175], v[108:111]
	v_mfma_f32_16x16x32_bf16 v[100:103], v[140:143], v[180:183], v[100:103]
	v_mfma_f32_16x16x32_bf16 v[96:99], v[148:151], v[180:183], v[96:99]
	v_mfma_f32_16x16x32_bf16 v[124:127], v[144:147], v[160:163], v[124:127]
	v_mfma_f32_16x16x32_bf16 v[120:123], v[152:155], v[160:163], v[120:123]
	v_mfma_f32_16x16x32_bf16 v[116:119], v[144:147], v[168:171], v[116:119]
	v_mfma_f32_16x16x32_bf16 v[112:115], v[152:155], v[168:171], v[112:115]
	v_mfma_f32_16x16x32_bf16 v[108:111], v[144:147], v[176:179], v[108:111]
	v_mfma_f32_16x16x32_bf16 v[104:107], v[148:151], v[172:175], v[104:107]
	v_mfma_f32_16x16x32_bf16 v[100:103], v[144:147], v[184:187], v[100:103]
	v_mfma_f32_16x16x32_bf16 v[96:99], v[152:155], v[184:187], v[96:99]
	v_mfma_f32_16x16x32_bf16 v[128:131], v[152:155], v[176:179], v[104:107]
	s_setprio 0
	s_barrier
	s_nop 2
	ds_read_b128 v[104:107], v139
	ds_read_b128 v[188:191], v139 offset:1024
	ds_read_b128 v[192:195], v139 offset:2048
	ds_read_b128 v[202:205], v139 offset:3072
	s_barrier
	s_waitcnt lgkmcnt(0)
	s_setprio 1
	s_waitcnt lgkmcnt(0)
	v_mfma_f32_16x16x32_bf16 v[92:95], v[104:107], v[156:159], v[92:95]
	v_mfma_f32_16x16x32_bf16 v[84:87], v[104:107], v[164:167], v[84:87]
	v_mfma_f32_16x16x32_bf16 v[76:79], v[104:107], v[172:175], v[76:79]
	v_mfma_f32_16x16x32_bf16 v[68:71], v[104:107], v[180:183], v[68:71]
	v_mfma_f32_16x16x32_bf16 v[64:67], v[192:195], v[180:183], v[64:67]
	v_mfma_f32_16x16x32_bf16 v[92:95], v[188:191], v[160:163], v[92:95]
	v_mfma_f32_16x16x32_bf16 v[88:91], v[192:195], v[156:159], v[88:91]
	v_mfma_f32_16x16x32_bf16 v[84:87], v[188:191], v[168:171], v[84:87]
	v_mfma_f32_16x16x32_bf16 v[80:83], v[192:195], v[164:167], v[80:83]
	v_mfma_f32_16x16x32_bf16 v[76:79], v[188:191], v[176:179], v[76:79]
	v_mfma_f32_16x16x32_bf16 v[72:75], v[192:195], v[172:175], v[72:75]
	v_mfma_f32_16x16x32_bf16 v[68:71], v[188:191], v[184:187], v[68:71]
	v_mfma_f32_16x16x32_bf16 v[64:67], v[202:205], v[184:187], v[64:67]
	v_mfma_f32_16x16x32_bf16 v[156:159], v[202:205], v[160:163], v[88:91]
	v_mfma_f32_16x16x32_bf16 v[160:163], v[202:205], v[168:171], v[80:83]
	v_mfma_f32_16x16x32_bf16 v[164:167], v[202:205], v[176:179], v[72:75]
	s_setprio 0
	s_barrier
	s_nop 0
	ds_read_b128 v[72:75], v136 offset:16384
	ds_read_b128 v[80:83], v136 offset:17408
	ds_read_b128 v[88:91], v135 offset:16384
	ds_read_b128 v[168:171], v135 offset:17408
	ds_read_b128 v[172:175], v134 offset:16384
	ds_read_b128 v[176:179], v134 offset:17408
	ds_read_b128 v[180:183], v133 offset:16384
	ds_read_b128 v[184:187], v133 offset:17408
	s_waitcnt vmcnt(4)
	s_barrier
	s_waitcnt lgkmcnt(0)
	s_setprio 1
	s_waitcnt lgkmcnt(0)
	v_mfma_f32_16x16x32_bf16 v[60:63], v[140:143], v[72:75], v[60:63]
	v_mfma_f32_16x16x32_bf16 v[56:59], v[148:151], v[72:75], v[56:59]
	v_mfma_f32_16x16x32_bf16 v[48:51], v[148:151], v[88:91], v[48:51]
	v_mfma_f32_16x16x32_bf16 v[32:35], v[148:151], v[180:183], v[32:35]
	v_mfma_f32_16x16x32_bf16 v[60:63], v[144:147], v[80:83], v[60:63]
	v_mfma_f32_16x16x32_bf16 v[56:59], v[152:155], v[80:83], v[56:59]
	v_mfma_f32_16x16x32_bf16 v[52:55], v[140:143], v[88:91], v[52:55]
	v_mfma_f32_16x16x32_bf16 v[48:51], v[152:155], v[168:171], v[48:51]
	v_mfma_f32_16x16x32_bf16 v[44:47], v[140:143], v[172:175], v[44:47]
	v_mfma_f32_16x16x32_bf16 v[40:43], v[148:151], v[172:175], v[40:43]
	v_mfma_f32_16x16x32_bf16 v[36:39], v[140:143], v[180:183], v[36:39]
	v_mfma_f32_16x16x32_bf16 v[32:35], v[152:155], v[184:187], v[32:35]
	v_mfma_f32_16x16x32_bf16 v[206:209], v[144:147], v[168:171], v[52:55]
	v_mfma_f32_16x16x32_bf16 v[210:213], v[144:147], v[176:179], v[44:47]
	v_mfma_f32_16x16x32_bf16 v[214:217], v[152:155], v[176:179], v[40:43]
	v_mfma_f32_16x16x32_bf16 v[140:143], v[144:147], v[184:187], v[36:39]
	s_setprio 0
	s_setprio 1
	v_mfma_f32_16x16x32_bf16 v[24:27], v[192:195], v[72:75], v[24:27]
	v_mfma_f32_16x16x32_bf16 v[20:23], v[104:107], v[88:91], v[20:23]
	v_mfma_f32_16x16x32_bf16 v[28:31], v[104:107], v[72:75], v[28:31]
	v_mfma_f32_16x16x32_bf16 v[24:27], v[202:205], v[80:83], v[24:27]
	v_mfma_f32_16x16x32_bf16 v[20:23], v[188:191], v[168:171], v[20:23]
	v_mfma_f32_16x16x32_bf16 v[16:19], v[192:195], v[88:91], v[16:19]
	v_mfma_f32_16x16x32_bf16 v[12:15], v[104:107], v[172:175], v[12:15]
	v_mfma_f32_16x16x32_bf16 v[8:11], v[192:195], v[172:175], v[8:11]
	v_mfma_f32_16x16x32_bf16 v[4:7], v[104:107], v[180:183], v[4:7]
	v_mfma_f32_16x16x32_bf16 v[0:3], v[192:195], v[180:183], v[0:3]
	v_mfma_f32_16x16x32_bf16 v[144:147], v[188:191], v[80:83], v[28:31]
	v_mfma_f32_16x16x32_bf16 v[148:151], v[202:205], v[168:171], v[16:19]
	v_mfma_f32_16x16x32_bf16 v[152:155], v[188:191], v[176:179], v[12:15]
	v_mfma_f32_16x16x32_bf16 v[168:171], v[202:205], v[176:179], v[8:11]
	v_mfma_f32_16x16x32_bf16 v[172:175], v[188:191], v[184:187], v[4:7]
	v_mfma_f32_16x16x32_bf16 v[176:179], v[202:205], v[184:187], v[0:3]
	s_setprio 0
	s_barrier
	ds_read_b128 v[16:19], v138
	ds_read_b128 v[180:183], v138 offset:1024
	ds_read_b128 v[184:187], v138 offset:2048
	ds_read_b128 v[188:191], v138 offset:3072
	ds_read_b128 v[0:3], v136 offset:32768
	ds_read_b128 v[4:7], v136 offset:33792
	ds_read_b128 v[8:11], v135 offset:32768
	ds_read_b128 v[12:15], v135 offset:33792
	ds_read_b128 v[44:47], v134 offset:32768
	ds_read_b128 v[192:195], v134 offset:33792
	ds_read_b128 v[202:205], v133 offset:32768
	ds_read_b128 v[218:221], v133 offset:33792
	s_waitcnt vmcnt(2)
	s_barrier
	s_waitcnt lgkmcnt(0)
	s_setprio 1
	s_waitcnt lgkmcnt(0)
	v_mfma_f32_16x16x32_bf16 v[28:31], v[16:19], v[0:3], v[124:127]
	v_mfma_f32_16x16x32_bf16 v[52:55], v[180:183], v[4:7], v[28:31]
	v_mfma_f32_16x16x32_bf16 v[28:31], v[184:187], v[0:3], v[120:123]
	v_mfma_f32_16x16x32_bf16 v[104:107], v[188:191], v[4:7], v[28:31]
	v_mfma_f32_16x16x32_bf16 v[28:31], v[16:19], v[8:11], v[116:119]
	v_mfma_f32_16x16x32_bf16 v[72:75], v[180:183], v[12:15], v[28:31]
	v_mfma_f32_16x16x32_bf16 v[28:31], v[184:187], v[8:11], v[112:115]
	v_mfma_f32_16x16x32_bf16 v[116:119], v[188:191], v[12:15], v[28:31]
	v_mfma_f32_16x16x32_bf16 v[28:31], v[16:19], v[44:47], v[108:111]
	v_mfma_f32_16x16x32_bf16 v[80:83], v[180:183], v[192:195], v[28:31]
	v_mfma_f32_16x16x32_bf16 v[28:31], v[184:187], v[44:47], v[128:131]
	v_mfma_f32_16x16x32_bf16 v[108:111], v[188:191], v[192:195], v[28:31]
	v_mfma_f32_16x16x32_bf16 v[28:31], v[16:19], v[202:205], v[100:103]
	v_mfma_f32_16x16x32_bf16 v[88:91], v[180:183], v[218:221], v[28:31]
	v_mfma_f32_16x16x32_bf16 v[28:31], v[184:187], v[202:205], v[96:99]
	v_mfma_f32_16x16x32_bf16 v[96:99], v[188:191], v[218:221], v[28:31]
	s_setprio 0
	s_barrier
	ds_read_b128 v[128:131], v137
	ds_read_b128 v[222:225], v137 offset:1024
	ds_read_b128 v[228:231], v137 offset:2048
	ds_read_b128 v[232:235], v137 offset:3072
	s_waitcnt vmcnt(0)
	s_barrier
	s_waitcnt lgkmcnt(0)
	s_setprio 1
	s_waitcnt lgkmcnt(0)
	v_mfma_f32_16x16x32_bf16 v[28:31], v[128:131], v[0:3], v[92:95]
	v_mfma_f32_16x16x32_bf16 v[0:3], v[228:231], v[0:3], v[156:159]
	v_mfma_f32_16x16x32_bf16 v[28:31], v[222:225], v[4:7], v[28:31]
	v_mfma_f32_16x16x32_bf16 v[0:3], v[232:235], v[4:7], v[0:3]
	v_mfma_f32_16x16x32_bf16 v[4:7], v[128:131], v[8:11], v[84:87]
	v_mfma_f32_16x16x32_bf16 v[36:39], v[222:225], v[12:15], v[4:7]
	v_mfma_f32_16x16x32_bf16 v[4:7], v[228:231], v[8:11], v[160:163]
	v_mfma_f32_16x16x32_bf16 v[4:7], v[232:235], v[12:15], v[4:7]
	v_mfma_f32_16x16x32_bf16 v[8:11], v[128:131], v[44:47], v[76:79]
	v_mfma_f32_16x16x32_bf16 v[12:15], v[128:131], v[202:205], v[68:71]
	v_mfma_f32_16x16x32_bf16 v[40:43], v[222:225], v[192:195], v[8:11]
	v_mfma_f32_16x16x32_bf16 v[8:11], v[228:231], v[44:47], v[164:167]
	v_mfma_f32_16x16x32_bf16 v[44:47], v[222:225], v[218:221], v[12:15]
	v_mfma_f32_16x16x32_bf16 v[12:15], v[228:231], v[202:205], v[64:67]
	v_mfma_f32_16x16x32_bf16 v[8:11], v[232:235], v[192:195], v[8:11]
	v_mfma_f32_16x16x32_bf16 v[12:15], v[232:235], v[218:221], v[12:15]
	s_setprio 0
	s_barrier
	ds_read_b128 v[64:67], v136 offset:49152
	ds_read_b128 v[136:139], v136 offset:50176
	ds_read_b128 v[156:159], v135 offset:49152
	ds_read_b128 v[160:163], v135 offset:50176
	ds_read_b128 v[164:167], v134 offset:49152
	ds_read_b128 v[192:195], v134 offset:50176
	ds_read_b128 v[202:205], v133 offset:49152
	ds_read_b128 v[218:221], v133 offset:50176
	s_barrier
	s_waitcnt lgkmcnt(0)
	s_setprio 1
	s_waitcnt lgkmcnt(0)
	v_mfma_f32_16x16x32_bf16 v[56:59], v[184:187], v[64:67], v[56:59]
	v_mfma_f32_16x16x32_bf16 v[48:51], v[184:187], v[156:159], v[48:51]
	v_mfma_f32_16x16x32_bf16 v[60:63], v[16:19], v[64:67], v[60:63]
	v_mfma_f32_16x16x32_bf16 v[92:95], v[188:191], v[136:139], v[56:59]
	v_mfma_f32_16x16x32_bf16 v[56:59], v[16:19], v[156:159], v[206:209]
	v_mfma_f32_16x16x32_bf16 v[84:87], v[188:191], v[160:163], v[48:51]
	v_mfma_f32_16x16x32_bf16 v[48:51], v[16:19], v[164:167], v[210:213]
	v_mfma_f32_16x16x32_bf16 v[16:19], v[16:19], v[202:205], v[140:143]
	v_mfma_f32_16x16x32_bf16 v[120:123], v[180:183], v[192:195], v[48:51]
	v_mfma_f32_16x16x32_bf16 v[48:51], v[184:187], v[164:167], v[214:217]
	v_mfma_f32_16x16x32_bf16 v[124:127], v[180:183], v[218:221], v[16:19]
	v_mfma_f32_16x16x32_bf16 v[16:19], v[184:187], v[202:205], v[32:35]
	v_mfma_f32_16x16x32_bf16 v[100:103], v[180:183], v[136:139], v[60:63]
	v_mfma_f32_16x16x32_bf16 v[112:115], v[180:183], v[160:163], v[56:59]
	v_mfma_f32_16x16x32_bf16 v[76:79], v[188:191], v[192:195], v[48:51]
	v_mfma_f32_16x16x32_bf16 v[68:71], v[188:191], v[218:221], v[16:19]
	s_setprio 0
	s_setprio 1
	v_mfma_f32_16x16x32_bf16 v[16:19], v[128:131], v[64:67], v[144:147]
	v_mfma_f32_16x16x32_bf16 v[48:51], v[222:225], v[136:139], v[16:19]
	v_mfma_f32_16x16x32_bf16 v[16:19], v[228:231], v[64:67], v[24:27]
	v_mfma_f32_16x16x32_bf16 v[20:23], v[128:131], v[156:159], v[20:23]
	v_mfma_f32_16x16x32_bf16 v[24:27], v[128:131], v[164:167], v[152:155]
	v_mfma_f32_16x16x32_bf16 v[32:35], v[128:131], v[202:205], v[172:175]
	v_mfma_f32_16x16x32_bf16 v[56:59], v[222:225], v[160:163], v[20:23]
	v_mfma_f32_16x16x32_bf16 v[20:23], v[228:231], v[156:159], v[148:151]
	v_mfma_f32_16x16x32_bf16 v[60:63], v[222:225], v[192:195], v[24:27]
	v_mfma_f32_16x16x32_bf16 v[24:27], v[228:231], v[164:167], v[168:171]
	v_mfma_f32_16x16x32_bf16 v[64:67], v[222:225], v[218:221], v[32:35]
	v_mfma_f32_16x16x32_bf16 v[32:35], v[228:231], v[202:205], v[176:179]
	v_mfma_f32_16x16x32_bf16 v[16:19], v[232:235], v[136:139], v[16:19]
	v_mfma_f32_16x16x32_bf16 v[20:23], v[232:235], v[160:163], v[20:23]
	v_mfma_f32_16x16x32_bf16 v[24:27], v[232:235], v[192:195], v[24:27]
	v_mfma_f32_16x16x32_bf16 v[32:35], v[232:235], v[218:221], v[32:35]
	s_setprio 0
	s_movk_i32 s9, 0x100
	v_cmp_gt_u32_e32 vcc, s9, v132
	s_barrier
	s_and_saveexec_b64 s[28:29], vcc
	s_cbranch_execz .LBB0_212
	s_barrier
	s_branch .LBB0_212

.LBB0_314:
	ds_read_b128 v[172:175], v170
	ds_read_b128 v[176:179], v170 offset:1024
	ds_read_b128 v[180:183], v170 offset:2048
	ds_read_b128 v[184:187], v170 offset:3072
	s_add_u32 s8, s37, vcc_lo
	s_addc_u32 s9, s38, vcc_hi
	ds_read_b128 v[188:191], v166
	ds_read_b128 v[192:195], v166 offset:1024
	ds_read_b128 v[202:205], v165
	ds_read_b128 v[206:209], v165 offset:1024
	ds_read_b128 v[210:213], v163
	ds_read_b128 v[214:217], v163 offset:1024
	ds_read_b128 v[218:221], v162
	ds_read_b128 v[236:239], v162 offset:1024
	s_add_i32 s40, s34, 0xc000
	s_mov_b32 m0, s40
	s_add_i32 s41, s34, 0xe000
	s_add_u32 s98, s8, s94
	s_addc_u32 s99, s9, s95
	global_load_lds_dwordx4 v160, s[98:99]
	s_mov_b32 m0, s41
	s_nop 0
	global_load_lds_dwordx4 v161, s[98:99]
	s_waitcnt lgkmcnt(8)
	s_barrier
	s_waitcnt lgkmcnt(7)
	v_mfma_f32_16x16x32_bf16 v[44:47], v[172:175], v[188:191], v[44:47]
	v_mfma_f32_16x16x32_bf16 v[40:43], v[180:183], v[188:191], v[40:43]
	s_waitcnt lgkmcnt(5)
	v_mfma_f32_16x16x32_bf16 v[60:63], v[172:175], v[202:205], v[60:63]
	v_mfma_f32_16x16x32_bf16 v[56:59], v[180:183], v[202:205], v[56:59]
	s_waitcnt lgkmcnt(3)
	v_mfma_f32_16x16x32_bf16 v[76:79], v[172:175], v[210:213], v[76:79]
	v_mfma_f32_16x16x32_bf16 v[72:75], v[180:183], v[210:213], v[72:75]
	s_waitcnt lgkmcnt(1)
	v_mfma_f32_16x16x32_bf16 v[92:95], v[172:175], v[218:221], v[92:95]
	v_mfma_f32_16x16x32_bf16 v[88:91], v[180:183], v[218:221], v[88:91]
	v_mfma_f32_16x16x32_bf16 v[44:47], v[176:179], v[192:195], v[44:47]
	v_mfma_f32_16x16x32_bf16 v[40:43], v[184:187], v[192:195], v[40:43]
	v_mfma_f32_16x16x32_bf16 v[60:63], v[176:179], v[206:209], v[60:63]
	v_mfma_f32_16x16x32_bf16 v[56:59], v[184:187], v[206:209], v[56:59]
	v_mfma_f32_16x16x32_bf16 v[76:79], v[176:179], v[214:217], v[76:79]
	v_mfma_f32_16x16x32_bf16 v[72:75], v[184:187], v[214:217], v[72:75]
	s_waitcnt lgkmcnt(0)
	v_mfma_f32_16x16x32_bf16 v[92:95], v[176:179], v[236:239], v[92:95]
	v_mfma_f32_16x16x32_bf16 v[88:91], v[184:187], v[236:239], v[88:91]
	s_barrier
	s_add_i32 s39, s39, 2
	s_add_u32 s28, s6, vcc_lo
	s_addc_u32 s29, s7, vcc_hi
	ds_read_b128 v[240:243], v169
	ds_read_b128 v[244:247], v169 offset:1024
	ds_read_b128 v[248:251], v169 offset:2048
	ds_read_b128 v[228:231], v169 offset:3072
	s_mov_b32 m0, s59
	s_add_u32 s98, s28, s0
	s_addc_u32 s99, s29, s1
	global_load_lds_dwordx4 v160, s[98:99]
	s_mov_b32 m0, s61
	s_nop 0
	global_load_lds_dwordx4 v161, s[98:99]
	s_barrier
	s_waitcnt lgkmcnt(3)
	v_mfma_f32_16x16x32_bf16 v[32:35], v[240:243], v[188:191], v[32:35]
	s_waitcnt lgkmcnt(1)
	v_mfma_f32_16x16x32_bf16 v[36:39], v[248:251], v[188:191], v[36:39]
	v_mfma_f32_16x16x32_bf16 v[48:51], v[240:243], v[202:205], v[48:51]
	v_mfma_f32_16x16x32_bf16 v[52:55], v[248:251], v[202:205], v[52:55]
	v_mfma_f32_16x16x32_bf16 v[64:67], v[240:243], v[210:213], v[64:67]
	v_mfma_f32_16x16x32_bf16 v[68:71], v[248:251], v[210:213], v[68:71]
	v_mfma_f32_16x16x32_bf16 v[80:83], v[240:243], v[218:221], v[80:83]
	v_mfma_f32_16x16x32_bf16 v[84:87], v[248:251], v[218:221], v[84:87]
	v_mfma_f32_16x16x32_bf16 v[32:35], v[244:247], v[192:195], v[32:35]
	s_waitcnt lgkmcnt(0)
	v_mfma_f32_16x16x32_bf16 v[36:39], v[228:231], v[192:195], v[36:39]
	v_mfma_f32_16x16x32_bf16 v[48:51], v[244:247], v[206:209], v[48:51]
	v_mfma_f32_16x16x32_bf16 v[52:55], v[228:231], v[206:209], v[52:55]
	v_mfma_f32_16x16x32_bf16 v[64:67], v[244:247], v[214:217], v[64:67]
	v_mfma_f32_16x16x32_bf16 v[68:71], v[228:231], v[214:217], v[68:71]
	v_mfma_f32_16x16x32_bf16 v[80:83], v[244:247], v[236:239], v[80:83]
	v_mfma_f32_16x16x32_bf16 v[84:87], v[228:231], v[236:239], v[84:87]
	s_add_u32 s92, s90, vcc_lo
	s_addc_u32 s93, s91, vcc_hi
	s_barrier
	ds_read_b128 v[188:191], v166 offset:16384
	ds_read_b128 v[192:195], v166 offset:17408
	ds_read_b128 v[202:205], v165 offset:16384
	ds_read_b128 v[206:209], v165 offset:17408
	ds_read_b128 v[210:213], v163 offset:16384
	ds_read_b128 v[214:217], v163 offset:17408
	ds_read_b128 v[218:221], v162 offset:16384
	ds_read_b128 v[236:239], v162 offset:17408
	s_mov_b32 m0, s34
	s_add_u32 s98, s92, s0
	s_addc_u32 s99, s93, s1
	global_load_lds_dwordx4 v160, s[98:99]
	s_mov_b32 m0, s79
	s_nop 0
	global_load_lds_dwordx4 v161, s[98:99]
	s_barrier
	s_waitcnt lgkmcnt(7)
	v_mfma_f32_16x16x32_bf16 v[108:111], v[172:175], v[188:191], v[108:111]
	v_mfma_f32_16x16x32_bf16 v[104:107], v[180:183], v[188:191], v[104:107]
	s_waitcnt lgkmcnt(5)
	v_mfma_f32_16x16x32_bf16 v[124:127], v[172:175], v[202:205], v[124:127]
	v_mfma_f32_16x16x32_bf16 v[120:123], v[180:183], v[202:205], v[120:123]
	s_waitcnt lgkmcnt(3)
	v_mfma_f32_16x16x32_bf16 v[140:143], v[172:175], v[210:213], v[140:143]
	v_mfma_f32_16x16x32_bf16 v[136:139], v[180:183], v[210:213], v[136:139]
	s_waitcnt lgkmcnt(1)
	v_mfma_f32_16x16x32_bf16 v[156:159], v[172:175], v[218:221], v[156:159]
	v_mfma_f32_16x16x32_bf16 v[152:155], v[180:183], v[218:221], v[152:155]
	v_mfma_f32_16x16x32_bf16 v[108:111], v[176:179], v[192:195], v[108:111]
	v_mfma_f32_16x16x32_bf16 v[104:107], v[184:187], v[192:195], v[104:107]
	v_mfma_f32_16x16x32_bf16 v[124:127], v[176:179], v[206:209], v[124:127]
	v_mfma_f32_16x16x32_bf16 v[120:123], v[184:187], v[206:209], v[120:123]
	v_mfma_f32_16x16x32_bf16 v[140:143], v[176:179], v[214:217], v[140:143]
	v_mfma_f32_16x16x32_bf16 v[136:139], v[184:187], v[214:217], v[136:139]
	s_waitcnt lgkmcnt(0)
	v_mfma_f32_16x16x32_bf16 v[156:159], v[176:179], v[236:239], v[156:159]
	v_mfma_f32_16x16x32_bf16 v[152:155], v[184:187], v[236:239], v[152:155]
	s_barrier
	s_add_u32 s96, s82, vcc_lo
	s_addc_u32 s97, s36, vcc_hi
	s_mov_b32 m0, s52
	s_add_u32 s98, s96, s0
	s_addc_u32 s99, s97, s1
	global_load_lds_dwordx4 v160, s[98:99]
	s_mov_b32 m0, s53
	s_nop 0
	global_load_lds_dwordx4 v161, s[98:99]
	s_waitcnt vmcnt(6)
	s_barrier
	v_mfma_f32_16x16x32_bf16 v[96:99], v[240:243], v[188:191], v[96:99]
	v_mfma_f32_16x16x32_bf16 v[100:103], v[248:251], v[188:191], v[100:103]
	v_mfma_f32_16x16x32_bf16 v[112:115], v[240:243], v[202:205], v[112:115]
	v_mfma_f32_16x16x32_bf16 v[116:119], v[248:251], v[202:205], v[116:119]
	v_mfma_f32_16x16x32_bf16 v[128:131], v[240:243], v[210:213], v[128:131]
	v_mfma_f32_16x16x32_bf16 v[132:135], v[248:251], v[210:213], v[132:135]
	v_mfma_f32_16x16x32_bf16 v[144:147], v[240:243], v[218:221], v[144:147]
	v_mfma_f32_16x16x32_bf16 v[148:151], v[248:251], v[218:221], v[148:151]
	v_mfma_f32_16x16x32_bf16 v[96:99], v[244:247], v[192:195], v[96:99]
	v_mfma_f32_16x16x32_bf16 v[100:103], v[228:231], v[192:195], v[100:103]
	v_mfma_f32_16x16x32_bf16 v[112:115], v[244:247], v[206:209], v[112:115]
	v_mfma_f32_16x16x32_bf16 v[116:119], v[228:231], v[206:209], v[116:119]
	v_mfma_f32_16x16x32_bf16 v[128:131], v[244:247], v[214:217], v[128:131]
	v_mfma_f32_16x16x32_bf16 v[132:135], v[228:231], v[214:217], v[132:135]
	v_mfma_f32_16x16x32_bf16 v[144:147], v[244:247], v[236:239], v[144:147]
	v_mfma_f32_16x16x32_bf16 v[148:151], v[228:231], v[236:239], v[148:151]
	s_barrier
	ds_read_b128 v[172:175], v168
	ds_read_b128 v[176:179], v168 offset:1024
	ds_read_b128 v[180:183], v168 offset:2048
	ds_read_b128 v[184:187], v168 offset:3072
	ds_read_b128 v[188:191], v166 offset:32768
	ds_read_b128 v[192:195], v166 offset:33792
	ds_read_b128 v[202:205], v165 offset:32768
	ds_read_b128 v[206:209], v165 offset:33792
	ds_read_b128 v[210:213], v163 offset:32768
	ds_read_b128 v[214:217], v163 offset:33792
	ds_read_b128 v[218:221], v162 offset:32768
	ds_read_b128 v[228:231], v162 offset:33792
	s_mov_b32 m0, s68
	s_add_u32 s98, s8, s0
	s_addc_u32 s99, s9, s1
	global_load_lds_dwordx4 v160, s[98:99]
	s_mov_b32 m0, s69
	s_nop 0
	global_load_lds_dwordx4 v161, s[98:99]
	s_waitcnt lgkmcnt(8)
	s_barrier
	s_waitcnt lgkmcnt(7)
	v_mfma_f32_16x16x32_bf16 v[44:47], v[172:175], v[188:191], v[44:47]
	v_mfma_f32_16x16x32_bf16 v[40:43], v[180:183], v[188:191], v[40:43]
	s_waitcnt lgkmcnt(5)
	v_mfma_f32_16x16x32_bf16 v[60:63], v[172:175], v[202:205], v[60:63]
	v_mfma_f32_16x16x32_bf16 v[56:59], v[180:183], v[202:205], v[56:59]
	s_waitcnt lgkmcnt(3)
	v_mfma_f32_16x16x32_bf16 v[76:79], v[172:175], v[210:213], v[76:79]
	v_mfma_f32_16x16x32_bf16 v[72:75], v[180:183], v[210:213], v[72:75]
	s_waitcnt lgkmcnt(1)
	v_mfma_f32_16x16x32_bf16 v[92:95], v[172:175], v[218:221], v[92:95]
	v_mfma_f32_16x16x32_bf16 v[88:91], v[180:183], v[218:221], v[88:91]
	v_mfma_f32_16x16x32_bf16 v[44:47], v[176:179], v[192:195], v[44:47]
	v_mfma_f32_16x16x32_bf16 v[40:43], v[184:187], v[192:195], v[40:43]
	v_mfma_f32_16x16x32_bf16 v[60:63], v[176:179], v[206:209], v[60:63]
	v_mfma_f32_16x16x32_bf16 v[56:59], v[184:187], v[206:209], v[56:59]
	v_mfma_f32_16x16x32_bf16 v[76:79], v[176:179], v[214:217], v[76:79]
	v_mfma_f32_16x16x32_bf16 v[72:75], v[184:187], v[214:217], v[72:75]
	s_waitcnt lgkmcnt(0)
	v_mfma_f32_16x16x32_bf16 v[92:95], v[176:179], v[228:231], v[92:95]
	v_mfma_f32_16x16x32_bf16 v[88:91], v[184:187], v[228:231], v[88:91]
	s_barrier
	ds_read_b128 v[236:239], v167
	ds_read_b128 v[240:243], v167 offset:1024
	ds_read_b128 v[244:247], v167 offset:2048
	ds_read_b128 v[248:251], v167 offset:3072
	s_mov_b32 m0, s70
	s_add_u32 s98, s28, s30
	s_addc_u32 s99, s29, s31
	global_load_lds_dwordx4 v160, s[98:99]
	s_mov_b32 m0, s71
	s_nop 0
	global_load_lds_dwordx4 v161, s[98:99]
	s_barrier
	s_waitcnt lgkmcnt(3)
	v_mfma_f32_16x16x32_bf16 v[32:35], v[236:239], v[188:191], v[32:35]
	s_waitcnt lgkmcnt(1)
	v_mfma_f32_16x16x32_bf16 v[36:39], v[244:247], v[188:191], v[36:39]
	v_mfma_f32_16x16x32_bf16 v[48:51], v[236:239], v[202:205], v[48:51]
	v_mfma_f32_16x16x32_bf16 v[52:55], v[244:247], v[202:205], v[52:55]
	v_mfma_f32_16x16x32_bf16 v[64:67], v[236:239], v[210:213], v[64:67]
	v_mfma_f32_16x16x32_bf16 v[68:71], v[244:247], v[210:213], v[68:71]
	v_mfma_f32_16x16x32_bf16 v[80:83], v[236:239], v[218:221], v[80:83]
	v_mfma_f32_16x16x32_bf16 v[84:87], v[244:247], v[218:221], v[84:87]
	v_mfma_f32_16x16x32_bf16 v[32:35], v[240:243], v[192:195], v[32:35]
	s_waitcnt lgkmcnt(0)
	v_mfma_f32_16x16x32_bf16 v[36:39], v[248:251], v[192:195], v[36:39]
	v_mfma_f32_16x16x32_bf16 v[48:51], v[240:243], v[206:209], v[48:51]
	v_mfma_f32_16x16x32_bf16 v[52:55], v[248:251], v[206:209], v[52:55]
	v_mfma_f32_16x16x32_bf16 v[64:67], v[240:243], v[214:217], v[64:67]
	v_mfma_f32_16x16x32_bf16 v[68:71], v[248:251], v[214:217], v[68:71]
	v_mfma_f32_16x16x32_bf16 v[80:83], v[240:243], v[228:231], v[80:83]
	v_mfma_f32_16x16x32_bf16 v[84:87], v[248:251], v[228:231], v[84:87]
	v_mov_b32_e32 v222, v161
	s_barrier
	ds_read_b128 v[188:191], v166 offset:49152
	ds_read_b128 v[192:195], v166 offset:50176
	ds_read_b128 v[202:205], v165 offset:49152
	ds_read_b128 v[206:209], v165 offset:50176
	ds_read_b128 v[210:213], v163 offset:49152
	ds_read_b128 v[214:217], v163 offset:50176
	ds_read_b128 v[218:221], v162 offset:49152
	ds_read_b128 v[228:231], v162 offset:50176
	v_mov_b32_e32 v223, v197
	s_mov_b32 m0, s72
	s_add_u32 s98, s92, s30
	s_addc_u32 s99, s93, s31
	global_load_lds_dwordx4 v160, s[98:99]
	s_mov_b32 m0, s73
	s_nop 0
	global_load_lds_dwordx4 v161, s[98:99]
	s_barrier
	s_waitcnt lgkmcnt(7)
	v_mfma_f32_16x16x32_bf16 v[108:111], v[172:175], v[188:191], v[108:111]
	v_mfma_f32_16x16x32_bf16 v[104:107], v[180:183], v[188:191], v[104:107]
	s_waitcnt lgkmcnt(5)
	v_mfma_f32_16x16x32_bf16 v[124:127], v[172:175], v[202:205], v[124:127]
	v_mfma_f32_16x16x32_bf16 v[120:123], v[180:183], v[202:205], v[120:123]
	s_waitcnt lgkmcnt(3)
	v_mfma_f32_16x16x32_bf16 v[140:143], v[172:175], v[210:213], v[140:143]
	v_mfma_f32_16x16x32_bf16 v[136:139], v[180:183], v[210:213], v[136:139]
	s_waitcnt lgkmcnt(1)
	v_mfma_f32_16x16x32_bf16 v[156:159], v[172:175], v[218:221], v[156:159]
	v_mfma_f32_16x16x32_bf16 v[152:155], v[180:183], v[218:221], v[152:155]
	v_mfma_f32_16x16x32_bf16 v[108:111], v[176:179], v[192:195], v[108:111]
	v_mfma_f32_16x16x32_bf16 v[104:107], v[184:187], v[192:195], v[104:107]
	v_mfma_f32_16x16x32_bf16 v[124:127], v[176:179], v[206:209], v[124:127]
	v_mfma_f32_16x16x32_bf16 v[120:123], v[184:187], v[206:209], v[120:123]
	v_mfma_f32_16x16x32_bf16 v[140:143], v[176:179], v[214:217], v[140:143]
	v_mfma_f32_16x16x32_bf16 v[136:139], v[184:187], v[214:217], v[136:139]
	s_waitcnt lgkmcnt(0)
	v_mfma_f32_16x16x32_bf16 v[156:159], v[176:179], v[228:231], v[156:159]
	v_mfma_f32_16x16x32_bf16 v[152:155], v[184:187], v[228:231], v[152:155]
	s_barrier
	v_mov_b32_e32 v196, v160
	s_mov_b32 m0, s75
	s_add_u32 s98, s96, s30
	s_addc_u32 s99, s97, s31
	global_load_lds_dwordx4 v160, s[98:99]
	s_mov_b32 m0, s89
	s_nop 0
	global_load_lds_dwordx4 v161, s[98:99]
	s_waitcnt vmcnt(6)
	s_barrier
	v_mfma_f32_16x16x32_bf16 v[96:99], v[236:239], v[188:191], v[96:99]
	v_mfma_f32_16x16x32_bf16 v[100:103], v[244:247], v[188:191], v[100:103]
	v_mfma_f32_16x16x32_bf16 v[112:115], v[236:239], v[202:205], v[112:115]
	v_mfma_f32_16x16x32_bf16 v[116:119], v[244:247], v[202:205], v[116:119]
	v_mfma_f32_16x16x32_bf16 v[128:131], v[236:239], v[210:213], v[128:131]
	v_mfma_f32_16x16x32_bf16 v[132:135], v[244:247], v[210:213], v[132:135]
	v_mfma_f32_16x16x32_bf16 v[144:147], v[236:239], v[218:221], v[144:147]
	v_mfma_f32_16x16x32_bf16 v[148:151], v[244:247], v[218:221], v[148:151]
	v_mfma_f32_16x16x32_bf16 v[96:99], v[240:243], v[192:195], v[96:99]
	v_mfma_f32_16x16x32_bf16 v[100:103], v[248:251], v[192:195], v[100:103]
	v_mfma_f32_16x16x32_bf16 v[112:115], v[240:243], v[206:209], v[112:115]
	v_mfma_f32_16x16x32_bf16 v[116:119], v[248:251], v[206:209], v[116:119]
	v_mfma_f32_16x16x32_bf16 v[128:131], v[240:243], v[214:217], v[128:131]
	v_mfma_f32_16x16x32_bf16 v[132:135], v[248:251], v[214:217], v[132:135]
	v_mfma_f32_16x16x32_bf16 v[144:147], v[240:243], v[228:231], v[144:147]
	v_mfma_f32_16x16x32_bf16 v[148:151], v[248:251], v[228:231], v[148:151]
	s_add_u32 vcc_lo, vcc_lo, 0x100
	s_addc_u32 vcc_hi, vcc_hi, 0
	s_cmp_lt_u32 s39, s74
	s_barrier
	s_cbranch_scc1 .LBB0_314
	s_add_i32 s34, s33, -1
	s_lshl_b64 s[6:7], s[34:35], 7
	s_add_u32 s6, s84, s6
	s_addc_u32 s7, s85, s7
	s_mov_b32 m0, s40
	ds_read_b128 v[172:175], v170
	ds_read_b128 v[176:179], v170 offset:1024
	ds_read_b128 v[180:183], v170 offset:2048
	ds_read_b128 v[184:187], v170 offset:3072
	ds_read_b128 v[188:191], v166
	ds_read_b128 v[192:195], v166 offset:1024
	ds_read_b128 v[202:205], v165
	ds_read_b128 v[206:209], v165 offset:1024
	ds_read_b128 v[210:213], v163
	ds_read_b128 v[214:217], v163 offset:1024
	ds_read_b128 v[218:221], v162
	ds_read_b128 v[228:231], v162 offset:1024
	s_nop 0
	global_load_lds_dwordx4 v160, s[6:7]
	s_mov_b32 m0, s41
	s_nop 0
	global_load_lds_dwordx4 v161, s[6:7]
	s_barrier
	s_waitcnt lgkmcnt(0)
	s_setprio 1
	s_waitcnt lgkmcnt(0)
	v_mfma_f32_16x16x32_bf16 v[40:43], v[180:183], v[188:191], v[40:43]
	v_mfma_f32_16x16x32_bf16 v[56:59], v[180:183], v[202:205], v[56:59]
	v_mfma_f32_16x16x32_bf16 v[72:75], v[180:183], v[210:213], v[72:75]
	v_mfma_f32_16x16x32_bf16 v[92:95], v[172:175], v[218:221], v[92:95]
	v_mfma_f32_16x16x32_bf16 v[88:91], v[180:183], v[218:221], v[88:91]
	v_mfma_f32_16x16x32_bf16 v[44:47], v[172:175], v[188:191], v[44:47]
	v_mfma_f32_16x16x32_bf16 v[40:43], v[184:187], v[192:195], v[40:43]
	v_mfma_f32_16x16x32_bf16 v[60:63], v[172:175], v[202:205], v[60:63]
	v_mfma_f32_16x16x32_bf16 v[56:59], v[184:187], v[206:209], v[56:59]
	v_mfma_f32_16x16x32_bf16 v[76:79], v[172:175], v[210:213], v[76:79]
	v_mfma_f32_16x16x32_bf16 v[72:75], v[184:187], v[214:217], v[72:75]
	v_mfma_f32_16x16x32_bf16 v[92:95], v[176:179], v[228:231], v[92:95]
	v_mfma_f32_16x16x32_bf16 v[88:91], v[184:187], v[228:231], v[88:91]
	v_mfma_f32_16x16x32_bf16 v[44:47], v[176:179], v[192:195], v[44:47]
	v_mfma_f32_16x16x32_bf16 v[60:63], v[176:179], v[206:209], v[60:63]
	v_mfma_f32_16x16x32_bf16 v[76:79], v[176:179], v[214:217], v[76:79]
	s_setprio 0
	s_barrier
	ds_read_b128 v[236:239], v169
	ds_read_b128 v[240:243], v169 offset:1024
	ds_read_b128 v[244:247], v169 offset:2048
	ds_read_b128 v[248:251], v169 offset:3072
	s_barrier
	s_waitcnt lgkmcnt(0)
	s_setprio 1
	s_waitcnt lgkmcnt(0)
	v_mfma_f32_16x16x32_bf16 v[36:39], v[244:247], v[188:191], v[36:39]
	v_mfma_f32_16x16x32_bf16 v[32:35], v[236:239], v[188:191], v[32:35]
	v_mfma_f32_16x16x32_bf16 v[188:191], v[248:251], v[192:195], v[36:39]
	v_mfma_f32_16x16x32_bf16 v[36:39], v[236:239], v[202:205], v[48:51]
	v_mfma_f32_16x16x32_bf16 v[48:51], v[240:243], v[206:209], v[36:39]
	v_mfma_f32_16x16x32_bf16 v[36:39], v[244:247], v[202:205], v[52:55]
	v_mfma_f32_16x16x32_bf16 v[32:35], v[240:243], v[192:195], v[32:35]
	v_mfma_f32_16x16x32_bf16 v[192:195], v[248:251], v[206:209], v[36:39]
	v_mfma_f32_16x16x32_bf16 v[36:39], v[236:239], v[210:213], v[64:67]
	v_mfma_f32_16x16x32_bf16 v[64:67], v[240:243], v[214:217], v[36:39]
	v_mfma_f32_16x16x32_bf16 v[36:39], v[244:247], v[210:213], v[68:71]
	v_mfma_f32_16x16x32_bf16 v[202:205], v[248:251], v[214:217], v[36:39]
	v_mfma_f32_16x16x32_bf16 v[36:39], v[236:239], v[218:221], v[80:83]
	v_mfma_f32_16x16x32_bf16 v[80:83], v[240:243], v[228:231], v[36:39]
	v_mfma_f32_16x16x32_bf16 v[36:39], v[244:247], v[218:221], v[84:87]
	v_mfma_f32_16x16x32_bf16 v[206:209], v[248:251], v[228:231], v[36:39]
	s_setprio 0
	s_barrier
	s_nop 4
	ds_read_b128 v[36:39], v166 offset:16384
	ds_read_b128 v[52:55], v166 offset:17408
	ds_read_b128 v[68:71], v165 offset:16384
	ds_read_b128 v[84:87], v165 offset:17408
	ds_read_b128 v[210:213], v163 offset:16384
	ds_read_b128 v[214:217], v163 offset:17408
	ds_read_b128 v[218:221], v162 offset:16384
	ds_read_b128 v[228:231], v162 offset:17408
	s_waitcnt vmcnt(4)
	s_barrier
	s_waitcnt lgkmcnt(0)
	s_setprio 1
	s_waitcnt lgkmcnt(0)
	v_mfma_f32_16x16x32_bf16 v[108:111], v[172:175], v[36:39], v[108:111]
	v_mfma_f32_16x16x32_bf16 v[222:225], v[176:179], v[52:55], v[108:111]
	v_mfma_f32_16x16x32_bf16 v[108:111], v[172:175], v[68:71], v[124:127]
	v_mfma_f32_16x16x32_bf16 v[124:127], v[176:179], v[84:87], v[108:111]
	v_mfma_f32_16x16x32_bf16 v[108:111], v[180:183], v[68:71], v[120:123]
	v_mfma_f32_16x16x32_bf16 v[120:123], v[184:187], v[84:87], v[108:111]
	v_mfma_f32_16x16x32_bf16 v[108:111], v[172:175], v[210:213], v[140:143]
	v_mfma_f32_16x16x32_bf16 v[140:143], v[176:179], v[214:217], v[108:111]
	v_mfma_f32_16x16x32_bf16 v[108:111], v[180:183], v[210:213], v[136:139]
	v_mfma_f32_16x16x32_bf16 v[136:139], v[184:187], v[214:217], v[108:111]
	v_mfma_f32_16x16x32_bf16 v[108:111], v[172:175], v[218:221], v[156:159]
	v_mfma_f32_16x16x32_bf16 v[104:107], v[180:183], v[36:39], v[104:107]
	v_mfma_f32_16x16x32_bf16 v[156:159], v[176:179], v[228:231], v[108:111]
	v_mfma_f32_16x16x32_bf16 v[108:111], v[180:183], v[218:221], v[152:155]
	v_mfma_f32_16x16x32_bf16 v[104:107], v[184:187], v[52:55], v[104:107]
	v_mfma_f32_16x16x32_bf16 v[152:155], v[184:187], v[228:231], v[108:111]
	s_setprio 0
	s_setprio 1
	v_mfma_f32_16x16x32_bf16 v[96:99], v[236:239], v[36:39], v[96:99]
	v_mfma_f32_16x16x32_bf16 v[36:39], v[244:247], v[36:39], v[100:103]
	v_mfma_f32_16x16x32_bf16 v[172:175], v[248:251], v[52:55], v[36:39]
	v_mfma_f32_16x16x32_bf16 v[36:39], v[236:239], v[68:71], v[112:115]
	v_mfma_f32_16x16x32_bf16 v[112:115], v[240:243], v[84:87], v[36:39]
	v_mfma_f32_16x16x32_bf16 v[36:39], v[244:247], v[68:71], v[116:119]
	v_mfma_f32_16x16x32_bf16 v[180:183], v[248:251], v[84:87], v[36:39]
	v_mfma_f32_16x16x32_bf16 v[36:39], v[236:239], v[210:213], v[128:131]
	v_mfma_f32_16x16x32_bf16 v[128:131], v[240:243], v[214:217], v[36:39]
	v_mfma_f32_16x16x32_bf16 v[36:39], v[244:247], v[210:213], v[132:135]
	v_mfma_f32_16x16x32_bf16 v[184:187], v[248:251], v[214:217], v[36:39]
	v_mfma_f32_16x16x32_bf16 v[36:39], v[236:239], v[218:221], v[144:147]
	v_mfma_f32_16x16x32_bf16 v[96:99], v[240:243], v[52:55], v[96:99]
	v_mfma_f32_16x16x32_bf16 v[144:147], v[240:243], v[228:231], v[36:39]
	v_mfma_f32_16x16x32_bf16 v[36:39], v[244:247], v[218:221], v[148:151]
	v_mfma_f32_16x16x32_bf16 v[210:213], v[248:251], v[228:231], v[36:39]
	s_setprio 0
	s_barrier
	ds_read_b128 v[148:151], v168
	ds_read_b128 v[214:217], v168 offset:1024
	ds_read_b128 v[218:221], v168 offset:2048
	ds_read_b128 v[228:231], v168 offset:3072
	ds_read_b128 v[100:103], v166 offset:32768
	ds_read_b128 v[108:111], v166 offset:33792
	ds_read_b128 v[116:119], v165 offset:32768
	ds_read_b128 v[132:135], v165 offset:33792
	ds_read_b128 v[236:239], v163 offset:32768
	ds_read_b128 v[240:243], v163 offset:33792
	ds_read_b128 v[244:247], v162 offset:32768
	ds_read_b128 v[248:251], v162 offset:33792
	s_waitcnt vmcnt(2)
	s_barrier
	s_waitcnt lgkmcnt(0)
	s_setprio 1
	s_waitcnt lgkmcnt(0)
	v_mfma_f32_16x16x32_bf16 v[36:39], v[148:151], v[100:103], v[44:47]
	v_mfma_f32_16x16x32_bf16 v[44:47], v[148:151], v[116:119], v[60:63]
	v_mfma_f32_16x16x32_bf16 v[52:55], v[214:217], v[132:135], v[44:47]
	v_mfma_f32_16x16x32_bf16 v[44:47], v[218:221], v[116:119], v[56:59]
	v_mfma_f32_16x16x32_bf16 v[56:59], v[228:231], v[132:135], v[44:47]
	v_mfma_f32_16x16x32_bf16 v[44:47], v[148:151], v[236:239], v[76:79]
	v_mfma_f32_16x16x32_bf16 v[68:71], v[214:217], v[240:243], v[44:47]
	v_mfma_f32_16x16x32_bf16 v[44:47], v[218:221], v[236:239], v[72:75]
	v_mfma_f32_16x16x32_bf16 v[72:75], v[228:231], v[240:243], v[44:47]
	v_mfma_f32_16x16x32_bf16 v[44:47], v[148:151], v[244:247], v[92:95]
	v_mfma_f32_16x16x32_bf16 v[40:43], v[218:221], v[100:103], v[40:43]
	v_mfma_f32_16x16x32_bf16 v[84:87], v[214:217], v[248:251], v[44:47]
	v_mfma_f32_16x16x32_bf16 v[44:47], v[218:221], v[244:247], v[88:91]
	v_mfma_f32_16x16x32_bf16 v[36:39], v[214:217], v[108:111], v[36:39]
	v_mfma_f32_16x16x32_bf16 v[40:43], v[228:231], v[108:111], v[40:43]
	v_mfma_f32_16x16x32_bf16 v[88:91], v[228:231], v[248:251], v[44:47]
	s_setprio 0
	s_barrier
	s_nop 2
	ds_read_b128 v[44:47], v167
	ds_read_b128 v[60:63], v167 offset:1024
	ds_read_b128 v[76:79], v167 offset:2048
	ds_read_b128 v[232:235], v167 offset:3072
	s_waitcnt vmcnt(0)
	s_barrier
	s_waitcnt lgkmcnt(0)
	s_setprio 1
	s_waitcnt lgkmcnt(0)
	v_mfma_f32_16x16x32_bf16 v[92:95], v[76:79], v[100:103], v[188:191]
	v_mfma_f32_16x16x32_bf16 v[176:179], v[232:235], v[108:111], v[92:95]
	v_mfma_f32_16x16x32_bf16 v[92:95], v[76:79], v[116:119], v[192:195]
	v_mfma_f32_16x16x32_bf16 v[32:35], v[44:47], v[100:103], v[32:35]
	v_mfma_f32_16x16x32_bf16 v[48:51], v[44:47], v[116:119], v[48:51]
	v_mfma_f32_16x16x32_bf16 v[168:171], v[232:235], v[132:135], v[92:95]
	v_mfma_f32_16x16x32_bf16 v[64:67], v[44:47], v[236:239], v[64:67]
	v_mfma_f32_16x16x32_bf16 v[92:95], v[76:79], v[236:239], v[202:205]
	v_mfma_f32_16x16x32_bf16 v[80:83], v[44:47], v[244:247], v[80:83]
	v_mfma_f32_16x16x32_bf16 v[100:103], v[76:79], v[244:247], v[206:209]
	v_mfma_f32_16x16x32_bf16 v[32:35], v[60:63], v[108:111], v[32:35]
	v_mfma_f32_16x16x32_bf16 v[48:51], v[60:63], v[132:135], v[48:51]
	v_mfma_f32_16x16x32_bf16 v[64:67], v[60:63], v[240:243], v[64:67]
	v_mfma_f32_16x16x32_bf16 v[92:95], v[232:235], v[240:243], v[92:95]
	v_mfma_f32_16x16x32_bf16 v[80:83], v[60:63], v[248:251], v[80:83]
	v_mfma_f32_16x16x32_bf16 v[108:111], v[232:235], v[248:251], v[100:103]
	s_setprio 0
	s_barrier
	ds_read_b128 v[188:191], v166 offset:49152
	ds_read_b128 v[192:195], v166 offset:50176
	ds_read_b128 v[202:205], v165 offset:49152
	ds_read_b128 v[206:209], v165 offset:50176
	ds_read_b128 v[236:239], v163 offset:49152
	ds_read_b128 v[240:243], v163 offset:50176
	ds_read_b128 v[244:247], v162 offset:49152
	ds_read_b128 v[160:163], v162 offset:50176
	s_barrier
	s_waitcnt lgkmcnt(0)
	s_setprio 1
	s_waitcnt lgkmcnt(0)
	v_mfma_f32_16x16x32_bf16 v[116:119], v[148:151], v[202:205], v[124:127]
	v_mfma_f32_16x16x32_bf16 v[124:127], v[148:151], v[236:239], v[140:143]
	v_mfma_f32_16x16x32_bf16 v[132:135], v[214:217], v[240:243], v[124:127]
	v_mfma_f32_16x16x32_bf16 v[124:127], v[218:221], v[236:239], v[136:139]
	v_mfma_f32_16x16x32_bf16 v[136:139], v[228:231], v[240:243], v[124:127]
	v_mfma_f32_16x16x32_bf16 v[124:127], v[148:151], v[244:247], v[156:159]
	v_mfma_f32_16x16x32_bf16 v[100:103], v[148:151], v[188:191], v[222:225]
	v_mfma_f32_16x16x32_bf16 v[104:107], v[218:221], v[188:191], v[104:107]
	v_mfma_f32_16x16x32_bf16 v[120:123], v[218:221], v[202:205], v[120:123]
	v_mfma_f32_16x16x32_bf16 v[148:151], v[214:217], v[160:163], v[124:127]
	v_mfma_f32_16x16x32_bf16 v[124:127], v[218:221], v[244:247], v[152:155]
	v_mfma_f32_16x16x32_bf16 v[100:103], v[214:217], v[192:195], v[100:103]
	v_mfma_f32_16x16x32_bf16 v[104:107], v[228:231], v[192:195], v[104:107]
	v_mfma_f32_16x16x32_bf16 v[116:119], v[214:217], v[206:209], v[116:119]
	v_mfma_f32_16x16x32_bf16 v[120:123], v[228:231], v[206:209], v[120:123]
	v_mfma_f32_16x16x32_bf16 v[152:155], v[228:231], v[160:163], v[124:127]
	s_setprio 0
	s_setprio 1
	v_mfma_f32_16x16x32_bf16 v[96:99], v[44:47], v[188:191], v[96:99]
	v_mfma_f32_16x16x32_bf16 v[112:115], v[44:47], v[202:205], v[112:115]
	v_mfma_f32_16x16x32_bf16 v[128:131], v[44:47], v[236:239], v[128:131]
	v_mfma_f32_16x16x32_bf16 v[44:47], v[44:47], v[244:247], v[144:147]
	v_mfma_f32_16x16x32_bf16 v[124:127], v[76:79], v[188:191], v[172:175]
	v_mfma_f32_16x16x32_bf16 v[140:143], v[76:79], v[202:205], v[180:183]
	v_mfma_f32_16x16x32_bf16 v[156:159], v[76:79], v[236:239], v[184:187]
	v_mfma_f32_16x16x32_bf16 v[144:147], v[60:63], v[160:163], v[44:47]
	v_mfma_f32_16x16x32_bf16 v[44:47], v[76:79], v[244:247], v[210:213]
	v_mfma_f32_16x16x32_bf16 v[96:99], v[60:63], v[192:195], v[96:99]
	v_mfma_f32_16x16x32_bf16 v[124:127], v[232:235], v[192:195], v[124:127]
	v_mfma_f32_16x16x32_bf16 v[112:115], v[60:63], v[206:209], v[112:115]
	v_mfma_f32_16x16x32_bf16 v[140:143], v[232:235], v[206:209], v[140:143]
	v_mfma_f32_16x16x32_bf16 v[128:131], v[60:63], v[240:243], v[128:131]
	v_mfma_f32_16x16x32_bf16 v[156:159], v[232:235], v[240:243], v[156:159]
	v_mfma_f32_16x16x32_bf16 v[160:163], v[232:235], v[160:163], v[44:47]
	s_setprio 0
	s_movk_i32 s6, 0x100
	v_cmp_gt_u32_e32 vcc, s6, v164
	s_barrier
	s_and_saveexec_b64 s[6:7], vcc
	s_cbranch_execz .LBB0_317
	s_barrier

.LBB0_568:
	ds_read_b128 v[140:143], v129
	ds_read_b128 v[144:147], v129 offset:1024
	ds_read_b128 v[148:151], v129 offset:2048
	ds_read_b128 v[152:155], v129 offset:3072
	s_add_u32 s28, s8, s10
	s_addc_u32 s29, s9, s11
	ds_read_b128 v[156:159], v136
	ds_read_b128 v[160:163], v136 offset:1024
	ds_read_b128 v[164:167], v135
	ds_read_b128 v[168:171], v135 offset:1024
	ds_read_b128 v[172:175], v134
	ds_read_b128 v[176:179], v134 offset:1024
	ds_read_b128 v[180:183], v133
	ds_read_b128 v[184:187], v133 offset:1024
	s_add_i32 s39, s68, 0xc000
	s_mov_b32 m0, s39
	s_add_i32 s38, s68, 0xe000
	s_add_u32 s98, s28, s44
	s_addc_u32 s99, s29, s45
	global_load_lds_dwordx4 v128, s[98:99]
	s_mov_b32 m0, s38
	s_nop 0
	global_load_lds_dwordx4 v130, s[98:99]
	s_waitcnt lgkmcnt(8)
	s_barrier
	s_waitcnt lgkmcnt(7)
	v_mfma_f32_16x16x32_bf16 v[124:127], v[140:143], v[156:159], v[124:127]
	v_mfma_f32_16x16x32_bf16 v[120:123], v[148:151], v[156:159], v[120:123]
	s_waitcnt lgkmcnt(5)
	v_mfma_f32_16x16x32_bf16 v[116:119], v[140:143], v[164:167], v[116:119]
	v_mfma_f32_16x16x32_bf16 v[112:115], v[148:151], v[164:167], v[112:115]
	s_waitcnt lgkmcnt(3)
	v_mfma_f32_16x16x32_bf16 v[108:111], v[140:143], v[172:175], v[108:111]
	v_mfma_f32_16x16x32_bf16 v[104:107], v[148:151], v[172:175], v[104:107]
	s_waitcnt lgkmcnt(1)
	v_mfma_f32_16x16x32_bf16 v[100:103], v[140:143], v[180:183], v[100:103]
	v_mfma_f32_16x16x32_bf16 v[96:99], v[148:151], v[180:183], v[96:99]
	v_mfma_f32_16x16x32_bf16 v[124:127], v[144:147], v[160:163], v[124:127]
	v_mfma_f32_16x16x32_bf16 v[120:123], v[152:155], v[160:163], v[120:123]
	v_mfma_f32_16x16x32_bf16 v[116:119], v[144:147], v[168:171], v[116:119]
	v_mfma_f32_16x16x32_bf16 v[112:115], v[152:155], v[168:171], v[112:115]
	v_mfma_f32_16x16x32_bf16 v[108:111], v[144:147], v[176:179], v[108:111]
	v_mfma_f32_16x16x32_bf16 v[104:107], v[152:155], v[176:179], v[104:107]
	s_waitcnt lgkmcnt(0)
	v_mfma_f32_16x16x32_bf16 v[100:103], v[144:147], v[184:187], v[100:103]
	v_mfma_f32_16x16x32_bf16 v[96:99], v[152:155], v[184:187], v[96:99]
	s_barrier
	s_add_u32 s56, s6, s10
	s_addc_u32 s57, s7, s11
	ds_read_b128 v[188:191], v139
	ds_read_b128 v[192:195], v139 offset:1024
	ds_read_b128 v[202:205], v139 offset:2048
	ds_read_b128 v[206:209], v139 offset:3072
	s_add_i32 m0, s68, 0x10000
	s_add_u32 s98, s56, s0
	s_addc_u32 s99, s57, s1
	global_load_lds_dwordx4 v128, s[98:99]
	s_add_i32 m0, s68, 0x12000
	s_nop 0
	global_load_lds_dwordx4 v130, s[98:99]
	s_barrier
	s_waitcnt lgkmcnt(3)
	v_mfma_f32_16x16x32_bf16 v[92:95], v[188:191], v[156:159], v[92:95]
	s_waitcnt lgkmcnt(1)
	v_mfma_f32_16x16x32_bf16 v[88:91], v[202:205], v[156:159], v[88:91]
	v_mfma_f32_16x16x32_bf16 v[84:87], v[188:191], v[164:167], v[84:87]
	v_mfma_f32_16x16x32_bf16 v[80:83], v[202:205], v[164:167], v[80:83]
	v_mfma_f32_16x16x32_bf16 v[76:79], v[188:191], v[172:175], v[76:79]
	v_mfma_f32_16x16x32_bf16 v[72:75], v[202:205], v[172:175], v[72:75]
	v_mfma_f32_16x16x32_bf16 v[68:71], v[188:191], v[180:183], v[68:71]
	v_mfma_f32_16x16x32_bf16 v[64:67], v[202:205], v[180:183], v[64:67]
	v_mfma_f32_16x16x32_bf16 v[92:95], v[192:195], v[160:163], v[92:95]
	s_waitcnt lgkmcnt(0)
	v_mfma_f32_16x16x32_bf16 v[88:91], v[206:209], v[160:163], v[88:91]
	v_mfma_f32_16x16x32_bf16 v[84:87], v[192:195], v[168:171], v[84:87]
	v_mfma_f32_16x16x32_bf16 v[80:83], v[206:209], v[168:171], v[80:83]
	v_mfma_f32_16x16x32_bf16 v[76:79], v[192:195], v[176:179], v[76:79]
	v_mfma_f32_16x16x32_bf16 v[72:75], v[206:209], v[176:179], v[72:75]
	v_mfma_f32_16x16x32_bf16 v[68:71], v[192:195], v[184:187], v[68:71]
	v_mfma_f32_16x16x32_bf16 v[64:67], v[206:209], v[184:187], v[64:67]
	s_barrier
	ds_read_b128 v[156:159], v136 offset:16384
	ds_read_b128 v[160:163], v136 offset:17408
	ds_read_b128 v[164:167], v135 offset:16384
	ds_read_b128 v[168:171], v135 offset:17408
	ds_read_b128 v[172:175], v134 offset:16384
	ds_read_b128 v[176:179], v134 offset:17408
	ds_read_b128 v[180:183], v133 offset:16384
	ds_read_b128 v[184:187], v133 offset:17408
	s_mov_b32 m0, s68
	s_add_u32 s98, s28, s0
	s_addc_u32 s99, s29, s1
	global_load_lds_dwordx4 v128, s[98:99]
	s_add_i32 m0, s68, 0x2000
	s_nop 0
	global_load_lds_dwordx4 v130, s[98:99]
	s_barrier
	s_waitcnt lgkmcnt(7)
	v_mfma_f32_16x16x32_bf16 v[60:63], v[140:143], v[156:159], v[60:63]
	v_mfma_f32_16x16x32_bf16 v[56:59], v[148:151], v[156:159], v[56:59]
	s_waitcnt lgkmcnt(5)
	v_mfma_f32_16x16x32_bf16 v[52:55], v[140:143], v[164:167], v[52:55]
	v_mfma_f32_16x16x32_bf16 v[48:51], v[148:151], v[164:167], v[48:51]
	s_waitcnt lgkmcnt(3)
	v_mfma_f32_16x16x32_bf16 v[44:47], v[140:143], v[172:175], v[44:47]
	v_mfma_f32_16x16x32_bf16 v[40:43], v[148:151], v[172:175], v[40:43]
	s_waitcnt lgkmcnt(1)
	v_mfma_f32_16x16x32_bf16 v[36:39], v[140:143], v[180:183], v[36:39]
	v_mfma_f32_16x16x32_bf16 v[32:35], v[148:151], v[180:183], v[32:35]
	v_mfma_f32_16x16x32_bf16 v[60:63], v[144:147], v[160:163], v[60:63]
	v_mfma_f32_16x16x32_bf16 v[56:59], v[152:155], v[160:163], v[56:59]
	v_mfma_f32_16x16x32_bf16 v[52:55], v[144:147], v[168:171], v[52:55]
	v_mfma_f32_16x16x32_bf16 v[48:51], v[152:155], v[168:171], v[48:51]
	v_mfma_f32_16x16x32_bf16 v[44:47], v[144:147], v[176:179], v[44:47]
	v_mfma_f32_16x16x32_bf16 v[40:43], v[152:155], v[176:179], v[40:43]
	s_waitcnt lgkmcnt(0)
	v_mfma_f32_16x16x32_bf16 v[36:39], v[144:147], v[184:187], v[36:39]
	v_mfma_f32_16x16x32_bf16 v[32:35], v[152:155], v[184:187], v[32:35]
	s_barrier
	s_add_i32 m0, s68, 0x14000
	s_add_u32 s98, s56, s46
	s_addc_u32 s99, s57, s47
	global_load_lds_dwordx4 v128, s[98:99]
	s_add_i32 m0, s68, 0x16000
	s_nop 0
	global_load_lds_dwordx4 v130, s[98:99]
	s_waitcnt vmcnt(6)
	s_barrier
	v_mfma_f32_16x16x32_bf16 v[28:31], v[188:191], v[156:159], v[28:31]
	v_mfma_f32_16x16x32_bf16 v[24:27], v[202:205], v[156:159], v[24:27]
	v_mfma_f32_16x16x32_bf16 v[20:23], v[188:191], v[164:167], v[20:23]
	v_mfma_f32_16x16x32_bf16 v[16:19], v[202:205], v[164:167], v[16:19]
	v_mfma_f32_16x16x32_bf16 v[12:15], v[188:191], v[172:175], v[12:15]
	v_mfma_f32_16x16x32_bf16 v[8:11], v[202:205], v[172:175], v[8:11]
	v_mfma_f32_16x16x32_bf16 v[4:7], v[188:191], v[180:183], v[4:7]
	v_mfma_f32_16x16x32_bf16 v[0:3], v[202:205], v[180:183], v[0:3]
	v_mfma_f32_16x16x32_bf16 v[28:31], v[192:195], v[160:163], v[28:31]
	v_mfma_f32_16x16x32_bf16 v[24:27], v[206:209], v[160:163], v[24:27]
	v_mfma_f32_16x16x32_bf16 v[20:23], v[192:195], v[168:171], v[20:23]
	v_mfma_f32_16x16x32_bf16 v[16:19], v[206:209], v[168:171], v[16:19]
	v_mfma_f32_16x16x32_bf16 v[12:15], v[192:195], v[176:179], v[12:15]
	v_mfma_f32_16x16x32_bf16 v[8:11], v[206:209], v[176:179], v[8:11]
	v_mfma_f32_16x16x32_bf16 v[4:7], v[192:195], v[184:187], v[4:7]
	v_mfma_f32_16x16x32_bf16 v[0:3], v[206:209], v[184:187], v[0:3]
	s_barrier
	ds_read_b128 v[140:143], v138
	ds_read_b128 v[144:147], v138 offset:1024
	ds_read_b128 v[148:151], v138 offset:2048
	ds_read_b128 v[152:155], v138 offset:3072
	ds_read_b128 v[156:159], v136 offset:32768
	ds_read_b128 v[160:163], v136 offset:33792
	ds_read_b128 v[164:167], v135 offset:32768
	ds_read_b128 v[168:171], v135 offset:33792
	ds_read_b128 v[172:175], v134 offset:32768
	ds_read_b128 v[176:179], v134 offset:33792
	ds_read_b128 v[180:183], v133 offset:32768
	ds_read_b128 v[184:187], v133 offset:33792
	s_add_i32 m0, s68, 0x4000
	s_add_u32 s98, s28, s46
	s_addc_u32 s99, s29, s47
	global_load_lds_dwordx4 v128, s[98:99]
	s_add_i32 m0, s68, 0x6000
	s_nop 0
	global_load_lds_dwordx4 v130, s[98:99]
	s_waitcnt lgkmcnt(8)
	s_barrier
	s_waitcnt lgkmcnt(7)
	v_mfma_f32_16x16x32_bf16 v[124:127], v[140:143], v[156:159], v[124:127]
	v_mfma_f32_16x16x32_bf16 v[120:123], v[148:151], v[156:159], v[120:123]
	s_waitcnt lgkmcnt(5)
	v_mfma_f32_16x16x32_bf16 v[116:119], v[140:143], v[164:167], v[116:119]
	v_mfma_f32_16x16x32_bf16 v[112:115], v[148:151], v[164:167], v[112:115]
	s_waitcnt lgkmcnt(3)
	v_mfma_f32_16x16x32_bf16 v[108:111], v[140:143], v[172:175], v[108:111]
	v_mfma_f32_16x16x32_bf16 v[104:107], v[148:151], v[172:175], v[104:107]
	s_waitcnt lgkmcnt(1)
	v_mfma_f32_16x16x32_bf16 v[100:103], v[140:143], v[180:183], v[100:103]
	v_mfma_f32_16x16x32_bf16 v[96:99], v[148:151], v[180:183], v[96:99]
	v_mfma_f32_16x16x32_bf16 v[124:127], v[144:147], v[160:163], v[124:127]
	v_mfma_f32_16x16x32_bf16 v[120:123], v[152:155], v[160:163], v[120:123]
	v_mfma_f32_16x16x32_bf16 v[116:119], v[144:147], v[168:171], v[116:119]
	v_mfma_f32_16x16x32_bf16 v[112:115], v[152:155], v[168:171], v[112:115]
	v_mfma_f32_16x16x32_bf16 v[108:111], v[144:147], v[176:179], v[108:111]
	v_mfma_f32_16x16x32_bf16 v[104:107], v[152:155], v[176:179], v[104:107]
	s_waitcnt lgkmcnt(0)
	v_mfma_f32_16x16x32_bf16 v[100:103], v[144:147], v[184:187], v[100:103]
	v_mfma_f32_16x16x32_bf16 v[96:99], v[152:155], v[184:187], v[96:99]
	s_barrier
	ds_read_b128 v[188:191], v137
	ds_read_b128 v[192:195], v137 offset:1024
	ds_read_b128 v[202:205], v137 offset:2048
	ds_read_b128 v[206:209], v137 offset:3072
	s_mov_b32 m0, s69
	s_add_u32 s98, s56, s30
	s_addc_u32 s99, s57, s31
	global_load_lds_dwordx4 v128, s[98:99]
	s_mov_b32 m0, s70
	s_nop 0
	global_load_lds_dwordx4 v130, s[98:99]
	s_barrier
	s_waitcnt lgkmcnt(3)
	v_mfma_f32_16x16x32_bf16 v[92:95], v[188:191], v[156:159], v[92:95]
	s_waitcnt lgkmcnt(1)
	v_mfma_f32_16x16x32_bf16 v[88:91], v[202:205], v[156:159], v[88:91]
	v_mfma_f32_16x16x32_bf16 v[84:87], v[188:191], v[164:167], v[84:87]
	v_mfma_f32_16x16x32_bf16 v[80:83], v[202:205], v[164:167], v[80:83]
	v_mfma_f32_16x16x32_bf16 v[76:79], v[188:191], v[172:175], v[76:79]
	v_mfma_f32_16x16x32_bf16 v[72:75], v[202:205], v[172:175], v[72:75]
	v_mfma_f32_16x16x32_bf16 v[68:71], v[188:191], v[180:183], v[68:71]
	v_mfma_f32_16x16x32_bf16 v[64:67], v[202:205], v[180:183], v[64:67]
	v_mfma_f32_16x16x32_bf16 v[92:95], v[192:195], v[160:163], v[92:95]
	s_waitcnt lgkmcnt(0)
	v_mfma_f32_16x16x32_bf16 v[88:91], v[206:209], v[160:163], v[88:91]
	v_mfma_f32_16x16x32_bf16 v[84:87], v[192:195], v[168:171], v[84:87]
	v_mfma_f32_16x16x32_bf16 v[80:83], v[206:209], v[168:171], v[80:83]
	v_mfma_f32_16x16x32_bf16 v[76:79], v[192:195], v[176:179], v[76:79]
	v_mfma_f32_16x16x32_bf16 v[72:75], v[206:209], v[176:179], v[72:75]
	v_mfma_f32_16x16x32_bf16 v[68:71], v[192:195], v[184:187], v[68:71]
	v_mfma_f32_16x16x32_bf16 v[64:67], v[206:209], v[184:187], v[64:67]
	v_mov_b32_e32 v210, v130
	s_barrier
	ds_read_b128 v[156:159], v136 offset:49152
	ds_read_b128 v[160:163], v136 offset:50176
	ds_read_b128 v[164:167], v135 offset:49152
	ds_read_b128 v[168:171], v135 offset:50176
	ds_read_b128 v[172:175], v134 offset:49152
	ds_read_b128 v[176:179], v134 offset:50176
	ds_read_b128 v[180:183], v133 offset:49152
	ds_read_b128 v[184:187], v133 offset:50176
	v_mov_b32_e32 v211, v197
	s_mov_b32 m0, s71
	s_add_u32 s98, s28, s30
	s_addc_u32 s99, s29, s31
	global_load_lds_dwordx4 v128, s[98:99]
	s_mov_b32 m0, s33
	s_nop 0
	global_load_lds_dwordx4 v130, s[98:99]
	s_barrier
	s_waitcnt lgkmcnt(7)
	v_mfma_f32_16x16x32_bf16 v[60:63], v[140:143], v[156:159], v[60:63]
	v_mfma_f32_16x16x32_bf16 v[56:59], v[148:151], v[156:159], v[56:59]
	s_waitcnt lgkmcnt(5)
	v_mfma_f32_16x16x32_bf16 v[52:55], v[140:143], v[164:167], v[52:55]
	v_mfma_f32_16x16x32_bf16 v[48:51], v[148:151], v[164:167], v[48:51]
	s_waitcnt lgkmcnt(3)
	v_mfma_f32_16x16x32_bf16 v[44:47], v[140:143], v[172:175], v[44:47]
	v_mfma_f32_16x16x32_bf16 v[40:43], v[148:151], v[172:175], v[40:43]
	s_waitcnt lgkmcnt(1)
	v_mfma_f32_16x16x32_bf16 v[36:39], v[140:143], v[180:183], v[36:39]
	v_mfma_f32_16x16x32_bf16 v[32:35], v[148:151], v[180:183], v[32:35]
	v_mfma_f32_16x16x32_bf16 v[60:63], v[144:147], v[160:163], v[60:63]
	v_mfma_f32_16x16x32_bf16 v[56:59], v[152:155], v[160:163], v[56:59]
	v_mfma_f32_16x16x32_bf16 v[52:55], v[144:147], v[168:171], v[52:55]
	v_mfma_f32_16x16x32_bf16 v[48:51], v[152:155], v[168:171], v[48:51]
	v_mfma_f32_16x16x32_bf16 v[44:47], v[144:147], v[176:179], v[44:47]
	v_mfma_f32_16x16x32_bf16 v[40:43], v[152:155], v[176:179], v[40:43]
	s_waitcnt lgkmcnt(0)
	v_mfma_f32_16x16x32_bf16 v[36:39], v[144:147], v[184:187], v[36:39]
	v_mfma_f32_16x16x32_bf16 v[32:35], v[152:155], v[184:187], v[32:35]
	s_barrier
	v_mov_b32_e32 v196, v128
	s_mov_b32 m0, s72
	s_add_u32 s98, s56, s48
	s_addc_u32 s99, s57, s49
	global_load_lds_dwordx4 v128, s[98:99]
	s_mov_b32 m0, s36
	s_nop 0
	global_load_lds_dwordx4 v130, s[98:99]
	s_waitcnt vmcnt(6)
	s_barrier
	v_mfma_f32_16x16x32_bf16 v[28:31], v[188:191], v[156:159], v[28:31]
	v_mfma_f32_16x16x32_bf16 v[24:27], v[202:205], v[156:159], v[24:27]
	v_mfma_f32_16x16x32_bf16 v[20:23], v[188:191], v[164:167], v[20:23]
	v_mfma_f32_16x16x32_bf16 v[16:19], v[202:205], v[164:167], v[16:19]
	v_mfma_f32_16x16x32_bf16 v[12:15], v[188:191], v[172:175], v[12:15]
	v_mfma_f32_16x16x32_bf16 v[8:11], v[202:205], v[172:175], v[8:11]
	v_mfma_f32_16x16x32_bf16 v[4:7], v[188:191], v[180:183], v[4:7]
	v_mfma_f32_16x16x32_bf16 v[0:3], v[202:205], v[180:183], v[0:3]
	v_mfma_f32_16x16x32_bf16 v[28:31], v[192:195], v[160:163], v[28:31]
	v_mfma_f32_16x16x32_bf16 v[24:27], v[206:209], v[160:163], v[24:27]
	v_mfma_f32_16x16x32_bf16 v[20:23], v[192:195], v[168:171], v[20:23]
	v_mfma_f32_16x16x32_bf16 v[16:19], v[206:209], v[168:171], v[16:19]
	v_mfma_f32_16x16x32_bf16 v[12:15], v[192:195], v[176:179], v[12:15]
	v_mfma_f32_16x16x32_bf16 v[8:11], v[206:209], v[176:179], v[8:11]
	v_mfma_f32_16x16x32_bf16 v[4:7], v[192:195], v[184:187], v[4:7]
	v_mfma_f32_16x16x32_bf16 v[0:3], v[206:209], v[184:187], v[0:3]
	s_add_i32 s37, s37, 2
	s_add_u32 s10, s10, 0x100
	s_addc_u32 s11, s11, 0
	s_cmp_lt_u32 s37, 28
	s_barrier
	s_cbranch_scc1 .LBB0_568
	s_lshl_b64 s[4:5], s[4:5], 12
	s_add_u32 s4, s67, s4
	s_addc_u32 s5, s53, s5
	ds_read_b128 v[140:143], v129
	ds_read_b128 v[144:147], v129 offset:1024
	ds_read_b128 v[148:151], v129 offset:2048
	ds_read_b128 v[152:155], v129 offset:3072
	ds_read_b128 v[156:159], v136
	ds_read_b128 v[160:163], v136 offset:1024
	ds_read_b128 v[164:167], v135
	ds_read_b128 v[168:171], v135 offset:1024
	ds_read_b128 v[172:175], v134
	ds_read_b128 v[176:179], v134 offset:1024
	ds_read_b128 v[180:183], v133
	ds_read_b128 v[184:187], v133 offset:1024
	v_mov_b32_e32 v129, v197
	v_lshl_add_u64 v[128:129], s[4:5], 0, v[128:129]
	s_mov_b64 s[6:7], 0xf80
	s_mov_b32 m0, s39
	v_lshl_add_u64 v[128:129], v[128:129], 0, s[6:7]
	v_mov_b32_e32 v131, v197
	global_load_lds_dwordx4 v[128:129], off
	v_lshl_add_u64 v[128:129], s[4:5], 0, v[130:131]
	v_lshl_add_u64 v[128:129], v[128:129], 0, s[6:7]
	s_mov_b32 m0, s38
	s_nop 0
	global_load_lds_dwordx4 v[128:129], off
	s_barrier
	s_waitcnt lgkmcnt(0)
	s_setprio 1
	s_waitcnt lgkmcnt(0)
	v_mfma_f32_16x16x32_bf16 v[124:127], v[140:143], v[156:159], v[124:127]
	v_mfma_f32_16x16x32_bf16 v[120:123], v[148:151], v[156:159], v[120:123]
	v_mfma_f32_16x16x32_bf16 v[116:119], v[140:143], v[164:167], v[116:119]
	v_mfma_f32_16x16x32_bf16 v[112:115], v[148:151], v[164:167], v[112:115]
	v_mfma_f32_16x16x32_bf16 v[100:103], v[140:143], v[180:183], v[100:103]
	v_mfma_f32_16x16x32_bf16 v[96:99], v[148:151], v[180:183], v[96:99]
	v_mfma_f32_16x16x32_bf16 v[124:127], v[144:147], v[160:163], v[124:127]
	v_mfma_f32_16x16x32_bf16 v[120:123], v[152:155], v[160:163], v[120:123]
	v_mfma_f32_16x16x32_bf16 v[116:119], v[144:147], v[168:171], v[116:119]
	v_mfma_f32_16x16x32_bf16 v[112:115], v[152:155], v[168:171], v[112:115]
	v_mfma_f32_16x16x32_bf16 v[108:111], v[140:143], v[172:175], v[108:111]
	v_mfma_f32_16x16x32_bf16 v[104:107], v[148:151], v[172:175], v[104:107]
	v_mfma_f32_16x16x32_bf16 v[100:103], v[144:147], v[184:187], v[100:103]
	v_mfma_f32_16x16x32_bf16 v[96:99], v[152:155], v[184:187], v[96:99]
	v_mfma_f32_16x16x32_bf16 v[128:131], v[144:147], v[176:179], v[108:111]
	v_mfma_f32_16x16x32_bf16 v[188:191], v[152:155], v[176:179], v[104:107]
	s_setprio 0
	s_barrier
	s_nop 1
	ds_read_b128 v[104:107], v139
	ds_read_b128 v[108:111], v139 offset:1024
	ds_read_b128 v[192:195], v139 offset:2048
	ds_read_b128 v[202:205], v139 offset:3072
	s_barrier
	s_waitcnt lgkmcnt(0)
	s_setprio 1
	s_waitcnt lgkmcnt(0)
	v_mfma_f32_16x16x32_bf16 v[84:87], v[104:107], v[164:167], v[84:87]
	v_mfma_f32_16x16x32_bf16 v[80:83], v[192:195], v[164:167], v[80:83]
	v_mfma_f32_16x16x32_bf16 v[68:71], v[104:107], v[180:183], v[68:71]
	v_mfma_f32_16x16x32_bf16 v[64:67], v[192:195], v[180:183], v[64:67]
	v_mfma_f32_16x16x32_bf16 v[92:95], v[104:107], v[156:159], v[92:95]
	v_mfma_f32_16x16x32_bf16 v[88:91], v[192:195], v[156:159], v[88:91]
	v_mfma_f32_16x16x32_bf16 v[84:87], v[108:111], v[168:171], v[84:87]
	v_mfma_f32_16x16x32_bf16 v[80:83], v[202:205], v[168:171], v[80:83]
	v_mfma_f32_16x16x32_bf16 v[76:79], v[104:107], v[172:175], v[76:79]
	v_mfma_f32_16x16x32_bf16 v[72:75], v[192:195], v[172:175], v[72:75]
	v_mfma_f32_16x16x32_bf16 v[68:71], v[108:111], v[184:187], v[68:71]
	v_mfma_f32_16x16x32_bf16 v[64:67], v[202:205], v[184:187], v[64:67]
	v_mfma_f32_16x16x32_bf16 v[206:209], v[108:111], v[160:163], v[92:95]
	v_mfma_f32_16x16x32_bf16 v[156:159], v[202:205], v[160:163], v[88:91]
	v_mfma_f32_16x16x32_bf16 v[160:163], v[108:111], v[176:179], v[76:79]
	v_mfma_f32_16x16x32_bf16 v[164:167], v[202:205], v[176:179], v[72:75]
	s_setprio 0
	s_barrier
	s_nop 0
	ds_read_b128 v[72:75], v136 offset:16384
	ds_read_b128 v[76:79], v136 offset:17408
	ds_read_b128 v[88:91], v135 offset:16384
	ds_read_b128 v[92:95], v135 offset:17408
	ds_read_b128 v[168:171], v134 offset:16384
	ds_read_b128 v[172:175], v134 offset:17408
	ds_read_b128 v[176:179], v133 offset:16384
	ds_read_b128 v[180:183], v133 offset:17408
	s_waitcnt vmcnt(4)
	s_barrier
	s_waitcnt lgkmcnt(0)
	s_setprio 1
	s_waitcnt lgkmcnt(0)
	v_mfma_f32_16x16x32_bf16 v[60:63], v[140:143], v[72:75], v[60:63]
	v_mfma_f32_16x16x32_bf16 v[56:59], v[148:151], v[72:75], v[56:59]
	v_mfma_f32_16x16x32_bf16 v[52:55], v[140:143], v[88:91], v[52:55]
	v_mfma_f32_16x16x32_bf16 v[48:51], v[148:151], v[88:91], v[48:51]
	v_mfma_f32_16x16x32_bf16 v[36:39], v[140:143], v[176:179], v[36:39]
	v_mfma_f32_16x16x32_bf16 v[32:35], v[148:151], v[176:179], v[32:35]
	v_mfma_f32_16x16x32_bf16 v[60:63], v[144:147], v[76:79], v[60:63]
	v_mfma_f32_16x16x32_bf16 v[56:59], v[152:155], v[76:79], v[56:59]
	v_mfma_f32_16x16x32_bf16 v[52:55], v[144:147], v[92:95], v[52:55]
	v_mfma_f32_16x16x32_bf16 v[48:51], v[152:155], v[92:95], v[48:51]
	v_mfma_f32_16x16x32_bf16 v[44:47], v[140:143], v[168:171], v[44:47]
	v_mfma_f32_16x16x32_bf16 v[40:43], v[148:151], v[168:171], v[40:43]
	v_mfma_f32_16x16x32_bf16 v[36:39], v[144:147], v[180:183], v[36:39]
	v_mfma_f32_16x16x32_bf16 v[32:35], v[152:155], v[180:183], v[32:35]
	v_mfma_f32_16x16x32_bf16 v[184:187], v[144:147], v[172:175], v[44:47]
	v_mfma_f32_16x16x32_bf16 v[210:213], v[152:155], v[172:175], v[40:43]
	s_setprio 0
	s_setprio 1
	v_mfma_f32_16x16x32_bf16 v[20:23], v[104:107], v[88:91], v[20:23]
	v_mfma_f32_16x16x32_bf16 v[16:19], v[192:195], v[88:91], v[16:19]
	v_mfma_f32_16x16x32_bf16 v[4:7], v[104:107], v[176:179], v[4:7]
	v_mfma_f32_16x16x32_bf16 v[0:3], v[192:195], v[176:179], v[0:3]
	v_mfma_f32_16x16x32_bf16 v[28:31], v[104:107], v[72:75], v[28:31]
	v_mfma_f32_16x16x32_bf16 v[24:27], v[192:195], v[72:75], v[24:27]
	v_mfma_f32_16x16x32_bf16 v[20:23], v[108:111], v[92:95], v[20:23]
	v_mfma_f32_16x16x32_bf16 v[16:19], v[202:205], v[92:95], v[16:19]
	v_mfma_f32_16x16x32_bf16 v[12:15], v[104:107], v[168:171], v[12:15]
	v_mfma_f32_16x16x32_bf16 v[8:11], v[192:195], v[168:171], v[8:11]
	v_mfma_f32_16x16x32_bf16 v[4:7], v[108:111], v[180:183], v[4:7]
	v_mfma_f32_16x16x32_bf16 v[0:3], v[202:205], v[180:183], v[0:3]
	v_mfma_f32_16x16x32_bf16 v[140:143], v[108:111], v[76:79], v[28:31]
	v_mfma_f32_16x16x32_bf16 v[144:147], v[202:205], v[76:79], v[24:27]
	v_mfma_f32_16x16x32_bf16 v[148:151], v[108:111], v[172:175], v[12:15]
	v_mfma_f32_16x16x32_bf16 v[152:155], v[202:205], v[172:175], v[8:11]
	s_setprio 0
	s_barrier
	s_nop 0
	ds_read_b128 v[8:11], v138
	ds_read_b128 v[12:15], v138 offset:1024
	ds_read_b128 v[168:171], v138 offset:2048
	ds_read_b128 v[172:175], v138 offset:3072
	ds_read_b128 v[24:27], v136 offset:32768
	ds_read_b128 v[28:31], v136 offset:33792
	ds_read_b128 v[40:43], v135 offset:32768
	ds_read_b128 v[44:47], v135 offset:33792
	ds_read_b128 v[176:179], v134 offset:32768
	ds_read_b128 v[180:183], v134 offset:33792
	ds_read_b128 v[192:195], v133 offset:32768
	ds_read_b128 v[202:205], v133 offset:33792
	s_waitcnt vmcnt(2)
	s_barrier
	s_waitcnt lgkmcnt(0)
	s_setprio 1
	s_waitcnt lgkmcnt(0)
	v_mfma_f32_16x16x32_bf16 v[72:75], v[8:11], v[24:27], v[124:127]
	v_mfma_f32_16x16x32_bf16 v[124:127], v[12:15], v[28:31], v[72:75]
	v_mfma_f32_16x16x32_bf16 v[72:75], v[168:171], v[24:27], v[120:123]
	v_mfma_f32_16x16x32_bf16 v[120:123], v[172:175], v[28:31], v[72:75]
	v_mfma_f32_16x16x32_bf16 v[72:75], v[8:11], v[40:43], v[116:119]
	v_mfma_f32_16x16x32_bf16 v[108:111], v[12:15], v[44:47], v[72:75]
	v_mfma_f32_16x16x32_bf16 v[72:75], v[168:171], v[40:43], v[112:115]
	v_mfma_f32_16x16x32_bf16 v[104:107], v[172:175], v[44:47], v[72:75]
	v_mfma_f32_16x16x32_bf16 v[72:75], v[8:11], v[176:179], v[128:131]
	v_mfma_f32_16x16x32_bf16 v[92:95], v[12:15], v[180:183], v[72:75]
	v_mfma_f32_16x16x32_bf16 v[72:75], v[168:171], v[176:179], v[188:191]
	v_mfma_f32_16x16x32_bf16 v[88:91], v[172:175], v[180:183], v[72:75]
	v_mfma_f32_16x16x32_bf16 v[72:75], v[8:11], v[192:195], v[100:103]
	v_mfma_f32_16x16x32_bf16 v[76:79], v[12:15], v[202:205], v[72:75]
	v_mfma_f32_16x16x32_bf16 v[72:75], v[168:171], v[192:195], v[96:99]
	v_mfma_f32_16x16x32_bf16 v[72:75], v[172:175], v[202:205], v[72:75]
	s_setprio 0
	s_barrier
	ds_read_b128 v[128:131], v137
	ds_read_b128 v[188:191], v137 offset:1024
	ds_read_b128 v[214:217], v137 offset:2048
	ds_read_b128 v[218:221], v137 offset:3072
	s_waitcnt vmcnt(0)
	s_barrier
	s_waitcnt lgkmcnt(0)
	s_setprio 1
	s_waitcnt lgkmcnt(0)
	v_mfma_f32_16x16x32_bf16 v[96:99], v[128:131], v[24:27], v[206:209]
	v_mfma_f32_16x16x32_bf16 v[24:27], v[214:217], v[24:27], v[156:159]
	v_mfma_f32_16x16x32_bf16 v[112:115], v[218:221], v[28:31], v[24:27]
	v_mfma_f32_16x16x32_bf16 v[24:27], v[128:131], v[40:43], v[84:87]
	v_mfma_f32_16x16x32_bf16 v[100:103], v[188:191], v[44:47], v[24:27]
	v_mfma_f32_16x16x32_bf16 v[24:27], v[214:217], v[40:43], v[80:83]
	v_mfma_f32_16x16x32_bf16 v[116:119], v[188:191], v[28:31], v[96:99]
	v_mfma_f32_16x16x32_bf16 v[96:99], v[218:221], v[44:47], v[24:27]
	v_mfma_f32_16x16x32_bf16 v[24:27], v[128:131], v[176:179], v[160:163]
	v_mfma_f32_16x16x32_bf16 v[84:87], v[188:191], v[180:183], v[24:27]
	v_mfma_f32_16x16x32_bf16 v[24:27], v[214:217], v[176:179], v[164:167]
	v_mfma_f32_16x16x32_bf16 v[80:83], v[218:221], v[180:183], v[24:27]
	v_mfma_f32_16x16x32_bf16 v[24:27], v[128:131], v[192:195], v[68:71]
	v_mfma_f32_16x16x32_bf16 v[68:71], v[188:191], v[202:205], v[24:27]
	v_mfma_f32_16x16x32_bf16 v[24:27], v[214:217], v[192:195], v[64:67]
	v_mfma_f32_16x16x32_bf16 v[64:67], v[218:221], v[202:205], v[24:27]
	s_setprio 0
	s_barrier
	ds_read_b128 v[156:159], v136 offset:49152
	ds_read_b128 v[136:139], v136 offset:50176
	ds_read_b128 v[160:163], v135 offset:49152
	ds_read_b128 v[164:167], v135 offset:50176
	ds_read_b128 v[176:179], v134 offset:49152
	ds_read_b128 v[180:183], v134 offset:50176
	ds_read_b128 v[192:195], v133 offset:49152
	ds_read_b128 v[202:205], v133 offset:50176
	s_barrier
	s_waitcnt lgkmcnt(0)
	s_setprio 1
	s_waitcnt lgkmcnt(0)
	v_mfma_f32_16x16x32_bf16 v[24:27], v[8:11], v[156:159], v[60:63]
	v_mfma_f32_16x16x32_bf16 v[60:63], v[12:15], v[136:139], v[24:27]
	v_mfma_f32_16x16x32_bf16 v[24:27], v[168:171], v[156:159], v[56:59]
	v_mfma_f32_16x16x32_bf16 v[56:59], v[172:175], v[136:139], v[24:27]
	v_mfma_f32_16x16x32_bf16 v[24:27], v[8:11], v[160:163], v[52:55]
	v_mfma_f32_16x16x32_bf16 v[44:47], v[12:15], v[164:167], v[24:27]
	v_mfma_f32_16x16x32_bf16 v[24:27], v[168:171], v[160:163], v[48:51]
	v_mfma_f32_16x16x32_bf16 v[40:43], v[172:175], v[164:167], v[24:27]
	v_mfma_f32_16x16x32_bf16 v[24:27], v[8:11], v[176:179], v[184:187]
	v_mfma_f32_16x16x32_bf16 v[8:11], v[8:11], v[192:195], v[36:39]
	v_mfma_f32_16x16x32_bf16 v[28:31], v[12:15], v[180:183], v[24:27]
	v_mfma_f32_16x16x32_bf16 v[24:27], v[168:171], v[176:179], v[210:213]
	v_mfma_f32_16x16x32_bf16 v[12:15], v[12:15], v[202:205], v[8:11]
	v_mfma_f32_16x16x32_bf16 v[8:11], v[168:171], v[192:195], v[32:35]
	v_mfma_f32_16x16x32_bf16 v[24:27], v[172:175], v[180:183], v[24:27]
	v_mfma_f32_16x16x32_bf16 v[8:11], v[172:175], v[202:205], v[8:11]
	s_setprio 0
	s_setprio 1
	v_mfma_f32_16x16x32_bf16 v[32:35], v[128:131], v[156:159], v[140:143]
	v_mfma_f32_16x16x32_bf16 v[52:55], v[188:191], v[136:139], v[32:35]
	v_mfma_f32_16x16x32_bf16 v[32:35], v[214:217], v[156:159], v[144:147]
	v_mfma_f32_16x16x32_bf16 v[16:19], v[214:217], v[160:163], v[16:19]
	v_mfma_f32_16x16x32_bf16 v[48:51], v[218:221], v[136:139], v[32:35]
	v_mfma_f32_16x16x32_bf16 v[20:23], v[128:131], v[160:163], v[20:23]
	v_mfma_f32_16x16x32_bf16 v[32:35], v[218:221], v[164:167], v[16:19]
	v_mfma_f32_16x16x32_bf16 v[16:19], v[128:131], v[176:179], v[148:151]
	v_mfma_f32_16x16x32_bf16 v[36:39], v[188:191], v[164:167], v[20:23]
	v_mfma_f32_16x16x32_bf16 v[20:23], v[188:191], v[180:183], v[16:19]
	v_mfma_f32_16x16x32_bf16 v[16:19], v[214:217], v[176:179], v[152:155]
	v_mfma_f32_16x16x32_bf16 v[4:7], v[128:131], v[192:195], v[4:7]
	v_mfma_f32_16x16x32_bf16 v[0:3], v[214:217], v[192:195], v[0:3]
	v_mfma_f32_16x16x32_bf16 v[16:19], v[218:221], v[180:183], v[16:19]
	v_mfma_f32_16x16x32_bf16 v[4:7], v[188:191], v[202:205], v[4:7]
	v_mfma_f32_16x16x32_bf16 v[0:3], v[218:221], v[202:205], v[0:3]
	s_setprio 0
	s_movk_i32 s4, 0x100
	v_cmp_gt_u32_e32 vcc, s4, v132
	s_barrier
	s_and_saveexec_b64 s[4:5], vcc
	s_cbranch_execz .LBB0_571
	s_barrier
